# epilogue butterfly: in-place permlane swap + add (3 VALU per step), dead index code removed
# speedup vs baseline: 1.0054x; 1.0046x over previous
; __device__ __forceinline__ unsigned cvt_pk_bf16(float lo, float hi) { unsigned r; asm volatile("v_cvt_pk_bf16_f32 %0, %1, %2" : "=v"(r) : "v"(lo), "v"(hi)); return r; }
; __device__ __forceinline__ float bf_lo(unsigned w) { return __uint_as_float(w << 16); }
; __device__ __forceinline__ float bf_hi(unsigned w) { return __uint_as_float(w & 0xffff0000u); }
;     __device__ __forceinline__ void operator()(const f32x4 (&acc)[2][2][4][2], const Unit& u, int wr, int wc, int fr, int fq) const {
;     ...
;             for (int mm = 0; mm < RB; ++mm) { const size_t off = (size_t)(row0 + ai * HALF + (mh + mm) * 16) * D_MODEL + col0;
; #pragma unroll
;                 for (int bj = 0; bj < 2; ++bj) {
;                     if (BASE_F32) { bf[mm][bj][0] = *(const f32x4*)(basef + off + bj * HALF); bf[mm][bj][1] = *(const f32x4*)(basef + off + bj * HALF + 4); }
;                     else bb[mm][bj] = *(const u32x4*)(xb + off + bj * HALF);
;                 } }
;             asm volatile("" ::: "memory");
; #pragma unroll
;             for (int mm = 0; mm < RB; ++mm) {
;                 const int m = mh + mm;
;                 const int row = row0 + ai * HALF + m * 16; const size_t off = (size_t)row * D_MODEL + col0; float s = 0.f;
; #pragma unroll
;                 for (int bj = 0; bj < 2; ++bj) {
;                     f32x4 b0, b1;
;                     if (BASE_F32) { b0 = bf[mm][bj][0]; b1 = bf[mm][bj][1]; }
;                     else { const u32x4 w = bb[mm][bj]; b0 = (f32x4){bf_lo(w.x), bf_hi(w.x), bf_lo(w.y), bf_hi(w.y)}; b1 = (f32x4){bf_lo(w.z), bf_hi(w.z), bf_lo(w.w), bf_hi(w.w)}; }
;                     const f32x4 o0 = b0 + acc[ai][bj][m][0] * alpha, o1 = b1 + acc[ai][bj][m][1] * alpha;
;                     if (OUT_F32) { *(f32x4*)(out + off + bj * HALF) = o0; *(f32x4*)(out + off + bj * HALF + 4) = o1; }
;                     else { u32x4 w; w.x = cvt_pk_bf16(o0[0], o0[1]); w.y = cvt_pk_bf16(o0[2], o0[3]); w.z = cvt_pk_bf16(o1[0], o1[1]); w.w = cvt_pk_bf16(o1[2], o1[3]); *(u32x4*)(xb + off + bj * HALF) = w; }
;                     s += ((o0[0] * o0[0] + o0[1] * o0[1]) + (o0[2] * o0[2] + o0[3] * o0[3])) + ((o1[0] * o1[0] + o1[1] * o1[1]) + (o1[2] * o1[2] + o1[3] * o1[3]));
;                 }
;                 if (ssp) { s += __shfl_xor(s, 16); s += __shfl_xor(s, 32); if (fq == 0) ssp[(size_t)row * 16 + u.pn * 4 + wc] = s; }
.LBB0_260:
	s_mov_b32 s98, 0xffff0000
	s_mov_b32 s99, 0xffff0000
	s_mov_b32 s100, 0
	s_mov_b32 s101, -1
	v_lshl_or_b32 v166, s16, 8, v186
	v_lshl_add_u32 v168, s33, 8, v184
	v_ashrrev_i32_e32 v167, 31, v166
	v_readlane_b32 s2, v235, 38
	v_lshlrev_b64 v[202:203], 1, v[166:167]
	v_readlane_b32 s3, v235, 39
	v_ashrrev_i32_e32 v169, 31, v168
	v_or_b32_e32 v180, 16, v168
	v_or_b32_e32 v176, 32, v168
	v_lshl_add_u64 v[170:171], s[2:3], 0, v[202:203]
	v_lshlrev_b64 v[204:205], 11, v[168:169]
	v_or_b32_e32 v172, 48, v168
	v_ashrrev_i32_e32 v181, 31, v180
	v_ashrrev_i32_e32 v177, 31, v176
	v_lshl_add_u64 v[128:129], v[170:171], 0, v[204:205]
	v_ashrrev_i32_e32 v173, 31, v172
	v_lshlrev_b64 v[182:183], 11, v[180:181]
	v_lshlrev_b64 v[178:179], 11, v[176:177]
	global_load_dwordx4 v[192:195], v[128:129], off
	global_load_dwordx4 v[198:201], v[128:129], off offset:256
	v_lshlrev_b64 v[174:175], 11, v[172:173]
	v_lshl_add_u64 v[128:129], v[170:171], 0, v[182:183]
	v_lshl_add_u64 v[130:131], v[170:171], 0, v[178:179]
	v_lshl_add_u64 v[206:207], v[170:171], 0, v[174:175]
	global_load_dwordx4 v[148:151], v[128:129], off
	global_load_dwordx4 v[144:147], v[128:129], off offset:256
	global_load_dwordx4 v[140:143], v[130:131], off
	global_load_dwordx4 v[136:139], v[130:131], off offset:256
	global_load_dwordx4 v[132:135], v[206:207], off
	s_nop 0
	global_load_dwordx4 v[128:131], v[206:207], off offset:256
	v_readlane_b32 s30, v235, 42
	v_readlane_b32 s31, v235, 43
	v_lshl_add_u64 v[204:205], s[2:3], 0, v[204:205]
	s_lshl_b32 s26, s16, 2
	v_cndmask_b32_e64 v197, 0, 1, s[30:31]
	v_lshl_add_u64 v[202:203], v[204:205], 0, v[202:203]
	s_ashr_i32 s27, s26, 31
	v_cmp_ne_u32_e64 s[8:9], 1, v197
	s_andn2_b64 vcc, exec, s[30:31]
	s_waitcnt vmcnt(0)
	v_lshlrev_b32_e32 v204, 16, v192
	v_and_b32_e32 v205, 0xffff0000, v192
	v_lshlrev_b32_e32 v192, 16, v193
	v_and_b32_e32 v193, 0xffff0000, v193
	v_lshlrev_b32_e32 v206, 16, v194
	v_and_b32_e32 v207, 0xffff0000, v194
	v_lshlrev_b32_e32 v194, 16, v195
	v_and_b32_e32 v195, 0xffff0000, v195
	v_lshlrev_b32_e32 v208, 16, v198
	v_and_b32_e32 v209, 0xffff0000, v198
	v_lshlrev_b32_e32 v198, 16, v199
	v_and_b32_e32 v199, 0xffff0000, v199
	v_lshlrev_b32_e32 v210, 16, v200
	v_and_b32_e32 v211, 0xffff0000, v200
	v_lshlrev_b32_e32 v200, 16, v201
	v_and_b32_e32 v201, 0xffff0000, v201
	v_pk_fma_f32 v[126:127], v[126:127], 0.5, v[192:193] op_sel_hi:[1,0,1]
	v_pk_fma_f32 v[124:125], v[124:125], 0.5, v[204:205] op_sel_hi:[1,0,1]
	v_pk_fma_f32 v[122:123], v[122:123], 0.5, v[194:195] op_sel_hi:[1,0,1]
	v_pk_fma_f32 v[120:121], v[120:121], 0.5, v[206:207] op_sel_hi:[1,0,1]
	v_pk_fma_f32 v[118:119], v[118:119], 0.5, v[198:199] op_sel_hi:[1,0,1]
	v_pk_fma_f32 v[116:117], v[116:117], 0.5, v[208:209] op_sel_hi:[1,0,1]
	v_pk_fma_f32 v[114:115], v[114:115], 0.5, v[200:201] op_sel_hi:[1,0,1]
	v_pk_fma_f32 v[112:113], v[112:113], 0.5, v[210:211] op_sel_hi:[1,0,1]
	v_cvt_pk_bf16_f32 v192, v124, v125
	v_cvt_pk_bf16_f32 v193, v126, v127
	v_cvt_pk_bf16_f32 v194, v120, v121
	v_cvt_pk_bf16_f32 v195, v122, v123
	global_store_dwordx4 v[202:203], v[192:195], off
	s_nop 1
	v_cvt_pk_bf16_f32 v192, v116, v117
	v_cvt_pk_bf16_f32 v193, v118, v119
	v_cvt_pk_bf16_f32 v194, v112, v113
	v_cvt_pk_bf16_f32 v195, v114, v115
	global_store_dwordx4 v[202:203], v[192:195], off offset:256
	s_cbranch_vccnz .LBB0_264
	v_mul_f32_e32 v113, v113, v113
	v_mul_f32_e32 v125, v125, v125
	v_mul_f32_e32 v121, v121, v121
	v_mul_f32_e32 v117, v117, v117
	v_fmac_f32_e32 v113, v112, v112
	v_mul_f32_e32 v112, v115, v115
	v_fmac_f32_e32 v125, v124, v124
	v_mul_f32_e32 v124, v127, v127
	v_fmac_f32_e32 v121, v120, v120
	v_mul_f32_e32 v120, v123, v123
	v_fmac_f32_e32 v117, v116, v116
	v_mul_f32_e32 v116, v119, v119
	v_fmac_f32_e32 v112, v114, v114
	v_and_b32_e32 v114, 64, v191
	v_fmac_f32_e32 v124, v126, v126
	v_fmac_f32_e32 v120, v122, v122
	v_fmac_f32_e32 v116, v118, v118
	v_add_f32_e32 v112, v113, v112
	v_add_u32_e32 v114, 64, v114
	v_add_f32_e32 v124, v125, v124
	v_add_f32_e32 v120, v121, v120
	v_add_f32_e32 v116, v117, v116
	v_add_f32_e32 v120, v124, v120
	v_add_f32_e32 v112, v116, v112
	v_add_f32_e32 v112, v120, v112
	v_mov_b32_e32 v236, v112
	s_nop 1
	v_permlane16_swap_b32_e32 v112, v236
	s_waitcnt lgkmcnt(0)
	v_add_f32_e32 v112, v112, v236
	s_nop 1
	v_mov_b32_e32 v236, v112
	s_nop 1
	v_permlane32_swap_b32_e32 v112, v236
	s_and_saveexec_b64 s[2:3], s[4:5]
	s_cbranch_execz .LBB0_263
	v_readlane_b32 s30, v235, 50
	v_lshlrev_b64 v[114:115], 6, v[168:169]
	v_readlane_b32 s31, v235, 51
	s_lshl_b32 s16, s39, 2
	s_waitcnt lgkmcnt(0)
	v_add_f32_e32 v112, v112, v236
	v_lshl_add_u64 v[114:115], s[30:31], 0, v[114:115]
	v_lshl_add_u64 v[114:115], s[26:27], 2, v[114:115]
	v_lshl_add_u64 v[114:115], v[114:115], 0, s[16:17]
	global_store_dword v[114:115], v112, off

; __device__ __forceinline__ unsigned cvt_pk_bf16(float lo, float hi) { unsigned r; asm volatile("v_cvt_pk_bf16_f32 %0, %1, %2" : "=v"(r) : "v"(lo), "v"(hi)); return r; }
; __device__ __forceinline__ float bf_lo(unsigned w) { return __uint_as_float(w << 16); }
; __device__ __forceinline__ float bf_hi(unsigned w) { return __uint_as_float(w & 0xffff0000u); }
;     __device__ __forceinline__ void operator()(const f32x4 (&acc)[2][2][4][2], const Unit& u, int wr, int wc, int fr, int fq) const {
;     ...
;             for (int mm = 0; mm < RB; ++mm) {
;                 const int m = mh + mm;
;                 const int row = row0 + ai * HALF + m * 16; const size_t off = (size_t)row * D_MODEL + col0; float s = 0.f;
; #pragma unroll
;                 for (int bj = 0; bj < 2; ++bj) {
;                     f32x4 b0, b1;
;                     if (BASE_F32) { b0 = bf[mm][bj][0]; b1 = bf[mm][bj][1]; }
;                     else { const u32x4 w = bb[mm][bj]; b0 = (f32x4){bf_lo(w.x), bf_hi(w.x), bf_lo(w.y), bf_hi(w.y)}; b1 = (f32x4){bf_lo(w.z), bf_hi(w.z), bf_lo(w.w), bf_hi(w.w)}; }
;                     const f32x4 o0 = b0 + acc[ai][bj][m][0] * alpha, o1 = b1 + acc[ai][bj][m][1] * alpha;
;                     if (OUT_F32) { *(f32x4*)(out + off + bj * HALF) = o0; *(f32x4*)(out + off + bj * HALF + 4) = o1; }
;                     else { u32x4 w; w.x = cvt_pk_bf16(o0[0], o0[1]); w.y = cvt_pk_bf16(o0[2], o0[3]); w.z = cvt_pk_bf16(o1[0], o1[1]); w.w = cvt_pk_bf16(o1[2], o1[3]); *(u32x4*)(xb + off + bj * HALF) = w; }
;                     s += ((o0[0] * o0[0] + o0[1] * o0[1]) + (o0[2] * o0[2] + o0[3] * o0[3])) + ((o1[0] * o1[0] + o1[1] * o1[1]) + (o1[2] * o1[2] + o1[3] * o1[3]));
;                 }
;                 if (ssp) { s += __shfl_xor(s, 16); s += __shfl_xor(s, 32); if (fq == 0) ssp[(size_t)row * 16 + u.pn * 4 + wc] = s; }
.LBB0_264:
	v_readlane_b32 s2, v235, 38
	v_lshlrev_b32_e32 v116, 16, v150
	v_and_b32_e32 v117, 0xffff0000, v150
	v_readlane_b32 s3, v235, 39
	v_lshlrev_b32_e32 v112, 16, v148
	s_waitcnt lgkmcnt(0)
	v_and_b32_e32 v113, 0xffff0000, v148
	v_lshlrev_b32_e32 v114, 16, v149
	v_and_b32_e32 v115, 0xffff0000, v149
	v_lshlrev_b32_e32 v118, 16, v151
	v_and_b32_e32 v119, 0xffff0000, v151
	v_pk_fma_f32 v[104:105], v[104:105], 0.5, v[116:117] op_sel_hi:[1,0,1]
	v_lshl_add_u64 v[116:117], s[2:3], 0, v[182:183]
	v_pk_fma_f32 v[110:111], v[110:111], 0.5, v[114:115] op_sel_hi:[1,0,1]
	v_pk_fma_f32 v[108:109], v[108:109], 0.5, v[112:113] op_sel_hi:[1,0,1]
	v_pk_fma_f32 v[106:107], v[106:107], 0.5, v[118:119] op_sel_hi:[1,0,1]
	v_cvt_pk_bf16_f32 v112, v108, v109
	v_cvt_pk_bf16_f32 v113, v110, v111
	v_cvt_pk_bf16_f32 v114, v104, v105
	v_lshl_add_u64 v[116:117], v[166:167], 1, v[116:117]
	v_cvt_pk_bf16_f32 v115, v106, v107
	global_store_dwordx4 v[116:117], v[112:115], off
	v_lshlrev_b32_e32 v118, 16, v146
	v_and_b32_e32 v119, 0xffff0000, v146
	v_lshlrev_b32_e32 v112, 16, v144
	v_and_b32_e32 v113, 0xffff0000, v144
	v_lshlrev_b32_e32 v114, 16, v145
	v_and_b32_e32 v115, 0xffff0000, v145
	v_lshlrev_b32_e32 v120, 16, v147
	v_and_b32_e32 v121, 0xffff0000, v147
	v_pk_fma_f32 v[102:103], v[102:103], 0.5, v[114:115] op_sel_hi:[1,0,1]
	v_pk_fma_f32 v[100:101], v[100:101], 0.5, v[112:113] op_sel_hi:[1,0,1]
	v_pk_fma_f32 v[98:99], v[98:99], 0.5, v[120:121] op_sel_hi:[1,0,1]
	v_pk_fma_f32 v[96:97], v[96:97], 0.5, v[118:119] op_sel_hi:[1,0,1]
	s_and_b64 vcc, exec, s[8:9]
	v_cvt_pk_bf16_f32 v112, v100, v101
	v_cvt_pk_bf16_f32 v113, v102, v103
	v_cvt_pk_bf16_f32 v114, v96, v97
	v_cvt_pk_bf16_f32 v115, v98, v99
	global_store_dwordx4 v[116:117], v[112:115], off offset:256
	s_cbranch_vccnz .LBB0_268
	v_mul_f32_e32 v97, v97, v97
	v_mul_f32_e32 v109, v109, v109
	v_mul_f32_e32 v105, v105, v105
	v_mul_f32_e32 v101, v101, v101
	v_fmac_f32_e32 v97, v96, v96
	v_mul_f32_e32 v96, v99, v99
	v_fmac_f32_e32 v109, v108, v108
	v_mul_f32_e32 v108, v111, v111
	v_fmac_f32_e32 v105, v104, v104
	v_mul_f32_e32 v104, v107, v107
	v_fmac_f32_e32 v101, v100, v100
	v_mul_f32_e32 v100, v103, v103
	v_fmac_f32_e32 v96, v98, v98
	v_and_b32_e32 v98, 64, v191
	v_fmac_f32_e32 v108, v110, v110
	v_fmac_f32_e32 v104, v106, v106
	v_fmac_f32_e32 v100, v102, v102
	v_add_f32_e32 v96, v97, v96
	v_add_u32_e32 v98, 64, v98
	v_add_f32_e32 v108, v109, v108
	v_add_f32_e32 v104, v105, v104
	v_add_f32_e32 v100, v101, v100
	v_add_f32_e32 v104, v108, v104
	v_add_f32_e32 v96, v100, v96
	v_add_f32_e32 v96, v104, v96
	v_mov_b32_e32 v236, v96
	s_nop 1
	v_permlane16_swap_b32_e32 v96, v236
	s_waitcnt lgkmcnt(0)
	v_add_f32_e32 v96, v96, v236
	s_nop 1
	v_mov_b32_e32 v236, v96
	s_nop 1
	v_permlane32_swap_b32_e32 v96, v236
	s_and_saveexec_b64 s[2:3], s[4:5]
	s_cbranch_execz .LBB0_267
	v_readlane_b32 s30, v235, 50
	v_lshlrev_b64 v[98:99], 6, v[180:181]
	v_readlane_b32 s31, v235, 51
	s_lshl_b32 s16, s39, 2
	s_waitcnt lgkmcnt(0)
	v_add_f32_e32 v96, v96, v236
	v_lshl_add_u64 v[98:99], s[30:31], 0, v[98:99]
	v_lshl_add_u64 v[98:99], s[26:27], 2, v[98:99]
	v_lshl_add_u64 v[98:99], v[98:99], 0, s[16:17]
	global_store_dword v[98:99], v96, off

; __device__ __forceinline__ unsigned cvt_pk_bf16(float lo, float hi) { unsigned r; asm volatile("v_cvt_pk_bf16_f32 %0, %1, %2" : "=v"(r) : "v"(lo), "v"(hi)); return r; }
; __device__ __forceinline__ float bf_lo(unsigned w) { return __uint_as_float(w << 16); }
; __device__ __forceinline__ float bf_hi(unsigned w) { return __uint_as_float(w & 0xffff0000u); }
;     __device__ __forceinline__ void operator()(const f32x4 (&acc)[2][2][4][2], const Unit& u, int wr, int wc, int fr, int fq) const {
;     ...
;             for (int mm = 0; mm < RB; ++mm) {
;                 const int m = mh + mm;
;                 const int row = row0 + ai * HALF + m * 16; const size_t off = (size_t)row * D_MODEL + col0; float s = 0.f;
; #pragma unroll
;                 for (int bj = 0; bj < 2; ++bj) {
;                     f32x4 b0, b1;
;                     if (BASE_F32) { b0 = bf[mm][bj][0]; b1 = bf[mm][bj][1]; }
;                     else { const u32x4 w = bb[mm][bj]; b0 = (f32x4){bf_lo(w.x), bf_hi(w.x), bf_lo(w.y), bf_hi(w.y)}; b1 = (f32x4){bf_lo(w.z), bf_hi(w.z), bf_lo(w.w), bf_hi(w.w)}; }
;                     const f32x4 o0 = b0 + acc[ai][bj][m][0] * alpha, o1 = b1 + acc[ai][bj][m][1] * alpha;
;                     if (OUT_F32) { *(f32x4*)(out + off + bj * HALF) = o0; *(f32x4*)(out + off + bj * HALF + 4) = o1; }
;                     else { u32x4 w; w.x = cvt_pk_bf16(o0[0], o0[1]); w.y = cvt_pk_bf16(o0[2], o0[3]); w.z = cvt_pk_bf16(o1[0], o1[1]); w.w = cvt_pk_bf16(o1[2], o1[3]); *(u32x4*)(xb + off + bj * HALF) = w; }
;                     s += ((o0[0] * o0[0] + o0[1] * o0[1]) + (o0[2] * o0[2] + o0[3] * o0[3])) + ((o1[0] * o1[0] + o1[1] * o1[1]) + (o1[2] * o1[2] + o1[3] * o1[3]));
;                 }
;                 if (ssp) { s += __shfl_xor(s, 16); s += __shfl_xor(s, 32); if (fq == 0) ssp[(size_t)row * 16 + u.pn * 4 + wc] = s; }
.LBB0_268:
	v_readlane_b32 s2, v235, 38
	v_lshlrev_b32_e32 v100, 16, v142
	v_and_b32_e32 v101, 0xffff0000, v142
	v_readlane_b32 s3, v235, 39
	v_lshlrev_b32_e32 v96, 16, v140
	s_waitcnt lgkmcnt(0)
	v_and_b32_e32 v97, 0xffff0000, v140
	v_lshlrev_b32_e32 v98, 16, v141
	v_and_b32_e32 v99, 0xffff0000, v141
	v_lshlrev_b32_e32 v102, 16, v143
	v_and_b32_e32 v103, 0xffff0000, v143
	v_pk_fma_f32 v[88:89], v[88:89], 0.5, v[100:101] op_sel_hi:[1,0,1]
	v_lshl_add_u64 v[100:101], s[2:3], 0, v[178:179]
	v_pk_fma_f32 v[94:95], v[94:95], 0.5, v[98:99] op_sel_hi:[1,0,1]
	v_pk_fma_f32 v[92:93], v[92:93], 0.5, v[96:97] op_sel_hi:[1,0,1]
	v_pk_fma_f32 v[90:91], v[90:91], 0.5, v[102:103] op_sel_hi:[1,0,1]
	v_cvt_pk_bf16_f32 v96, v92, v93
	v_cvt_pk_bf16_f32 v97, v94, v95
	v_cvt_pk_bf16_f32 v98, v88, v89
	v_lshl_add_u64 v[100:101], v[166:167], 1, v[100:101]
	v_cvt_pk_bf16_f32 v99, v90, v91
	global_store_dwordx4 v[100:101], v[96:99], off
	v_lshlrev_b32_e32 v102, 16, v138
	v_and_b32_e32 v103, 0xffff0000, v138
	v_lshlrev_b32_e32 v96, 16, v136
	v_and_b32_e32 v97, 0xffff0000, v136
	v_lshlrev_b32_e32 v98, 16, v137
	v_and_b32_e32 v99, 0xffff0000, v137
	v_lshlrev_b32_e32 v104, 16, v139
	v_and_b32_e32 v105, 0xffff0000, v139
	v_pk_fma_f32 v[86:87], v[86:87], 0.5, v[98:99] op_sel_hi:[1,0,1]
	v_pk_fma_f32 v[84:85], v[84:85], 0.5, v[96:97] op_sel_hi:[1,0,1]
	v_pk_fma_f32 v[82:83], v[82:83], 0.5, v[104:105] op_sel_hi:[1,0,1]
	v_pk_fma_f32 v[80:81], v[80:81], 0.5, v[102:103] op_sel_hi:[1,0,1]
	s_and_b64 vcc, exec, s[8:9]
	v_cvt_pk_bf16_f32 v96, v84, v85
	v_cvt_pk_bf16_f32 v97, v86, v87
	v_cvt_pk_bf16_f32 v98, v80, v81
	v_cvt_pk_bf16_f32 v99, v82, v83
	global_store_dwordx4 v[100:101], v[96:99], off offset:256
	s_cbranch_vccnz .LBB0_272
	v_mul_f32_e32 v81, v81, v81
	v_mul_f32_e32 v93, v93, v93
	v_mul_f32_e32 v89, v89, v89
	v_mul_f32_e32 v85, v85, v85
	v_fmac_f32_e32 v81, v80, v80
	v_mul_f32_e32 v80, v83, v83
	v_fmac_f32_e32 v93, v92, v92
	v_mul_f32_e32 v92, v95, v95
	v_fmac_f32_e32 v89, v88, v88
	v_mul_f32_e32 v88, v91, v91
	v_fmac_f32_e32 v85, v84, v84
	v_mul_f32_e32 v84, v87, v87
	v_fmac_f32_e32 v80, v82, v82
	v_and_b32_e32 v82, 64, v191
	v_fmac_f32_e32 v92, v94, v94
	v_fmac_f32_e32 v88, v90, v90
	v_fmac_f32_e32 v84, v86, v86
	v_add_f32_e32 v80, v81, v80
	v_add_u32_e32 v82, 64, v82
	v_add_f32_e32 v92, v93, v92
	v_add_f32_e32 v88, v89, v88
	v_add_f32_e32 v84, v85, v84
	v_add_f32_e32 v88, v92, v88
	v_add_f32_e32 v80, v84, v80
	v_add_f32_e32 v80, v88, v80
	v_mov_b32_e32 v236, v80
	s_nop 1
	v_permlane16_swap_b32_e32 v80, v236
	s_waitcnt lgkmcnt(0)
	v_add_f32_e32 v80, v80, v236
	s_nop 1
	v_mov_b32_e32 v236, v80
	s_nop 1
	v_permlane32_swap_b32_e32 v80, v236
	s_and_saveexec_b64 s[2:3], s[4:5]
	s_cbranch_execz .LBB0_271
	v_readlane_b32 s30, v235, 50
	v_lshlrev_b64 v[82:83], 6, v[176:177]
	v_readlane_b32 s31, v235, 51
	s_lshl_b32 s16, s39, 2
	s_waitcnt lgkmcnt(0)
	v_add_f32_e32 v80, v80, v236
	v_lshl_add_u64 v[82:83], s[30:31], 0, v[82:83]
	v_lshl_add_u64 v[82:83], s[26:27], 2, v[82:83]
	v_lshl_add_u64 v[82:83], v[82:83], 0, s[16:17]
	global_store_dword v[82:83], v80, off

; __device__ __forceinline__ unsigned cvt_pk_bf16(float lo, float hi) { unsigned r; asm volatile("v_cvt_pk_bf16_f32 %0, %1, %2" : "=v"(r) : "v"(lo), "v"(hi)); return r; }
; __device__ __forceinline__ float bf_lo(unsigned w) { return __uint_as_float(w << 16); }
; __device__ __forceinline__ float bf_hi(unsigned w) { return __uint_as_float(w & 0xffff0000u); }
;     __device__ __forceinline__ void operator()(const f32x4 (&acc)[2][2][4][2], const Unit& u, int wr, int wc, int fr, int fq) const {
;     ...
;             for (int mm = 0; mm < RB; ++mm) {
;                 const int m = mh + mm;
;                 const int row = row0 + ai * HALF + m * 16; const size_t off = (size_t)row * D_MODEL + col0; float s = 0.f;
; #pragma unroll
;                 for (int bj = 0; bj < 2; ++bj) {
;                     f32x4 b0, b1;
;                     if (BASE_F32) { b0 = bf[mm][bj][0]; b1 = bf[mm][bj][1]; }
;                     else { const u32x4 w = bb[mm][bj]; b0 = (f32x4){bf_lo(w.x), bf_hi(w.x), bf_lo(w.y), bf_hi(w.y)}; b1 = (f32x4){bf_lo(w.z), bf_hi(w.z), bf_lo(w.w), bf_hi(w.w)}; }
;                     const f32x4 o0 = b0 + acc[ai][bj][m][0] * alpha, o1 = b1 + acc[ai][bj][m][1] * alpha;
;                     if (OUT_F32) { *(f32x4*)(out + off + bj * HALF) = o0; *(f32x4*)(out + off + bj * HALF + 4) = o1; }
;                     else { u32x4 w; w.x = cvt_pk_bf16(o0[0], o0[1]); w.y = cvt_pk_bf16(o0[2], o0[3]); w.z = cvt_pk_bf16(o1[0], o1[1]); w.w = cvt_pk_bf16(o1[2], o1[3]); *(u32x4*)(xb + off + bj * HALF) = w; }
;                     s += ((o0[0] * o0[0] + o0[1] * o0[1]) + (o0[2] * o0[2] + o0[3] * o0[3])) + ((o1[0] * o1[0] + o1[1] * o1[1]) + (o1[2] * o1[2] + o1[3] * o1[3]));
;                 }
;                 if (ssp) { s += __shfl_xor(s, 16); s += __shfl_xor(s, 32); if (fq == 0) ssp[(size_t)row * 16 + u.pn * 4 + wc] = s; }
.LBB0_272:
	v_readlane_b32 s2, v235, 38
	v_lshlrev_b32_e32 v84, 16, v134
	v_and_b32_e32 v85, 0xffff0000, v134
	v_readlane_b32 s3, v235, 39
	v_lshlrev_b32_e32 v80, 16, v132
	s_waitcnt lgkmcnt(0)
	v_and_b32_e32 v81, 0xffff0000, v132
	v_lshlrev_b32_e32 v82, 16, v133
	v_and_b32_e32 v83, 0xffff0000, v133
	v_lshlrev_b32_e32 v86, 16, v135
	v_and_b32_e32 v87, 0xffff0000, v135
	v_pk_fma_f32 v[72:73], v[72:73], 0.5, v[84:85] op_sel_hi:[1,0,1]
	v_lshl_add_u64 v[84:85], s[2:3], 0, v[174:175]
	v_pk_fma_f32 v[78:79], v[78:79], 0.5, v[82:83] op_sel_hi:[1,0,1]
	v_pk_fma_f32 v[76:77], v[76:77], 0.5, v[80:81] op_sel_hi:[1,0,1]
	v_pk_fma_f32 v[74:75], v[74:75], 0.5, v[86:87] op_sel_hi:[1,0,1]
	v_cvt_pk_bf16_f32 v80, v76, v77
	v_cvt_pk_bf16_f32 v81, v78, v79
	v_cvt_pk_bf16_f32 v82, v72, v73
	v_lshl_add_u64 v[84:85], v[166:167], 1, v[84:85]
	v_cvt_pk_bf16_f32 v83, v74, v75
	global_store_dwordx4 v[84:85], v[80:83], off
	v_lshlrev_b32_e32 v86, 16, v130
	v_and_b32_e32 v87, 0xffff0000, v130
	v_lshlrev_b32_e32 v80, 16, v128
	v_and_b32_e32 v81, 0xffff0000, v128
	v_lshlrev_b32_e32 v82, 16, v129
	v_and_b32_e32 v83, 0xffff0000, v129
	v_lshlrev_b32_e32 v88, 16, v131
	v_and_b32_e32 v89, 0xffff0000, v131
	v_pk_fma_f32 v[70:71], v[70:71], 0.5, v[82:83] op_sel_hi:[1,0,1]
	v_pk_fma_f32 v[68:69], v[68:69], 0.5, v[80:81] op_sel_hi:[1,0,1]
	v_pk_fma_f32 v[66:67], v[66:67], 0.5, v[88:89] op_sel_hi:[1,0,1]
	v_pk_fma_f32 v[64:65], v[64:65], 0.5, v[86:87] op_sel_hi:[1,0,1]
	s_and_b64 vcc, exec, s[8:9]
	v_cvt_pk_bf16_f32 v80, v68, v69
	v_cvt_pk_bf16_f32 v81, v70, v71
	v_cvt_pk_bf16_f32 v82, v64, v65
	v_cvt_pk_bf16_f32 v83, v66, v67
	global_store_dwordx4 v[84:85], v[80:83], off offset:256
	s_cbranch_vccnz .LBB0_276
	v_mul_f32_e32 v65, v65, v65
	v_mul_f32_e32 v77, v77, v77
	v_mul_f32_e32 v73, v73, v73
	v_mul_f32_e32 v69, v69, v69
	v_fmac_f32_e32 v65, v64, v64
	v_mul_f32_e32 v64, v67, v67
	v_fmac_f32_e32 v77, v76, v76
	v_mul_f32_e32 v76, v79, v79
	v_fmac_f32_e32 v73, v72, v72
	v_mul_f32_e32 v72, v75, v75
	v_fmac_f32_e32 v69, v68, v68
	v_mul_f32_e32 v68, v71, v71
	v_fmac_f32_e32 v64, v66, v66
	v_and_b32_e32 v66, 64, v191
	v_fmac_f32_e32 v76, v78, v78
	v_fmac_f32_e32 v72, v74, v74
	v_fmac_f32_e32 v68, v70, v70
	v_add_f32_e32 v64, v65, v64
	v_add_u32_e32 v66, 64, v66
	v_add_f32_e32 v76, v77, v76
	v_add_f32_e32 v72, v73, v72
	v_add_f32_e32 v68, v69, v68
	v_add_f32_e32 v72, v76, v72
	v_add_f32_e32 v64, v68, v64
	v_add_f32_e32 v64, v72, v64
	v_mov_b32_e32 v236, v64
	s_nop 1
	v_permlane16_swap_b32_e32 v64, v236
	s_waitcnt lgkmcnt(0)
	v_add_f32_e32 v64, v64, v236
	s_nop 1
	v_mov_b32_e32 v236, v64
	s_nop 1
	v_permlane32_swap_b32_e32 v64, v236
	s_and_saveexec_b64 s[2:3], s[4:5]
	s_cbranch_execz .LBB0_275
	v_readlane_b32 s30, v235, 50
	v_lshlrev_b64 v[66:67], 6, v[172:173]
	v_readlane_b32 s31, v235, 51
	s_lshl_b32 s16, s39, 2
	s_waitcnt lgkmcnt(0)
	v_add_f32_e32 v64, v64, v236
	v_lshl_add_u64 v[66:67], s[30:31], 0, v[66:67]
	v_lshl_add_u64 v[66:67], s[26:27], 2, v[66:67]
	v_lshl_add_u64 v[66:67], v[66:67], 0, s[16:17]
	global_store_dword v[66:67], v64, off

; __device__ __forceinline__ unsigned cvt_pk_bf16(float lo, float hi) { unsigned r; asm volatile("v_cvt_pk_bf16_f32 %0, %1, %2" : "=v"(r) : "v"(lo), "v"(hi)); return r; }
; __device__ __forceinline__ float bf_lo(unsigned w) { return __uint_as_float(w << 16); }
; __device__ __forceinline__ float bf_hi(unsigned w) { return __uint_as_float(w & 0xffff0000u); }
;     __device__ __forceinline__ void operator()(const f32x4 (&acc)[2][2][4][2], const Unit& u, int wr, int wc, int fr, int fq) const {
;     ...
;             for (int mm = 0; mm < RB; ++mm) { const size_t off = (size_t)(row0 + ai * HALF + (mh + mm) * 16) * D_MODEL + col0;
; #pragma unroll
;                 for (int bj = 0; bj < 2; ++bj) {
;                     if (BASE_F32) { bf[mm][bj][0] = *(const f32x4*)(basef + off + bj * HALF); bf[mm][bj][1] = *(const f32x4*)(basef + off + bj * HALF + 4); }
;                     else bb[mm][bj] = *(const u32x4*)(xb + off + bj * HALF);
;                 } }
;             asm volatile("" ::: "memory");
; #pragma unroll
;             for (int mm = 0; mm < RB; ++mm) {
;                 const int m = mh + mm;
;                 const int row = row0 + ai * HALF + m * 16; const size_t off = (size_t)row * D_MODEL + col0; float s = 0.f;
; #pragma unroll
;                 for (int bj = 0; bj < 2; ++bj) {
;                     f32x4 b0, b1;
;                     if (BASE_F32) { b0 = bf[mm][bj][0]; b1 = bf[mm][bj][1]; }
;                     else { const u32x4 w = bb[mm][bj]; b0 = (f32x4){bf_lo(w.x), bf_hi(w.x), bf_lo(w.y), bf_hi(w.y)}; b1 = (f32x4){bf_lo(w.z), bf_hi(w.z), bf_lo(w.w), bf_hi(w.w)}; }
;                     const f32x4 o0 = b0 + acc[ai][bj][m][0] * alpha, o1 = b1 + acc[ai][bj][m][1] * alpha;
;                     if (OUT_F32) { *(f32x4*)(out + off + bj * HALF) = o0; *(f32x4*)(out + off + bj * HALF + 4) = o1; }
;                     else { u32x4 w; w.x = cvt_pk_bf16(o0[0], o0[1]); w.y = cvt_pk_bf16(o0[2], o0[3]); w.z = cvt_pk_bf16(o1[0], o1[1]); w.w = cvt_pk_bf16(o1[2], o1[3]); *(u32x4*)(xb + off + bj * HALF) = w; }
;                     s += ((o0[0] * o0[0] + o0[1] * o0[1]) + (o0[2] * o0[2] + o0[3] * o0[3])) + ((o1[0] * o1[0] + o1[1] * o1[1]) + (o1[2] * o1[2] + o1[3] * o1[3]));
;                 }
;                 if (ssp) { s += __shfl_xor(s, 16); s += __shfl_xor(s, 32); if (fq == 0) ssp[(size_t)row * 16 + u.pn * 4 + wc] = s; }
.LBB0_276:
	v_add_u32_e32 v100, 0x80, v168
	v_ashrrev_i32_e32 v101, 31, v100
	v_add_u32_e32 v96, 0x90, v168
	v_add_u32_e32 v92, 0xa0, v168
	v_lshlrev_b64 v[110:111], 11, v[100:101]
	v_add_u32_e32 v88, 0xb0, v168
	v_ashrrev_i32_e32 v97, 31, v96
	v_ashrrev_i32_e32 v93, 31, v92
	s_waitcnt lgkmcnt(0)
	v_lshl_add_u64 v[64:65], v[170:171], 0, v[110:111]
	v_ashrrev_i32_e32 v89, 31, v88
	v_lshlrev_b64 v[98:99], 11, v[96:97]
	v_lshlrev_b64 v[94:95], 11, v[92:93]
	global_load_dwordx4 v[102:105], v[64:65], off
	global_load_dwordx4 v[106:109], v[64:65], off offset:256
	v_lshlrev_b64 v[90:91], 11, v[88:89]
	v_lshl_add_u64 v[64:65], v[170:171], 0, v[98:99]
	v_lshl_add_u64 v[66:67], v[170:171], 0, v[94:95]
	v_lshl_add_u64 v[112:113], v[170:171], 0, v[90:91]
	global_load_dwordx4 v[84:87], v[64:65], off
	global_load_dwordx4 v[80:83], v[64:65], off offset:256
	global_load_dwordx4 v[76:79], v[66:67], off
	global_load_dwordx4 v[72:75], v[66:67], off offset:256
	global_load_dwordx4 v[68:71], v[112:113], off
	s_nop 0
	global_load_dwordx4 v[64:67], v[112:113], off offset:256
	v_readlane_b32 s2, v235, 38
	v_readlane_b32 s3, v235, 39
	s_and_b64 vcc, exec, s[8:9]
	s_waitcnt vmcnt(7)
	v_lshlrev_b32_e32 v112, 16, v102
	v_lshl_add_u64 v[110:111], s[2:3], 0, v[110:111]
	v_and_b32_e32 v113, 0xffff0000, v102
	v_lshlrev_b32_e32 v102, 16, v103
	v_and_b32_e32 v103, 0xffff0000, v103
	v_lshlrev_b32_e32 v114, 16, v104
	v_and_b32_e32 v115, 0xffff0000, v104
	v_lshlrev_b32_e32 v104, 16, v105
	v_and_b32_e32 v105, 0xffff0000, v105
	s_waitcnt vmcnt(6)
	v_lshlrev_b32_e32 v116, 16, v106
	v_and_b32_e32 v117, 0xffff0000, v106
	v_lshlrev_b32_e32 v106, 16, v107
	v_and_b32_e32 v107, 0xffff0000, v107
	v_lshlrev_b32_e32 v118, 16, v108
	v_and_b32_e32 v119, 0xffff0000, v108
	v_lshlrev_b32_e32 v108, 16, v109
	v_and_b32_e32 v109, 0xffff0000, v109
	v_lshl_add_u64 v[110:111], v[166:167], 1, v[110:111]
	v_pk_fma_f32 v[62:63], v[62:63], 0.5, v[102:103] op_sel_hi:[1,0,1]
	v_pk_fma_f32 v[60:61], v[60:61], 0.5, v[112:113] op_sel_hi:[1,0,1]
	v_pk_fma_f32 v[58:59], v[58:59], 0.5, v[104:105] op_sel_hi:[1,0,1]
	v_pk_fma_f32 v[56:57], v[56:57], 0.5, v[114:115] op_sel_hi:[1,0,1]
	v_pk_fma_f32 v[54:55], v[54:55], 0.5, v[106:107] op_sel_hi:[1,0,1]
	v_pk_fma_f32 v[52:53], v[52:53], 0.5, v[116:117] op_sel_hi:[1,0,1]
	v_pk_fma_f32 v[50:51], v[50:51], 0.5, v[108:109] op_sel_hi:[1,0,1]
	v_pk_fma_f32 v[48:49], v[48:49], 0.5, v[118:119] op_sel_hi:[1,0,1]
	v_cvt_pk_bf16_f32 v102, v60, v61
	v_cvt_pk_bf16_f32 v103, v62, v63
	v_cvt_pk_bf16_f32 v104, v56, v57
	v_cvt_pk_bf16_f32 v105, v58, v59
	global_store_dwordx4 v[110:111], v[102:105], off
	s_nop 1
	v_cvt_pk_bf16_f32 v102, v52, v53
	v_cvt_pk_bf16_f32 v103, v54, v55
	v_cvt_pk_bf16_f32 v104, v48, v49
	v_cvt_pk_bf16_f32 v105, v50, v51
	global_store_dwordx4 v[110:111], v[102:105], off offset:256
	s_cbranch_vccnz .LBB0_280
	v_mul_f32_e32 v49, v49, v49
	v_mul_f32_e32 v61, v61, v61
	v_mul_f32_e32 v57, v57, v57
	v_mul_f32_e32 v53, v53, v53
	v_fmac_f32_e32 v49, v48, v48
	v_mul_f32_e32 v48, v51, v51
	v_fmac_f32_e32 v61, v60, v60
	v_mul_f32_e32 v60, v63, v63
	v_fmac_f32_e32 v57, v56, v56
	v_mul_f32_e32 v56, v59, v59
	v_fmac_f32_e32 v53, v52, v52
	v_mul_f32_e32 v52, v55, v55
	v_fmac_f32_e32 v48, v50, v50
	v_and_b32_e32 v50, 64, v191
	v_fmac_f32_e32 v60, v62, v62
	v_fmac_f32_e32 v56, v58, v58
	v_fmac_f32_e32 v52, v54, v54
	v_add_f32_e32 v48, v49, v48
	v_add_u32_e32 v50, 64, v50
	v_add_f32_e32 v60, v61, v60
	v_add_f32_e32 v56, v57, v56
	v_add_f32_e32 v52, v53, v52
	v_add_f32_e32 v56, v60, v56
	v_add_f32_e32 v48, v52, v48
	v_add_f32_e32 v48, v56, v48
	v_mov_b32_e32 v236, v48
	s_nop 1
	v_permlane16_swap_b32_e32 v48, v236
	s_waitcnt lgkmcnt(0)
	v_add_f32_e32 v48, v48, v236
	s_nop 1
	v_mov_b32_e32 v236, v48
	s_nop 1
	v_permlane32_swap_b32_e32 v48, v236
	s_and_saveexec_b64 s[2:3], s[4:5]
	s_cbranch_execz .LBB0_279
	v_readlane_b32 s30, v235, 50
	v_lshlrev_b64 v[50:51], 6, v[100:101]
	v_readlane_b32 s31, v235, 51
	s_lshl_b32 s16, s39, 2
	s_waitcnt lgkmcnt(0)
	v_add_f32_e32 v48, v48, v236
	v_lshl_add_u64 v[50:51], s[30:31], 0, v[50:51]
	v_lshl_add_u64 v[50:51], s[26:27], 2, v[50:51]
	v_lshl_add_u64 v[50:51], v[50:51], 0, s[16:17]
	global_store_dword v[50:51], v48, off

; __device__ __forceinline__ unsigned cvt_pk_bf16(float lo, float hi) { unsigned r; asm volatile("v_cvt_pk_bf16_f32 %0, %1, %2" : "=v"(r) : "v"(lo), "v"(hi)); return r; }
; __device__ __forceinline__ float bf_lo(unsigned w) { return __uint_as_float(w << 16); }
; __device__ __forceinline__ float bf_hi(unsigned w) { return __uint_as_float(w & 0xffff0000u); }
;     __device__ __forceinline__ void operator()(const f32x4 (&acc)[2][2][4][2], const Unit& u, int wr, int wc, int fr, int fq) const {
;     ...
;             for (int mm = 0; mm < RB; ++mm) {
;                 const int m = mh + mm;
;                 const int row = row0 + ai * HALF + m * 16; const size_t off = (size_t)row * D_MODEL + col0; float s = 0.f;
; #pragma unroll
;                 for (int bj = 0; bj < 2; ++bj) {
;                     f32x4 b0, b1;
;                     if (BASE_F32) { b0 = bf[mm][bj][0]; b1 = bf[mm][bj][1]; }
;                     else { const u32x4 w = bb[mm][bj]; b0 = (f32x4){bf_lo(w.x), bf_hi(w.x), bf_lo(w.y), bf_hi(w.y)}; b1 = (f32x4){bf_lo(w.z), bf_hi(w.z), bf_lo(w.w), bf_hi(w.w)}; }
;                     const f32x4 o0 = b0 + acc[ai][bj][m][0] * alpha, o1 = b1 + acc[ai][bj][m][1] * alpha;
;                     if (OUT_F32) { *(f32x4*)(out + off + bj * HALF) = o0; *(f32x4*)(out + off + bj * HALF + 4) = o1; }
;                     else { u32x4 w; w.x = cvt_pk_bf16(o0[0], o0[1]); w.y = cvt_pk_bf16(o0[2], o0[3]); w.z = cvt_pk_bf16(o1[0], o1[1]); w.w = cvt_pk_bf16(o1[2], o1[3]); *(u32x4*)(xb + off + bj * HALF) = w; }
;                     s += ((o0[0] * o0[0] + o0[1] * o0[1]) + (o0[2] * o0[2] + o0[3] * o0[3])) + ((o1[0] * o1[0] + o1[1] * o1[1]) + (o1[2] * o1[2] + o1[3] * o1[3]));
;                 }
;                 if (ssp) { s += __shfl_xor(s, 16); s += __shfl_xor(s, 32); if (fq == 0) ssp[(size_t)row * 16 + u.pn * 4 + wc] = s; }
.LBB0_280:
	v_readlane_b32 s2, v235, 38
	s_waitcnt vmcnt(7)
	v_lshlrev_b32_e32 v52, 16, v86
	v_and_b32_e32 v53, 0xffff0000, v86
	v_readlane_b32 s3, v235, 39
	v_lshlrev_b32_e32 v48, 16, v84
	s_waitcnt lgkmcnt(0)
	v_and_b32_e32 v49, 0xffff0000, v84
	v_lshlrev_b32_e32 v50, 16, v85
	v_and_b32_e32 v51, 0xffff0000, v85
	v_lshlrev_b32_e32 v54, 16, v87
	v_and_b32_e32 v55, 0xffff0000, v87
	v_pk_fma_f32 v[40:41], v[40:41], 0.5, v[52:53] op_sel_hi:[1,0,1]
	v_lshl_add_u64 v[52:53], s[2:3], 0, v[98:99]
	v_pk_fma_f32 v[46:47], v[46:47], 0.5, v[50:51] op_sel_hi:[1,0,1]
	v_pk_fma_f32 v[44:45], v[44:45], 0.5, v[48:49] op_sel_hi:[1,0,1]
	v_pk_fma_f32 v[42:43], v[42:43], 0.5, v[54:55] op_sel_hi:[1,0,1]
	v_cvt_pk_bf16_f32 v48, v44, v45
	v_cvt_pk_bf16_f32 v49, v46, v47
	v_cvt_pk_bf16_f32 v50, v40, v41
	v_lshl_add_u64 v[52:53], v[166:167], 1, v[52:53]
	v_cvt_pk_bf16_f32 v51, v42, v43
	global_store_dwordx4 v[52:53], v[48:51], off
	s_waitcnt vmcnt(7)
	v_lshlrev_b32_e32 v54, 16, v82
	v_and_b32_e32 v55, 0xffff0000, v82
	v_lshlrev_b32_e32 v48, 16, v80
	v_and_b32_e32 v49, 0xffff0000, v80
	v_lshlrev_b32_e32 v50, 16, v81
	v_and_b32_e32 v51, 0xffff0000, v81
	v_lshlrev_b32_e32 v56, 16, v83
	v_and_b32_e32 v57, 0xffff0000, v83
	v_pk_fma_f32 v[38:39], v[38:39], 0.5, v[50:51] op_sel_hi:[1,0,1]
	v_pk_fma_f32 v[36:37], v[36:37], 0.5, v[48:49] op_sel_hi:[1,0,1]
	v_pk_fma_f32 v[34:35], v[34:35], 0.5, v[56:57] op_sel_hi:[1,0,1]
	v_pk_fma_f32 v[32:33], v[32:33], 0.5, v[54:55] op_sel_hi:[1,0,1]
	s_and_b64 vcc, exec, s[8:9]
	v_cvt_pk_bf16_f32 v48, v36, v37
	v_cvt_pk_bf16_f32 v49, v38, v39
	v_cvt_pk_bf16_f32 v50, v32, v33
	v_cvt_pk_bf16_f32 v51, v34, v35
	global_store_dwordx4 v[52:53], v[48:51], off offset:256
	s_cbranch_vccnz .LBB0_284
	v_mul_f32_e32 v33, v33, v33
	v_mul_f32_e32 v45, v45, v45
	v_mul_f32_e32 v41, v41, v41
	v_mul_f32_e32 v37, v37, v37
	v_fmac_f32_e32 v33, v32, v32
	v_mul_f32_e32 v32, v35, v35
	v_fmac_f32_e32 v45, v44, v44
	v_mul_f32_e32 v44, v47, v47
	v_fmac_f32_e32 v41, v40, v40
	v_mul_f32_e32 v40, v43, v43
	v_fmac_f32_e32 v37, v36, v36
	v_mul_f32_e32 v36, v39, v39
	v_fmac_f32_e32 v32, v34, v34
	v_and_b32_e32 v34, 64, v191
	v_fmac_f32_e32 v44, v46, v46
	v_fmac_f32_e32 v40, v42, v42
	v_fmac_f32_e32 v36, v38, v38
	v_add_f32_e32 v32, v33, v32
	v_add_u32_e32 v34, 64, v34
	v_add_f32_e32 v44, v45, v44
	v_add_f32_e32 v40, v41, v40
	v_add_f32_e32 v36, v37, v36
	v_add_f32_e32 v40, v44, v40
	v_add_f32_e32 v32, v36, v32
	v_add_f32_e32 v32, v40, v32
	v_mov_b32_e32 v236, v32
	s_nop 1
	v_permlane16_swap_b32_e32 v32, v236
	s_waitcnt lgkmcnt(0)
	v_add_f32_e32 v32, v32, v236
	s_nop 1
	v_mov_b32_e32 v236, v32
	s_nop 1
	v_permlane32_swap_b32_e32 v32, v236
	s_and_saveexec_b64 s[2:3], s[4:5]
	s_cbranch_execz .LBB0_283
	v_readlane_b32 s30, v235, 50
	v_lshlrev_b64 v[34:35], 6, v[96:97]
	v_readlane_b32 s31, v235, 51
	s_lshl_b32 s16, s39, 2
	s_waitcnt lgkmcnt(0)
	v_add_f32_e32 v32, v32, v236
	v_lshl_add_u64 v[34:35], s[30:31], 0, v[34:35]
	v_lshl_add_u64 v[34:35], s[26:27], 2, v[34:35]
	v_lshl_add_u64 v[34:35], v[34:35], 0, s[16:17]
	global_store_dword v[34:35], v32, off

; __device__ __forceinline__ unsigned cvt_pk_bf16(float lo, float hi) { unsigned r; asm volatile("v_cvt_pk_bf16_f32 %0, %1, %2" : "=v"(r) : "v"(lo), "v"(hi)); return r; }
; __device__ __forceinline__ float bf_lo(unsigned w) { return __uint_as_float(w << 16); }
; __device__ __forceinline__ float bf_hi(unsigned w) { return __uint_as_float(w & 0xffff0000u); }
;     __device__ __forceinline__ void operator()(const f32x4 (&acc)[2][2][4][2], const Unit& u, int wr, int wc, int fr, int fq) const {
;     ...
;             for (int mm = 0; mm < RB; ++mm) {
;                 const int m = mh + mm;
;                 const int row = row0 + ai * HALF + m * 16; const size_t off = (size_t)row * D_MODEL + col0; float s = 0.f;
; #pragma unroll
;                 for (int bj = 0; bj < 2; ++bj) {
;                     f32x4 b0, b1;
;                     if (BASE_F32) { b0 = bf[mm][bj][0]; b1 = bf[mm][bj][1]; }
;                     else { const u32x4 w = bb[mm][bj]; b0 = (f32x4){bf_lo(w.x), bf_hi(w.x), bf_lo(w.y), bf_hi(w.y)}; b1 = (f32x4){bf_lo(w.z), bf_hi(w.z), bf_lo(w.w), bf_hi(w.w)}; }
;                     const f32x4 o0 = b0 + acc[ai][bj][m][0] * alpha, o1 = b1 + acc[ai][bj][m][1] * alpha;
;                     if (OUT_F32) { *(f32x4*)(out + off + bj * HALF) = o0; *(f32x4*)(out + off + bj * HALF + 4) = o1; }
;                     else { u32x4 w; w.x = cvt_pk_bf16(o0[0], o0[1]); w.y = cvt_pk_bf16(o0[2], o0[3]); w.z = cvt_pk_bf16(o1[0], o1[1]); w.w = cvt_pk_bf16(o1[2], o1[3]); *(u32x4*)(xb + off + bj * HALF) = w; }
;                     s += ((o0[0] * o0[0] + o0[1] * o0[1]) + (o0[2] * o0[2] + o0[3] * o0[3])) + ((o1[0] * o1[0] + o1[1] * o1[1]) + (o1[2] * o1[2] + o1[3] * o1[3]));
;                 }
;                 if (ssp) { s += __shfl_xor(s, 16); s += __shfl_xor(s, 32); if (fq == 0) ssp[(size_t)row * 16 + u.pn * 4 + wc] = s; }
.LBB0_284:
	v_readlane_b32 s2, v235, 38
	s_waitcnt vmcnt(7)
	v_lshlrev_b32_e32 v36, 16, v78
	v_and_b32_e32 v37, 0xffff0000, v78
	v_readlane_b32 s3, v235, 39
	v_lshlrev_b32_e32 v32, 16, v76
	s_waitcnt lgkmcnt(0)
	v_and_b32_e32 v33, 0xffff0000, v76
	v_lshlrev_b32_e32 v34, 16, v77
	v_and_b32_e32 v35, 0xffff0000, v77
	v_lshlrev_b32_e32 v38, 16, v79
	v_and_b32_e32 v39, 0xffff0000, v79
	v_pk_fma_f32 v[24:25], v[24:25], 0.5, v[36:37] op_sel_hi:[1,0,1]
	v_lshl_add_u64 v[36:37], s[2:3], 0, v[94:95]
	v_pk_fma_f32 v[30:31], v[30:31], 0.5, v[34:35] op_sel_hi:[1,0,1]
	v_pk_fma_f32 v[28:29], v[28:29], 0.5, v[32:33] op_sel_hi:[1,0,1]
	v_pk_fma_f32 v[26:27], v[26:27], 0.5, v[38:39] op_sel_hi:[1,0,1]
	v_cvt_pk_bf16_f32 v32, v28, v29
	v_cvt_pk_bf16_f32 v33, v30, v31
	v_cvt_pk_bf16_f32 v34, v24, v25
	v_lshl_add_u64 v[36:37], v[166:167], 1, v[36:37]
	v_cvt_pk_bf16_f32 v35, v26, v27
	global_store_dwordx4 v[36:37], v[32:35], off
	s_waitcnt vmcnt(7)
	v_lshlrev_b32_e32 v38, 16, v74
	v_and_b32_e32 v39, 0xffff0000, v74
	v_lshlrev_b32_e32 v32, 16, v72
	v_and_b32_e32 v33, 0xffff0000, v72
	v_lshlrev_b32_e32 v34, 16, v73
	v_and_b32_e32 v35, 0xffff0000, v73
	v_lshlrev_b32_e32 v40, 16, v75
	v_and_b32_e32 v41, 0xffff0000, v75
	v_pk_fma_f32 v[22:23], v[22:23], 0.5, v[34:35] op_sel_hi:[1,0,1]
	v_pk_fma_f32 v[20:21], v[20:21], 0.5, v[32:33] op_sel_hi:[1,0,1]
	v_pk_fma_f32 v[18:19], v[18:19], 0.5, v[40:41] op_sel_hi:[1,0,1]
	v_pk_fma_f32 v[16:17], v[16:17], 0.5, v[38:39] op_sel_hi:[1,0,1]
	s_and_b64 vcc, exec, s[8:9]
	v_cvt_pk_bf16_f32 v32, v20, v21
	v_cvt_pk_bf16_f32 v33, v22, v23
	v_cvt_pk_bf16_f32 v34, v16, v17
	v_cvt_pk_bf16_f32 v35, v18, v19
	global_store_dwordx4 v[36:37], v[32:35], off offset:256
	s_cbranch_vccnz .LBB0_288
	v_mul_f32_e32 v17, v17, v17
	v_mul_f32_e32 v29, v29, v29
	v_mul_f32_e32 v25, v25, v25
	v_mul_f32_e32 v21, v21, v21
	v_fmac_f32_e32 v17, v16, v16
	v_mul_f32_e32 v16, v19, v19
	v_fmac_f32_e32 v29, v28, v28
	v_mul_f32_e32 v28, v31, v31
	v_fmac_f32_e32 v25, v24, v24
	v_mul_f32_e32 v24, v27, v27
	v_fmac_f32_e32 v21, v20, v20
	v_mul_f32_e32 v20, v23, v23
	v_fmac_f32_e32 v16, v18, v18
	v_and_b32_e32 v18, 64, v191
	v_fmac_f32_e32 v28, v30, v30
	v_fmac_f32_e32 v24, v26, v26
	v_fmac_f32_e32 v20, v22, v22
	v_add_f32_e32 v16, v17, v16
	v_add_u32_e32 v18, 64, v18
	v_add_f32_e32 v28, v29, v28
	v_add_f32_e32 v24, v25, v24
	v_add_f32_e32 v20, v21, v20
	v_add_f32_e32 v24, v28, v24
	v_add_f32_e32 v16, v20, v16
	v_add_f32_e32 v16, v24, v16
	v_mov_b32_e32 v236, v16
	s_nop 1
	v_permlane16_swap_b32_e32 v16, v236
	s_waitcnt lgkmcnt(0)
	v_add_f32_e32 v16, v16, v236
	s_nop 1
	v_mov_b32_e32 v236, v16
	s_nop 1
	v_permlane32_swap_b32_e32 v16, v236
	s_and_saveexec_b64 s[2:3], s[4:5]
	s_cbranch_execz .LBB0_287
	v_readlane_b32 s30, v235, 50
	v_lshlrev_b64 v[18:19], 6, v[92:93]
	v_readlane_b32 s31, v235, 51
	s_lshl_b32 s16, s39, 2
	s_waitcnt lgkmcnt(0)
	v_add_f32_e32 v16, v16, v236
	v_lshl_add_u64 v[18:19], s[30:31], 0, v[18:19]
	v_lshl_add_u64 v[18:19], s[26:27], 2, v[18:19]
	v_lshl_add_u64 v[18:19], v[18:19], 0, s[16:17]
	global_store_dword v[18:19], v16, off

; __device__ __forceinline__ unsigned cvt_pk_bf16(float lo, float hi) { unsigned r; asm volatile("v_cvt_pk_bf16_f32 %0, %1, %2" : "=v"(r) : "v"(lo), "v"(hi)); return r; }
; __device__ __forceinline__ float bf_lo(unsigned w) { return __uint_as_float(w << 16); }
; __device__ __forceinline__ float bf_hi(unsigned w) { return __uint_as_float(w & 0xffff0000u); }
;     __device__ __forceinline__ void operator()(const f32x4 (&acc)[2][2][4][2], const Unit& u, int wr, int wc, int fr, int fq) const {
;     ...
;             for (int mm = 0; mm < RB; ++mm) {
;                 const int m = mh + mm;
;                 const int row = row0 + ai * HALF + m * 16; const size_t off = (size_t)row * D_MODEL + col0; float s = 0.f;
; #pragma unroll
;                 for (int bj = 0; bj < 2; ++bj) {
;                     f32x4 b0, b1;
;                     if (BASE_F32) { b0 = bf[mm][bj][0]; b1 = bf[mm][bj][1]; }
;                     else { const u32x4 w = bb[mm][bj]; b0 = (f32x4){bf_lo(w.x), bf_hi(w.x), bf_lo(w.y), bf_hi(w.y)}; b1 = (f32x4){bf_lo(w.z), bf_hi(w.z), bf_lo(w.w), bf_hi(w.w)}; }
;                     const f32x4 o0 = b0 + acc[ai][bj][m][0] * alpha, o1 = b1 + acc[ai][bj][m][1] * alpha;
;                     if (OUT_F32) { *(f32x4*)(out + off + bj * HALF) = o0; *(f32x4*)(out + off + bj * HALF + 4) = o1; }
;                     else { u32x4 w; w.x = cvt_pk_bf16(o0[0], o0[1]); w.y = cvt_pk_bf16(o0[2], o0[3]); w.z = cvt_pk_bf16(o1[0], o1[1]); w.w = cvt_pk_bf16(o1[2], o1[3]); *(u32x4*)(xb + off + bj * HALF) = w; }
;                     s += ((o0[0] * o0[0] + o0[1] * o0[1]) + (o0[2] * o0[2] + o0[3] * o0[3])) + ((o1[0] * o1[0] + o1[1] * o1[1]) + (o1[2] * o1[2] + o1[3] * o1[3]));
;                 }
;                 if (ssp) { s += __shfl_xor(s, 16); s += __shfl_xor(s, 32); if (fq == 0) ssp[(size_t)row * 16 + u.pn * 4 + wc] = s; }
.LBB0_288:
	v_readlane_b32 s2, v235, 38
	s_waitcnt vmcnt(7)
	v_lshlrev_b32_e32 v20, 16, v70
	v_and_b32_e32 v21, 0xffff0000, v70
	v_readlane_b32 s3, v235, 39
	v_lshlrev_b32_e32 v16, 16, v68
	s_waitcnt lgkmcnt(0)
	v_and_b32_e32 v17, 0xffff0000, v68
	v_lshlrev_b32_e32 v18, 16, v69
	v_and_b32_e32 v19, 0xffff0000, v69
	v_lshlrev_b32_e32 v22, 16, v71
	v_and_b32_e32 v23, 0xffff0000, v71
	v_pk_fma_f32 v[8:9], v[8:9], 0.5, v[20:21] op_sel_hi:[1,0,1]
	v_lshl_add_u64 v[20:21], s[2:3], 0, v[90:91]
	v_pk_fma_f32 v[14:15], v[14:15], 0.5, v[18:19] op_sel_hi:[1,0,1]
	v_pk_fma_f32 v[12:13], v[12:13], 0.5, v[16:17] op_sel_hi:[1,0,1]
	v_pk_fma_f32 v[10:11], v[10:11], 0.5, v[22:23] op_sel_hi:[1,0,1]
	v_cvt_pk_bf16_f32 v16, v12, v13
	v_cvt_pk_bf16_f32 v17, v14, v15
	v_cvt_pk_bf16_f32 v18, v8, v9
	v_lshl_add_u64 v[20:21], v[166:167], 1, v[20:21]
	v_cvt_pk_bf16_f32 v19, v10, v11
	global_store_dwordx4 v[20:21], v[16:19], off
	s_waitcnt vmcnt(7)
	v_lshlrev_b32_e32 v22, 16, v66
	v_and_b32_e32 v23, 0xffff0000, v66
	v_lshlrev_b32_e32 v16, 16, v64
	v_and_b32_e32 v17, 0xffff0000, v64
	v_lshlrev_b32_e32 v18, 16, v65
	v_and_b32_e32 v19, 0xffff0000, v65
	v_lshlrev_b32_e32 v24, 16, v67
	v_and_b32_e32 v25, 0xffff0000, v67
	v_pk_fma_f32 v[6:7], v[6:7], 0.5, v[18:19] op_sel_hi:[1,0,1]
	v_pk_fma_f32 v[4:5], v[4:5], 0.5, v[16:17] op_sel_hi:[1,0,1]
	v_pk_fma_f32 v[2:3], v[2:3], 0.5, v[24:25] op_sel_hi:[1,0,1]
	v_pk_fma_f32 v[0:1], v[0:1], 0.5, v[22:23] op_sel_hi:[1,0,1]
	s_and_b64 vcc, exec, s[8:9]
	v_cvt_pk_bf16_f32 v16, v4, v5
	v_cvt_pk_bf16_f32 v17, v6, v7
	v_cvt_pk_bf16_f32 v18, v0, v1
	v_cvt_pk_bf16_f32 v19, v2, v3
	global_store_dwordx4 v[20:21], v[16:19], off offset:256
	s_cbranch_vccnz .LBB0_292
	v_mul_f32_e32 v1, v1, v1
	v_mul_f32_e32 v13, v13, v13
	v_mul_f32_e32 v9, v9, v9
	v_mul_f32_e32 v5, v5, v5
	v_fmac_f32_e32 v1, v0, v0
	v_mul_f32_e32 v0, v3, v3
	v_fmac_f32_e32 v13, v12, v12
	v_mul_f32_e32 v12, v15, v15
	v_fmac_f32_e32 v9, v8, v8
	v_mul_f32_e32 v8, v11, v11
	v_fmac_f32_e32 v5, v4, v4
	v_mul_f32_e32 v4, v7, v7
	v_fmac_f32_e32 v0, v2, v2
	v_and_b32_e32 v2, 64, v191
	v_fmac_f32_e32 v12, v14, v14
	v_fmac_f32_e32 v8, v10, v10
	v_fmac_f32_e32 v4, v6, v6
	v_add_f32_e32 v0, v1, v0
	v_add_u32_e32 v2, 64, v2
	v_add_f32_e32 v12, v13, v12
	v_add_f32_e32 v8, v9, v8
	v_add_f32_e32 v4, v5, v4
	v_add_f32_e32 v8, v12, v8
	v_add_f32_e32 v0, v4, v0
	v_add_f32_e32 v0, v8, v0
	v_mov_b32_e32 v236, v0
	s_nop 1
	v_permlane16_swap_b32_e32 v0, v236
	s_waitcnt lgkmcnt(0)
	v_add_f32_e32 v0, v0, v236
	s_nop 1
	v_mov_b32_e32 v236, v0
	s_nop 1
	v_permlane32_swap_b32_e32 v0, v236
	s_and_saveexec_b64 s[2:3], s[4:5]
	s_cbranch_execz .LBB0_291
	v_readlane_b32 s8, v235, 50
	v_lshlrev_b64 v[2:3], 6, v[88:89]
	v_readlane_b32 s9, v235, 51
	s_lshl_b32 s16, s39, 2
	s_waitcnt lgkmcnt(0)
	v_add_f32_e32 v0, v0, v236
	v_lshl_add_u64 v[2:3], s[8:9], 0, v[2:3]
	v_lshl_add_u64 v[2:3], s[26:27], 2, v[2:3]
	v_lshl_add_u64 v[2:3], v[2:3], 0, s[16:17]
	global_store_dword v[2:3], v0, off

; template <int NP> __device__ __forceinline__ void load_rs(const float* ssp, int row0, int fq, float (&rs)[2][4]) {
;     ...
;             for (int m = 0; m < 4; ++m) p[ai][m] = *(const f32x4*)(ssp + (size_t)(row0 + ai * HALF + m * 16) * 16 + 4 * fq);
; #pragma unroll
;         for (int ai = 0; ai < 2; ++ai)
; #pragma unroll
;             for (int m = 0; m < 4; ++m) { float s = (p[ai][m][0] + p[ai][m][1]) + (p[ai][m][2] + p[ai][m][3]); s += __shfl_xor(s, 16); s += __shfl_xor(s, 32); rs[ai][m] = s; }
;     __device__ __forceinline__ void operator()(const f32x4 (&acc)[2][2][4][2], const Unit& u, int wr, int wc, int fr, int fq) const {
;         if (u.pn >= 9) body<true>(acc, u, wr, wc, fr, fq); else body<false>(acc, u, wr, wc, fr, fq);
.LBB0_382:
	s_mov_b32 s98, 0xffff0000
	s_mov_b32 s99, 0xffff0000
	s_mov_b32 s100, 0
	s_mov_b32 s101, -1
	v_lshl_add_u32 v186, s33, 8, v193
	v_or_b32_e32 v184, 16, v186
	v_ashrrev_i32_e32 v187, 31, v186
	v_ashrrev_i32_e32 v185, 31, v184
	v_lshlrev_b64 v[128:129], 6, v[186:187]
	v_lshlrev_b64 v[130:131], 6, v[184:185]
	v_or_b32_e32 v182, 32, v186
	v_or_b32_e32 v180, 48, v186
	v_lshl_add_u64 v[128:129], v[162:163], 0, v[128:129]
	v_lshl_add_u64 v[130:131], v[162:163], 0, v[130:131]
	v_ashrrev_i32_e32 v183, 31, v182
	v_ashrrev_i32_e32 v181, 31, v180
	global_load_dwordx4 v[148:151], v[128:129], off
	global_load_dwordx4 v[204:207], v[130:131], off
	v_lshlrev_b64 v[128:129], 6, v[182:183]
	v_lshlrev_b64 v[130:131], 6, v[180:181]
	v_add_u32_e32 v178, 0x80, v186
	v_add_u32_e32 v176, 0x90, v186
	v_lshl_add_u64 v[128:129], v[162:163], 0, v[128:129]
	v_lshl_add_u64 v[130:131], v[162:163], 0, v[130:131]
	v_ashrrev_i32_e32 v179, 31, v178
	v_ashrrev_i32_e32 v177, 31, v176
	global_load_dwordx4 v[208:211], v[128:129], off
	global_load_dwordx4 v[140:143], v[130:131], off
	v_lshlrev_b64 v[128:129], 6, v[178:179]
	v_lshlrev_b64 v[130:131], 6, v[176:177]
	v_add_u32_e32 v174, 0xa0, v186
	v_add_u32_e32 v170, 0xb0, v186
	v_lshl_add_u64 v[128:129], v[162:163], 0, v[128:129]
	v_lshl_add_u64 v[130:131], v[162:163], 0, v[130:131]
	v_ashrrev_i32_e32 v175, 31, v174
	v_ashrrev_i32_e32 v171, 31, v170
	global_load_dwordx4 v[144:147], v[128:129], off
	global_load_dwordx4 v[132:135], v[130:131], off
	v_lshlrev_b64 v[128:129], 6, v[174:175]
	v_lshlrev_b64 v[130:131], 6, v[170:171]
	v_lshl_add_u64 v[128:129], v[162:163], 0, v[128:129]
	v_lshl_add_u64 v[130:131], v[162:163], 0, v[130:131]
	global_load_dwordx4 v[136:139], v[128:129], off
	s_nop 0
	global_load_dwordx4 v[128:131], v[130:131], off
	v_and_b32_e32 v172, 64, v201
	v_xor_b32_e32 v171, 16, v201
	v_add_u32_e32 v172, 64, v172
	v_xor_b32_e32 v173, 32, v201
	v_cmp_lt_i32_e32 vcc, v171, v172
	s_cmp_lt_i32 s43, 9
	v_lshl_or_b32 v160, s43, 8, v197
	v_cndmask_b32_e32 v171, v201, v171, vcc
	v_cmp_lt_i32_e32 vcc, v173, v172
	v_lshlrev_b32_e32 v175, 2, v171
	s_waitcnt vmcnt(0)
	v_add_f32_e32 v148, v148, v149
	v_add_f32_e32 v149, v150, v151
	v_cndmask_b32_e32 v172, v201, v173, vcc
	v_add_f32_e32 v177, v148, v149
	v_add_f32_e32 v148, v204, v205
	v_add_f32_e32 v149, v206, v207
	v_lshlrev_b32_e32 v171, 2, v172
	v_add_f32_e32 v179, v148, v149
	v_add_f32_e32 v150, v208, v209
	v_add_f32_e32 v151, v210, v211
	v_add_f32_e32 v181, v150, v151
	s_cbranch_scc0 .LBB0_384
	v_mov_b32_e32 v244, v177
	v_mov_b32_e32 v245, v177
	s_nop 1
	v_permlane16_swap_b32_e32 v244, v245
	v_cndmask_b32_e64 v150, v245, v244, s[98:99]
	v_mov_b32_e32 v244, v179
	v_mov_b32_e32 v245, v179
	s_nop 1
	v_permlane16_swap_b32_e32 v244, v245
	v_cndmask_b32_e64 v151, v245, v244, s[98:99]
	v_mov_b32_e32 v148, v141
	v_mov_b32_e32 v149, v142
	v_mov_b32_e32 v244, v181
	v_mov_b32_e32 v245, v181
	s_nop 1
	v_permlane16_swap_b32_e32 v244, v245
	v_cndmask_b32_e64 v172, v245, v244, s[98:99]
	s_waitcnt lgkmcnt(2)
	v_add_f32_e32 v150, v177, v150
	v_mov_b32_e32 v236, v150
	s_nop 1
	v_permlane32_swap_b32_e32 v150, v236
	s_waitcnt lgkmcnt(2)
	v_add_f32_e32 v183, v179, v151
	v_mov_b32_e32 v151, v143
	v_mov_b32_e32 v237, v183
	s_nop 1
	v_permlane32_swap_b32_e32 v183, v237
	s_waitcnt lgkmcnt(2)
	v_add_f32_e32 v172, v181, v172
	s_waitcnt lgkmcnt(1)
	v_add_f32_e32 v173, v150, v236
	v_mov_b32_e32 v150, v140
	v_pk_add_f32 v[148:149], v[148:149], v[150:151]
	v_mov_b32_e32 v150, v144
	v_add_f32_e32 v188, v148, v149
	v_mov_b32_e32 v148, v145
	v_mov_b32_e32 v149, v146
	v_mov_b32_e32 v151, v147
	v_pk_add_f32 v[148:149], v[148:149], v[150:151]
	v_mov_b32_e32 v236, v188
	s_nop 1
	v_permlane16_swap_b32_e32 v188, v236
	v_add_f32_e32 v148, v148, v149
	v_mov_b32_e32 v238, v148
	s_nop 1
	v_permlane16_swap_b32_e32 v148, v238
	s_waitcnt lgkmcnt(2)
	v_add_f32_e32 v183, v183, v237
	v_mov_b32_e32 v150, v132
	s_waitcnt lgkmcnt(1)
	v_add_f32_e32 v185, v188, v236
	v_mov_b32_e32 v151, v135
	s_waitcnt lgkmcnt(0)
	v_add_f32_e32 v188, v148, v238
	v_mov_b32_e32 v148, v133
	v_mov_b32_e32 v149, v134
	v_pk_add_f32 v[148:149], v[148:149], v[150:151]
	v_mov_b32_e32 v150, v136
	v_add_f32_e32 v191, v148, v149
	v_mov_b32_e32 v148, v137
	v_mov_b32_e32 v149, v138
	v_mov_b32_e32 v151, v139
	v_pk_add_f32 v[148:149], v[148:149], v[150:151]
	v_mov_b32_e32 v150, v128
	v_add_f32_e32 v194, v148, v149
	v_mov_b32_e32 v148, v129
	v_mov_b32_e32 v149, v130
	v_mov_b32_e32 v151, v131
	v_pk_add_f32 v[148:149], v[148:149], v[150:151]
	v_mov_b32_e32 v236, v172
	s_nop 1
	v_permlane32_swap_b32_e32 v172, v236
	v_add_f32_e32 v148, v148, v149
	v_mov_b32_e32 v237, v148
	s_nop 1
	v_permlane16_swap_b32_e32 v148, v237
	v_mov_b32_e32 v238, v191
	s_nop 1
	v_permlane16_swap_b32_e32 v191, v238
	v_mov_b32_e32 v239, v194
	s_nop 1
	v_permlane16_swap_b32_e32 v194, v239
	s_waitcnt lgkmcnt(3)
	v_add_f32_e32 v172, v172, v236
	v_mov_b32_e32 v236, v185
	s_nop 1
	v_permlane32_swap_b32_e32 v185, v236
	s_waitcnt lgkmcnt(3)
	v_add_f32_e32 v148, v148, v237
	v_mov_b32_e32 v237, v148
	s_nop 1
	v_permlane32_swap_b32_e32 v148, v237
	v_mov_b32_e32 v240, v188
	s_nop 1
	v_permlane32_swap_b32_e32 v188, v240
	s_waitcnt lgkmcnt(4)
	v_add_f32_e32 v150, v191, v238
	v_mov_b32_e32 v238, v150
	s_nop 1
	v_permlane32_swap_b32_e32 v150, v238
	s_waitcnt lgkmcnt(4)
	v_add_f32_e32 v191, v194, v239
	v_mov_b32_e32 v244, v191
	v_mov_b32_e32 v245, v191
	s_nop 1
	v_permlane32_swap_b32_e32 v244, v245
	v_cndmask_b32_e64 v192, v245, v244, s[100:101]
	s_waitcnt lgkmcnt(3)
; __device__ __forceinline__ unsigned cvt_pk_bf16(float lo, float hi) { unsigned r; asm volatile("v_cvt_pk_bf16_f32 %0, %1, %2" : "=v"(r) : "v"(lo), "v"(hi)); return r; }
; template <int NP> __device__ __forceinline__ void load_rs(const float* ssp, int row0, int fq, float (&rs)[2][4]) {
;     ...
;             for (int m = 0; m < 4; ++m) { float s = (p[ai][m][0] + p[ai][m][1]) + (p[ai][m][2] + p[ai][m][3]); s += __shfl_xor(s, 16); s += __shfl_xor(s, 32); rs[ai][m] = s; }
;     }
; #pragma unroll
;     for (int ai = 0; ai < 2; ++ai)
; #pragma unroll
;         for (int m = 0; m < 4; ++m) rs[ai][m] = __builtin_amdgcn_rsqf(rs[ai][m] * (1.0f / D_MODEL) + RMS_EPS);
;     template <bool GATE> __device__ __forceinline__ void body(const f32x4 (&acc)[2][2][4][2], const Unit& u, int wr, int wc, int fr, int fq) const {
;     ...
;                 const int row = row0 + ai * HALF + m * 16; const float r = rs[ai][m], nrl = r * -1.44269504089f;
; #pragma unroll
;                 for (int bj = 0; bj < 2; ++bj) {
;                     unsigned pk[4];
; #pragma unroll
;                     for (int q = 0; q < 4; ++q) {
;                         const f32x4 va = acc[ai][bj][m][q >> 1]; const int e0 = 2 * (q & 1);
;                         const f32x2 v = (f32x2){va[e0], va[e0 + 1]};
;                         f32x2 o;
;                         if (GATE) { const f32x2 t = v * nrl; f32x2 ex; ex.x = __builtin_amdgcn_exp2f(t.x); ex.y = __builtin_amdgcn_exp2f(t.y);
;                             const f32x2 d = ex + 1.0f; o.x = __builtin_amdgcn_rcpf(d.x); o.y = __builtin_amdgcn_rcpf(d.y); }
;                         else o = v * r;
;                         pk[q] = cvt_pk_bf16(o.x, o.y);
;                     }
;                     u32x4 w; w.x = pk[0]; w.y = pk[1]; w.z = pk[2]; w.w = pk[3];
;                     *(u32x4*)(P + (size_t)row * PITCH + col0 + bj * HALF) = w;
	v_add_f32_e32 v148, v148, v237
	v_fmamk_f32 v149, v173, 0x3a800000, v202
	v_rsq_f32_e32 v208, v149
	v_fmamk_f32 v149, v183, 0x3a800000, v202
	v_add_f32_e32 v185, v185, v236
	v_rsq_f32_e32 v210, v149
	v_fmamk_f32 v149, v172, 0x3a800000, v202
	s_waitcnt lgkmcnt(2)
	v_add_f32_e32 v187, v188, v240
	v_rsq_f32_e32 v212, v149
	v_fmamk_f32 v149, v185, 0x3a800000, v202
	s_waitcnt lgkmcnt(1)
	v_add_f32_e32 v150, v150, v238
	v_rsq_f32_e32 v214, v149
	v_fmamk_f32 v149, v187, 0x3a800000, v202
	s_waitcnt lgkmcnt(0)
	v_add_f32_e32 v151, v191, v192
	v_rsq_f32_e32 v194, v149
	v_fmamk_f32 v149, v150, 0x3a800000, v202
	v_rsq_f32_e32 v192, v149
	v_fmamk_f32 v149, v151, 0x3a800000, v202
	v_fmamk_f32 v148, v148, 0x3a800000, v202
	v_rsq_f32_e32 v190, v149
	v_rsq_f32_e32 v188, v148
	v_pk_mul_f32 v[148:149], v[124:125], v[208:209] op_sel_hi:[1,0]
	v_readlane_b32 s2, v235, 44
	v_cvt_pk_bf16_f32 v204, v148, v149
	v_pk_mul_f32 v[148:149], v[126:127], v[208:209] op_sel_hi:[1,0]
	v_readlane_b32 s3, v235, 45
	v_cvt_pk_bf16_f32 v205, v148, v149
	v_pk_mul_f32 v[148:149], v[120:121], v[208:209] op_sel_hi:[1,0]
	v_ashrrev_i32_e32 v173, 31, v160
	v_cvt_pk_bf16_f32 v206, v148, v149
	v_pk_mul_f32 v[148:149], v[122:123], v[208:209] op_sel_hi:[1,0]
	v_mov_b32_e32 v172, v160
	v_cvt_pk_bf16_f32 v207, v148, v149
	v_mov_b64_e32 v[148:149], s[2:3]
	v_mad_i64_i32 v[216:217], s[2:3], v186, s41, v[148:149]
	v_lshlrev_b64 v[150:151], 1, v[172:173]
	v_lshl_add_u64 v[216:217], v[216:217], 0, v[150:151]
	global_store_dwordx4 v[216:217], v[204:207], off
	s_nop 1
	v_pk_mul_f32 v[204:205], v[116:117], v[208:209] op_sel_hi:[1,0]
	v_pk_mul_f32 v[206:207], v[118:119], v[208:209] op_sel_hi:[1,0]
	v_cvt_pk_bf16_f32 v204, v204, v205
	s_nop 0
	v_cvt_pk_bf16_f32 v205, v206, v207
	v_pk_mul_f32 v[206:207], v[112:113], v[208:209] op_sel_hi:[1,0]
	v_pk_mul_f32 v[208:209], v[114:115], v[208:209] op_sel_hi:[1,0]
	v_cvt_pk_bf16_f32 v206, v206, v207
	s_nop 0
	v_cvt_pk_bf16_f32 v207, v208, v209
	global_store_dwordx4 v[216:217], v[204:207], off offset:256
	v_pk_mul_f32 v[208:209], v[106:107], v[210:211] op_sel_hi:[1,0]
	s_nop 0
	v_pk_mul_f32 v[204:205], v[108:109], v[210:211] op_sel_hi:[1,0]
	v_pk_mul_f32 v[206:207], v[110:111], v[210:211] op_sel_hi:[1,0]
	v_cvt_pk_bf16_f32 v204, v204, v205
	s_nop 0
	v_cvt_pk_bf16_f32 v205, v206, v207
	v_pk_mul_f32 v[206:207], v[104:105], v[210:211] op_sel_hi:[1,0]
	s_nop 0
	v_cvt_pk_bf16_f32 v206, v206, v207
	v_cvt_pk_bf16_f32 v207, v208, v209
	v_mad_i64_i32 v[208:209], s[2:3], v184, s41, v[148:149]
	v_lshl_add_u64 v[208:209], v[208:209], 0, v[150:151]
	global_store_dwordx4 v[208:209], v[204:207], off
	s_nop 1
	v_pk_mul_f32 v[204:205], v[100:101], v[210:211] op_sel_hi:[1,0]
	v_pk_mul_f32 v[206:207], v[102:103], v[210:211] op_sel_hi:[1,0]
	v_cvt_pk_bf16_f32 v204, v204, v205
	s_nop 0
	v_cvt_pk_bf16_f32 v205, v206, v207
	v_pk_mul_f32 v[206:207], v[96:97], v[210:211] op_sel_hi:[1,0]
	v_pk_mul_f32 v[210:211], v[98:99], v[210:211] op_sel_hi:[1,0]
	v_cvt_pk_bf16_f32 v206, v206, v207
	s_nop 0
	v_cvt_pk_bf16_f32 v207, v210, v211
	global_store_dwordx4 v[208:209], v[204:207], off offset:256
	v_pk_mul_f32 v[208:209], v[90:91], v[212:213] op_sel_hi:[1,0]
	v_pk_mul_f32 v[210:211], v[82:83], v[212:213] op_sel_hi:[1,0]
	v_pk_mul_f32 v[204:205], v[92:93], v[212:213] op_sel_hi:[1,0]
	v_pk_mul_f32 v[206:207], v[94:95], v[212:213] op_sel_hi:[1,0]
	v_cvt_pk_bf16_f32 v204, v204, v205
	s_nop 0
	v_cvt_pk_bf16_f32 v205, v206, v207
	v_pk_mul_f32 v[206:207], v[88:89], v[212:213] op_sel_hi:[1,0]
	s_nop 0
	v_cvt_pk_bf16_f32 v206, v206, v207
	v_cvt_pk_bf16_f32 v207, v208, v209
	v_mad_i64_i32 v[208:209], s[2:3], v182, s41, v[148:149]
	v_lshl_add_u64 v[208:209], v[208:209], 0, v[150:151]
	global_store_dwordx4 v[208:209], v[204:207], off
	s_nop 1
	v_pk_mul_f32 v[204:205], v[84:85], v[212:213] op_sel_hi:[1,0]
	v_pk_mul_f32 v[206:207], v[86:87], v[212:213] op_sel_hi:[1,0]
	v_cvt_pk_bf16_f32 v204, v204, v205
	s_nop 0
	v_cvt_pk_bf16_f32 v205, v206, v207
	v_pk_mul_f32 v[206:207], v[80:81], v[212:213] op_sel_hi:[1,0]
	s_nop 0
	v_cvt_pk_bf16_f32 v206, v206, v207
	v_cvt_pk_bf16_f32 v207, v210, v211
	global_store_dwordx4 v[208:209], v[204:207], off offset:256
	v_pk_mul_f32 v[208:209], v[74:75], v[214:215] op_sel_hi:[1,0]
	v_pk_mul_f32 v[210:211], v[66:67], v[214:215] op_sel_hi:[1,0]
	v_pk_mul_f32 v[204:205], v[76:77], v[214:215] op_sel_hi:[1,0]
	v_pk_mul_f32 v[206:207], v[78:79], v[214:215] op_sel_hi:[1,0]
	v_cvt_pk_bf16_f32 v204, v204, v205
	s_nop 0
	v_cvt_pk_bf16_f32 v205, v206, v207
	v_pk_mul_f32 v[206:207], v[72:73], v[214:215] op_sel_hi:[1,0]
	s_nop 0
	v_cvt_pk_bf16_f32 v206, v206, v207
	v_cvt_pk_bf16_f32 v207, v208, v209
	v_mad_i64_i32 v[208:209], s[2:3], v180, s41, v[148:149]
	v_lshl_add_u64 v[208:209], v[208:209], 0, v[150:151]
; __device__ __forceinline__ unsigned cvt_pk_bf16(float lo, float hi) { unsigned r; asm volatile("v_cvt_pk_bf16_f32 %0, %1, %2" : "=v"(r) : "v"(lo), "v"(hi)); return r; }
;     template <bool GATE> __device__ __forceinline__ void body(const f32x4 (&acc)[2][2][4][2], const Unit& u, int wr, int wc, int fr, int fq) const {
;     ...
;                 const int row = row0 + ai * HALF + m * 16; const float r = rs[ai][m], nrl = r * -1.44269504089f;
; #pragma unroll
;                 for (int bj = 0; bj < 2; ++bj) {
;                     unsigned pk[4];
; #pragma unroll
;                     for (int q = 0; q < 4; ++q) {
;                         const f32x4 va = acc[ai][bj][m][q >> 1]; const int e0 = 2 * (q & 1);
;                         const f32x2 v = (f32x2){va[e0], va[e0 + 1]};
;                         f32x2 o;
;                         if (GATE) { const f32x2 t = v * nrl; f32x2 ex; ex.x = __builtin_amdgcn_exp2f(t.x); ex.y = __builtin_amdgcn_exp2f(t.y);
;                             const f32x2 d = ex + 1.0f; o.x = __builtin_amdgcn_rcpf(d.x); o.y = __builtin_amdgcn_rcpf(d.y); }
;                         else o = v * r;
;                         pk[q] = cvt_pk_bf16(o.x, o.y);
;                     }
;                     u32x4 w; w.x = pk[0]; w.y = pk[1]; w.z = pk[2]; w.w = pk[3];
;                     *(u32x4*)(P + (size_t)row * PITCH + col0 + bj * HALF) = w;
	global_store_dwordx4 v[208:209], v[204:207], off
	s_nop 1
	v_pk_mul_f32 v[204:205], v[68:69], v[214:215] op_sel_hi:[1,0]
	v_pk_mul_f32 v[206:207], v[70:71], v[214:215] op_sel_hi:[1,0]
	v_cvt_pk_bf16_f32 v204, v204, v205
	s_nop 0
	v_cvt_pk_bf16_f32 v205, v206, v207
	v_pk_mul_f32 v[206:207], v[64:65], v[214:215] op_sel_hi:[1,0]
	s_nop 0
	v_cvt_pk_bf16_f32 v206, v206, v207
	v_cvt_pk_bf16_f32 v207, v210, v211
	global_store_dwordx4 v[208:209], v[204:207], off offset:256
	v_pk_mul_f32 v[208:209], v[58:59], v[194:195] op_sel_hi:[1,0]
	v_pk_mul_f32 v[210:211], v[50:51], v[194:195] op_sel_hi:[1,0]
	v_pk_mul_f32 v[204:205], v[60:61], v[194:195] op_sel_hi:[1,0]
	v_pk_mul_f32 v[206:207], v[62:63], v[194:195] op_sel_hi:[1,0]
	v_cvt_pk_bf16_f32 v204, v204, v205
	s_nop 0
	v_cvt_pk_bf16_f32 v205, v206, v207
	v_pk_mul_f32 v[206:207], v[56:57], v[194:195] op_sel_hi:[1,0]
	s_nop 0
	v_cvt_pk_bf16_f32 v206, v206, v207
	v_cvt_pk_bf16_f32 v207, v208, v209
	v_mad_i64_i32 v[208:209], s[2:3], v178, s41, v[148:149]
	v_lshl_add_u64 v[208:209], v[208:209], 0, v[150:151]
	global_store_dwordx4 v[208:209], v[204:207], off
	s_nop 1
	v_pk_mul_f32 v[204:205], v[52:53], v[194:195] op_sel_hi:[1,0]
	v_pk_mul_f32 v[206:207], v[54:55], v[194:195] op_sel_hi:[1,0]
	v_cvt_pk_bf16_f32 v204, v204, v205
	s_nop 0
	v_cvt_pk_bf16_f32 v205, v206, v207
	v_pk_mul_f32 v[206:207], v[48:49], v[194:195] op_sel_hi:[1,0]
	s_nop 0
	v_cvt_pk_bf16_f32 v206, v206, v207
	v_cvt_pk_bf16_f32 v207, v210, v211
	global_store_dwordx4 v[208:209], v[204:207], off offset:256
	v_pk_mul_f32 v[208:209], v[42:43], v[192:193] op_sel_hi:[1,0]
	v_pk_mul_f32 v[210:211], v[34:35], v[192:193] op_sel_hi:[1,0]
	v_pk_mul_f32 v[204:205], v[44:45], v[192:193] op_sel_hi:[1,0]
	v_pk_mul_f32 v[206:207], v[46:47], v[192:193] op_sel_hi:[1,0]
	v_cvt_pk_bf16_f32 v204, v204, v205
	s_nop 0
	v_cvt_pk_bf16_f32 v205, v206, v207
	v_pk_mul_f32 v[206:207], v[40:41], v[192:193] op_sel_hi:[1,0]
	s_nop 0
	v_cvt_pk_bf16_f32 v206, v206, v207
	v_cvt_pk_bf16_f32 v207, v208, v209
	v_mad_i64_i32 v[208:209], s[2:3], v176, s41, v[148:149]
	v_lshl_add_u64 v[208:209], v[208:209], 0, v[150:151]
	global_store_dwordx4 v[208:209], v[204:207], off
	s_nop 1
	v_pk_mul_f32 v[204:205], v[36:37], v[192:193] op_sel_hi:[1,0]
	v_pk_mul_f32 v[206:207], v[38:39], v[192:193] op_sel_hi:[1,0]
	v_cvt_pk_bf16_f32 v204, v204, v205
	s_nop 0
	v_cvt_pk_bf16_f32 v205, v206, v207
	v_pk_mul_f32 v[206:207], v[32:33], v[192:193] op_sel_hi:[1,0]
	s_nop 0
	v_cvt_pk_bf16_f32 v206, v206, v207
	v_cvt_pk_bf16_f32 v207, v210, v211
	global_store_dwordx4 v[208:209], v[204:207], off offset:256
	v_pk_mul_f32 v[208:209], v[26:27], v[190:191] op_sel_hi:[1,0]
	s_nop 0
	v_pk_mul_f32 v[204:205], v[28:29], v[190:191] op_sel_hi:[1,0]
	v_pk_mul_f32 v[206:207], v[30:31], v[190:191] op_sel_hi:[1,0]
	v_cvt_pk_bf16_f32 v204, v204, v205
	s_nop 0
	v_cvt_pk_bf16_f32 v205, v206, v207
	v_pk_mul_f32 v[206:207], v[24:25], v[190:191] op_sel_hi:[1,0]
	s_nop 0
	v_cvt_pk_bf16_f32 v206, v206, v207
	v_cvt_pk_bf16_f32 v207, v208, v209
	v_mad_i64_i32 v[208:209], s[2:3], v174, s41, v[148:149]
	v_lshl_add_u64 v[208:209], v[208:209], 0, v[150:151]
	global_store_dwordx4 v[208:209], v[204:207], off
	v_mad_i64_i32 v[148:149], s[2:3], v170, s41, v[148:149]
	s_nop 0
	v_pk_mul_f32 v[204:205], v[20:21], v[190:191] op_sel_hi:[1,0]
	v_pk_mul_f32 v[206:207], v[22:23], v[190:191] op_sel_hi:[1,0]
	v_cvt_pk_bf16_f32 v204, v204, v205
	v_lshl_add_u64 v[148:149], v[148:149], 0, v[150:151]
	v_cvt_pk_bf16_f32 v205, v206, v207
	v_pk_mul_f32 v[206:207], v[16:17], v[190:191] op_sel_hi:[1,0]
	v_pk_mul_f32 v[190:191], v[18:19], v[190:191] op_sel_hi:[1,0]
	v_cvt_pk_bf16_f32 v206, v206, v207
	v_pk_mul_f32 v[150:151], v[6:7], v[188:189] op_sel_hi:[1,0]
	v_cvt_pk_bf16_f32 v207, v190, v191
	global_store_dwordx4 v[208:209], v[204:207], off offset:256
	v_pk_mul_f32 v[208:209], v[10:11], v[188:189] op_sel_hi:[1,0]
	v_mad_i64_i32 v[190:191], s[2:3], v170, s41, 0
	v_pk_mul_f32 v[204:205], v[12:13], v[188:189] op_sel_hi:[1,0]
	v_pk_mul_f32 v[206:207], v[14:15], v[188:189] op_sel_hi:[1,0]
	v_cvt_pk_bf16_f32 v204, v204, v205
	s_nop 0
	v_cvt_pk_bf16_f32 v205, v206, v207
	v_pk_mul_f32 v[206:207], v[8:9], v[188:189] op_sel_hi:[1,0]
	s_nop 0
	v_cvt_pk_bf16_f32 v206, v206, v207
	v_cvt_pk_bf16_f32 v207, v208, v209
	global_store_dwordx4 v[148:149], v[204:207], off
	v_pk_mul_f32 v[148:149], v[4:5], v[188:189] op_sel_hi:[1,0]
	s_nop 0
	v_cvt_pk_bf16_f32 v148, v148, v149
	v_cvt_pk_bf16_f32 v149, v150, v151
	v_pk_mul_f32 v[150:151], v[0:1], v[188:189] op_sel_hi:[1,0]
	v_pk_mul_f32 v[204:205], v[2:3], v[188:189] op_sel_hi:[1,0]
	v_cvt_pk_bf16_f32 v150, v150, v151
	s_nop 0
	v_cvt_pk_bf16_f32 v151, v204, v205
	s_cbranch_execz .LBB0_385
	s_branch .LBB0_386

; __device__ __forceinline__ unsigned cvt_pk_bf16(float lo, float hi) { unsigned r; asm volatile("v_cvt_pk_bf16_f32 %0, %1, %2" : "=v"(r) : "v"(lo), "v"(hi)); return r; }
; template <int NP> __device__ __forceinline__ void load_rs(const float* ssp, int row0, int fq, float (&rs)[2][4]) {
;     ...
;             for (int m = 0; m < 4; ++m) { float s = (p[ai][m][0] + p[ai][m][1]) + (p[ai][m][2] + p[ai][m][3]); s += __shfl_xor(s, 16); s += __shfl_xor(s, 32); rs[ai][m] = s; }
;     }
; #pragma unroll
;     for (int ai = 0; ai < 2; ++ai)
; #pragma unroll
;         for (int m = 0; m < 4; ++m) rs[ai][m] = __builtin_amdgcn_rsqf(rs[ai][m] * (1.0f / D_MODEL) + RMS_EPS);
;     template <bool GATE> __device__ __forceinline__ void body(const f32x4 (&acc)[2][2][4][2], const Unit& u, int wr, int wc, int fr, int fq) const {
;     ...
;                 const int row = row0 + ai * HALF + m * 16; const float r = rs[ai][m], nrl = r * -1.44269504089f;
; #pragma unroll
;                 for (int bj = 0; bj < 2; ++bj) {
;                     unsigned pk[4];
; #pragma unroll
;                     for (int q = 0; q < 4; ++q) {
;                         const f32x4 va = acc[ai][bj][m][q >> 1]; const int e0 = 2 * (q & 1);
;                         const f32x2 v = (f32x2){va[e0], va[e0 + 1]};
;                         f32x2 o;
;                         if (GATE) { const f32x2 t = v * nrl; f32x2 ex; ex.x = __builtin_amdgcn_exp2f(t.x); ex.y = __builtin_amdgcn_exp2f(t.y);
;                             const f32x2 d = ex + 1.0f; o.x = __builtin_amdgcn_rcpf(d.x); o.y = __builtin_amdgcn_rcpf(d.y); }
;                         else o = v * r;
;                         pk[q] = cvt_pk_bf16(o.x, o.y);
;                     }
;                     u32x4 w; w.x = pk[0]; w.y = pk[1]; w.z = pk[2]; w.w = pk[3];
;                     *(u32x4*)(P + (size_t)row * PITCH + col0 + bj * HALF) = w;
.LBB0_385:
	v_mov_b32_e32 v236, v177
	s_nop 1
	v_permlane16_swap_b32_e32 v177, v236
	v_mov_b32_e32 v148, v141
	v_mov_b32_e32 v149, v142
	v_mov_b32_e32 v237, v179
	s_nop 1
	v_permlane16_swap_b32_e32 v179, v237
	v_mov_b32_e32 v238, v181
	s_nop 1
	v_permlane16_swap_b32_e32 v181, v238
	s_waitcnt lgkmcnt(2)
	v_add_f32_e32 v141, v177, v236
	v_mov_b32_e32 v236, v141
	s_nop 1
	v_permlane32_swap_b32_e32 v141, v236
	v_readlane_b32 s2, v235, 44
	s_waitcnt lgkmcnt(2)
	v_add_f32_e32 v150, v179, v237
	v_mov_b32_e32 v237, v150
	s_nop 1
	v_permlane32_swap_b32_e32 v150, v237
	s_waitcnt lgkmcnt(2)
	v_add_f32_e32 v151, v181, v238
	s_waitcnt lgkmcnt(1)
	v_add_f32_e32 v142, v141, v236
	v_mov_b32_e32 v141, v143
	v_pk_add_f32 v[140:141], v[148:149], v[140:141]
	v_mov_b32_e32 v236, v151
	s_nop 1
	v_permlane32_swap_b32_e32 v151, v236
	v_add_f32_e32 v143, v140, v141
	v_mov_b32_e32 v140, v145
	v_mov_b32_e32 v141, v146
	v_mov_b32_e32 v145, v147
	v_pk_add_f32 v[140:141], v[140:141], v[144:145]
	v_mov_b32_e32 v238, v143
	s_nop 1
	v_permlane16_swap_b32_e32 v143, v238
	v_add_f32_e32 v140, v140, v141
	v_mov_b32_e32 v239, v140
	s_nop 1
	v_permlane16_swap_b32_e32 v140, v239
	s_waitcnt lgkmcnt(3)
	v_add_f32_e32 v144, v150, v237
	s_waitcnt lgkmcnt(2)
	v_add_f32_e32 v145, v151, v236
	s_waitcnt lgkmcnt(1)
	v_add_f32_e32 v143, v143, v238
	v_mov_b32_e32 v236, v143
	s_nop 1
	v_permlane32_swap_b32_e32 v143, v236
	s_waitcnt lgkmcnt(1)
	v_add_f32_e32 v147, v140, v239
	v_mov_b32_e32 v140, v133
	v_mov_b32_e32 v141, v134
	v_mov_b32_e32 v133, v135
	v_pk_add_f32 v[132:133], v[140:141], v[132:133]
	v_mov_b32_e32 v237, v147
	s_nop 1
	v_permlane32_swap_b32_e32 v147, v237
	v_add_f32_e32 v134, v132, v133
	v_mov_b32_e32 v132, v137
	v_mov_b32_e32 v133, v138
	v_mov_b32_e32 v137, v139
	v_pk_add_f32 v[132:133], v[132:133], v[136:137]
	v_mov_b32_e32 v238, v134
	s_nop 1
	v_permlane16_swap_b32_e32 v134, v238
	v_add_f32_e32 v136, v132, v133
	v_mov_b32_e32 v132, v129
	v_mov_b32_e32 v133, v130
	v_mov_b32_e32 v129, v131
	v_pk_add_f32 v[128:129], v[132:133], v[128:129]
	v_mov_b32_e32 v239, v136
	s_nop 1
	v_permlane16_swap_b32_e32 v136, v239
	v_add_f32_e32 v128, v128, v129
	v_mov_b32_e32 v240, v128
	s_nop 1
	v_permlane16_swap_b32_e32 v128, v240
	s_waitcnt lgkmcnt(2)
	v_add_f32_e32 v130, v134, v238
	v_mov_b32_e32 v238, v130
	s_nop 1
	v_permlane32_swap_b32_e32 v130, v238
	s_waitcnt lgkmcnt(2)
	v_add_f32_e32 v132, v136, v239
	v_mov_b32_e32 v239, v132
	s_nop 1
	v_permlane32_swap_b32_e32 v132, v239
	s_waitcnt lgkmcnt(2)
	v_add_f32_e32 v128, v128, v240
	v_mov_b32_e32 v240, v128
	s_nop 1
	v_permlane32_swap_b32_e32 v128, v240
	s_waitcnt lgkmcnt(2)
	v_add_f32_e32 v130, v130, v238
	v_add_f32_e32 v134, v143, v236
	s_waitcnt lgkmcnt(1)
	v_add_f32_e32 v131, v132, v239
	v_add_f32_e32 v135, v147, v237
	s_waitcnt lgkmcnt(0)
	v_add_f32_e32 v128, v128, v240
	v_fmamk_f32 v129, v142, 0x3a800000, v202
	v_rsq_f32_e32 v132, v129
	v_fmamk_f32 v129, v144, 0x3a800000, v202
	v_rsq_f32_e32 v133, v129
	v_fmamk_f32 v129, v145, 0x3a800000, v202
	v_mul_f32_e32 v132, 0xbfb8aa3b, v132
	v_rsq_f32_e32 v136, v129
	v_pk_mul_f32 v[124:125], v[124:125], v[132:133] op_sel_hi:[1,0]
	v_pk_mul_f32 v[120:121], v[120:121], v[132:133] op_sel_hi:[1,0]
	v_exp_f32_e32 v124, v124
	v_exp_f32_e32 v125, v125
	v_pk_mul_f32 v[126:127], v[126:127], v[132:133] op_sel_hi:[1,0]
	v_exp_f32_e32 v120, v120
	v_exp_f32_e32 v121, v121
	v_pk_mul_f32 v[122:123], v[122:123], v[132:133] op_sel_hi:[1,0]
	v_exp_f32_e32 v126, v126
	v_exp_f32_e32 v127, v127
	v_exp_f32_e32 v122, v122
	v_exp_f32_e32 v123, v123
	v_fmamk_f32 v129, v134, 0x3a800000, v202
	v_rsq_f32_e32 v137, v129
	v_fmamk_f32 v129, v135, 0x3a800000, v202
	v_rsq_f32_e32 v138, v129
	v_fmamk_f32 v129, v130, 0x3a800000, v202
	v_pk_add_f32 v[124:125], v[124:125], 1.0 op_sel_hi:[1,0]
	v_pk_add_f32 v[120:121], v[120:121], 1.0 op_sel_hi:[1,0]
	v_pk_mul_f32 v[116:117], v[116:117], v[132:133] op_sel_hi:[1,0]
	v_pk_mul_f32 v[112:113], v[112:113], v[132:133] op_sel_hi:[1,0]
	v_rsq_f32_e32 v130, v129
	v_fmamk_f32 v129, v131, 0x3a800000, v202
	v_rcp_f32_e32 v131, v124
	v_rcp_f32_e32 v134, v125
	v_pk_add_f32 v[124:125], v[126:127], 1.0 op_sel_hi:[1,0]
	v_rcp_f32_e32 v127, v120
	v_rcp_f32_e32 v135, v121
	v_pk_add_f32 v[120:121], v[122:123], 1.0 op_sel_hi:[1,0]
	v_exp_f32_e32 v116, v116
	v_exp_f32_e32 v117, v117
	v_pk_mul_f32 v[118:119], v[118:119], v[132:133] op_sel_hi:[1,0]
	v_exp_f32_e32 v112, v112
	v_exp_f32_e32 v113, v113
	v_pk_mul_f32 v[114:115], v[114:115], v[132:133] op_sel_hi:[1,0]
	v_rcp_f32_e32 v126, v124
	v_rcp_f32_e32 v125, v125
	v_rcp_f32_e32 v120, v120
	v_rcp_f32_e32 v121, v121
	v_readlane_b32 s3, v235, 45
	v_exp_f32_e32 v118, v118
	v_exp_f32_e32 v119, v119
	v_exp_f32_e32 v114, v114
	v_exp_f32_e32 v115, v115
	v_cvt_pk_bf16_f32 v124, v131, v134
	v_cvt_pk_bf16_f32 v125, v126, v125
	v_cvt_pk_bf16_f32 v126, v127, v135
	v_cvt_pk_bf16_f32 v127, v120, v121
	v_mov_b64_e32 v[120:121], s[2:3]
	v_mad_i64_i32 v[134:135], s[2:3], v186, s41, v[120:121]
	v_lshlrev_b64 v[122:123], 1, v[160:161]
	v_lshl_add_u64 v[134:135], v[134:135], 0, v[122:123]
	v_pk_add_f32 v[116:117], v[116:117], 1.0 op_sel_hi:[1,0]
	v_pk_add_f32 v[112:113], v[112:113], 1.0 op_sel_hi:[1,0]
	global_store_dwordx4 v[134:135], v[124:127], off
	v_rsq_f32_e32 v129, v129
	v_fmamk_f32 v128, v128, 0x3a800000, v202
	v_rcp_f32_e32 v124, v116
	v_rcp_f32_e32 v125, v117
	v_pk_add_f32 v[116:117], v[118:119], 1.0 op_sel_hi:[1,0]
	v_rcp_f32_e32 v118, v112
	v_rcp_f32_e32 v119, v113
	v_pk_add_f32 v[112:113], v[114:115], 1.0 op_sel_hi:[1,0]
	v_rcp_f32_e32 v116, v116
	v_rcp_f32_e32 v115, v112
	v_cvt_pk_bf16_f32 v112, v124, v125
	v_rcp_f32_e32 v117, v117
	v_rcp_f32_e32 v126, v113
; __device__ __forceinline__ unsigned cvt_pk_bf16(float lo, float hi) { unsigned r; asm volatile("v_cvt_pk_bf16_f32 %0, %1, %2" : "=v"(r) : "v"(lo), "v"(hi)); return r; }
;     template <bool GATE> __device__ __forceinline__ void body(const f32x4 (&acc)[2][2][4][2], const Unit& u, int wr, int wc, int fr, int fq) const {
;     ...
;                 const int row = row0 + ai * HALF + m * 16; const float r = rs[ai][m], nrl = r * -1.44269504089f;
; #pragma unroll
;                 for (int bj = 0; bj < 2; ++bj) {
;                     unsigned pk[4];
; #pragma unroll
;                     for (int q = 0; q < 4; ++q) {
;                         const f32x4 va = acc[ai][bj][m][q >> 1]; const int e0 = 2 * (q & 1);
;                         const f32x2 v = (f32x2){va[e0], va[e0 + 1]};
;                         f32x2 o;
;                         if (GATE) { const f32x2 t = v * nrl; f32x2 ex; ex.x = __builtin_amdgcn_exp2f(t.x); ex.y = __builtin_amdgcn_exp2f(t.y);
;                             const f32x2 d = ex + 1.0f; o.x = __builtin_amdgcn_rcpf(d.x); o.y = __builtin_amdgcn_rcpf(d.y); }
;                         else o = v * r;
;                         pk[q] = cvt_pk_bf16(o.x, o.y);
;                     }
;                     u32x4 w; w.x = pk[0]; w.y = pk[1]; w.z = pk[2]; w.w = pk[3];
;                     *(u32x4*)(P + (size_t)row * PITCH + col0 + bj * HALF) = w;
	v_cvt_pk_bf16_f32 v113, v116, v117
	v_cvt_pk_bf16_f32 v114, v118, v119
	v_cvt_pk_bf16_f32 v115, v115, v126
	global_store_dwordx4 v[134:135], v[112:115], off offset:256
	v_rsq_f32_e32 v128, v128
	v_mad_i64_i32 v[190:191], s[2:3], v170, s41, 0
	v_mul_f32_e32 v112, 0xbfb8aa3b, v133
	v_pk_mul_f32 v[108:109], v[108:109], v[112:113] op_sel_hi:[1,0]
	v_pk_mul_f32 v[110:111], v[110:111], v[112:113] op_sel_hi:[1,0]
	v_exp_f32_e32 v108, v108
	v_exp_f32_e32 v109, v109
	v_exp_f32_e32 v110, v110
	v_exp_f32_e32 v111, v111
	v_pk_add_f32 v[108:109], v[108:109], 1.0 op_sel_hi:[1,0]
	s_nop 0
	v_rcp_f32_e32 v113, v108
	v_rcp_f32_e32 v114, v109
	v_pk_add_f32 v[108:109], v[110:111], 1.0 op_sel_hi:[1,0]
	v_pk_mul_f32 v[104:105], v[104:105], v[112:113] op_sel_hi:[1,0]
	s_nop 0
	v_exp_f32_e32 v104, v104
	v_exp_f32_e32 v105, v105
	v_pk_mul_f32 v[106:107], v[106:107], v[112:113] op_sel_hi:[1,0]
	v_pk_mul_f32 v[100:101], v[100:101], v[112:113] op_sel_hi:[1,0]
	v_exp_f32_e32 v106, v106
	v_exp_f32_e32 v107, v107
	v_pk_mul_f32 v[96:97], v[96:97], v[112:113] op_sel_hi:[1,0]
	v_exp_f32_e32 v100, v100
	v_exp_f32_e32 v101, v101
	v_pk_mul_f32 v[102:103], v[102:103], v[112:113] op_sel_hi:[1,0]
	v_exp_f32_e32 v96, v96
	v_exp_f32_e32 v97, v97
	v_pk_mul_f32 v[98:99], v[98:99], v[112:113] op_sel_hi:[1,0]
	v_pk_add_f32 v[104:105], v[104:105], 1.0 op_sel_hi:[1,0]
	v_exp_f32_e32 v102, v102
	v_exp_f32_e32 v103, v103
	v_exp_f32_e32 v98, v98
	v_exp_f32_e32 v99, v99
	v_rcp_f32_e32 v108, v108
	v_rcp_f32_e32 v109, v109
	v_rcp_f32_e32 v110, v104
	v_rcp_f32_e32 v111, v105
	v_pk_add_f32 v[104:105], v[106:107], 1.0 op_sel_hi:[1,0]
	v_pk_add_f32 v[100:101], v[100:101], 1.0 op_sel_hi:[1,0]
	v_rcp_f32_e32 v107, v104
	v_rcp_f32_e32 v115, v105
	v_cvt_pk_bf16_f32 v104, v113, v114
	v_cvt_pk_bf16_f32 v105, v108, v109
	v_mad_i64_i32 v[108:109], s[2:3], v184, s41, v[120:121]
	v_lshl_add_u64 v[108:109], v[108:109], 0, v[122:123]
	v_pk_add_f32 v[96:97], v[96:97], 1.0 op_sel_hi:[1,0]
	v_cvt_pk_bf16_f32 v106, v110, v111
	v_cvt_pk_bf16_f32 v107, v107, v115
	global_store_dwordx4 v[108:109], v[104:107], off
	s_nop 1
	v_rcp_f32_e32 v104, v100
	v_rcp_f32_e32 v105, v101
	v_pk_add_f32 v[100:101], v[102:103], 1.0 op_sel_hi:[1,0]
	v_rcp_f32_e32 v102, v96
	v_rcp_f32_e32 v103, v97
	v_pk_add_f32 v[96:97], v[98:99], 1.0 op_sel_hi:[1,0]
	v_rcp_f32_e32 v100, v100
	v_rcp_f32_e32 v99, v96
	v_cvt_pk_bf16_f32 v96, v104, v105
	v_rcp_f32_e32 v101, v101
	v_rcp_f32_e32 v106, v97
	v_cvt_pk_bf16_f32 v97, v100, v101
	v_cvt_pk_bf16_f32 v98, v102, v103
	v_cvt_pk_bf16_f32 v99, v99, v106
	global_store_dwordx4 v[108:109], v[96:99], off offset:256
	s_nop 1
	v_mul_f32_e32 v96, 0xbfb8aa3b, v136
	v_pk_mul_f32 v[92:93], v[92:93], v[96:97] op_sel_hi:[1,0]
	v_pk_mul_f32 v[94:95], v[94:95], v[96:97] op_sel_hi:[1,0]
	v_exp_f32_e32 v92, v92
	v_exp_f32_e32 v93, v93
	v_exp_f32_e32 v94, v94
	v_exp_f32_e32 v95, v95
	v_pk_add_f32 v[92:93], v[92:93], 1.0 op_sel_hi:[1,0]
	s_nop 0
	v_rcp_f32_e32 v97, v92
	v_rcp_f32_e32 v98, v93
	v_pk_add_f32 v[92:93], v[94:95], 1.0 op_sel_hi:[1,0]
	v_pk_mul_f32 v[88:89], v[88:89], v[96:97] op_sel_hi:[1,0]
	s_nop 0
	v_exp_f32_e32 v88, v88
	v_exp_f32_e32 v89, v89
	v_pk_mul_f32 v[90:91], v[90:91], v[96:97] op_sel_hi:[1,0]
	v_pk_mul_f32 v[84:85], v[84:85], v[96:97] op_sel_hi:[1,0]
	v_exp_f32_e32 v90, v90
	v_exp_f32_e32 v91, v91
	v_pk_mul_f32 v[80:81], v[80:81], v[96:97] op_sel_hi:[1,0]
	v_exp_f32_e32 v84, v84
	v_exp_f32_e32 v85, v85
	v_pk_mul_f32 v[86:87], v[86:87], v[96:97] op_sel_hi:[1,0]
	v_exp_f32_e32 v80, v80
	v_exp_f32_e32 v81, v81
	v_pk_mul_f32 v[82:83], v[82:83], v[96:97] op_sel_hi:[1,0]
	v_pk_add_f32 v[88:89], v[88:89], 1.0 op_sel_hi:[1,0]
	v_exp_f32_e32 v86, v86
	v_exp_f32_e32 v87, v87
	v_exp_f32_e32 v82, v82
	v_exp_f32_e32 v83, v83
	v_rcp_f32_e32 v92, v92
	v_rcp_f32_e32 v93, v93
	v_rcp_f32_e32 v94, v88
	v_rcp_f32_e32 v95, v89
	v_pk_add_f32 v[88:89], v[90:91], 1.0 op_sel_hi:[1,0]
	v_pk_add_f32 v[84:85], v[84:85], 1.0 op_sel_hi:[1,0]
	v_rcp_f32_e32 v91, v88
	v_rcp_f32_e32 v99, v89
	v_cvt_pk_bf16_f32 v88, v97, v98
	v_cvt_pk_bf16_f32 v89, v92, v93
	v_mad_i64_i32 v[92:93], s[2:3], v182, s41, v[120:121]
	v_lshl_add_u64 v[92:93], v[92:93], 0, v[122:123]
	v_pk_add_f32 v[80:81], v[80:81], 1.0 op_sel_hi:[1,0]
	v_cvt_pk_bf16_f32 v90, v94, v95
	v_cvt_pk_bf16_f32 v91, v91, v99
	global_store_dwordx4 v[92:93], v[88:91], off
	s_nop 1
	v_rcp_f32_e32 v88, v84
	v_rcp_f32_e32 v89, v85
	v_pk_add_f32 v[84:85], v[86:87], 1.0 op_sel_hi:[1,0]
	v_rcp_f32_e32 v86, v80
	v_rcp_f32_e32 v87, v81
	v_pk_add_f32 v[80:81], v[82:83], 1.0 op_sel_hi:[1,0]
	v_rcp_f32_e32 v84, v84
	v_rcp_f32_e32 v83, v80
	v_cvt_pk_bf16_f32 v80, v88, v89
	v_rcp_f32_e32 v85, v85
	v_rcp_f32_e32 v90, v81
	v_cvt_pk_bf16_f32 v81, v84, v85
	v_cvt_pk_bf16_f32 v82, v86, v87
	v_cvt_pk_bf16_f32 v83, v83, v90
	global_store_dwordx4 v[92:93], v[80:83], off offset:256
	s_nop 1
	v_mul_f32_e32 v80, 0xbfb8aa3b, v137
	v_pk_mul_f32 v[76:77], v[76:77], v[80:81] op_sel_hi:[1,0]
	v_pk_mul_f32 v[78:79], v[78:79], v[80:81] op_sel_hi:[1,0]
	v_exp_f32_e32 v76, v76
	v_exp_f32_e32 v77, v77
	v_exp_f32_e32 v78, v78
	v_exp_f32_e32 v79, v79
	v_pk_add_f32 v[76:77], v[76:77], 1.0 op_sel_hi:[1,0]
	s_nop 0
	v_rcp_f32_e32 v81, v76
	v_rcp_f32_e32 v82, v77
	v_pk_add_f32 v[76:77], v[78:79], 1.0 op_sel_hi:[1,0]
	v_pk_mul_f32 v[72:73], v[72:73], v[80:81] op_sel_hi:[1,0]
	s_nop 0
	v_exp_f32_e32 v72, v72
	v_exp_f32_e32 v73, v73
	v_pk_mul_f32 v[74:75], v[74:75], v[80:81] op_sel_hi:[1,0]
	v_pk_mul_f32 v[68:69], v[68:69], v[80:81] op_sel_hi:[1,0]
	v_exp_f32_e32 v74, v74
	v_exp_f32_e32 v75, v75
	v_pk_mul_f32 v[64:65], v[64:65], v[80:81] op_sel_hi:[1,0]
	v_exp_f32_e32 v68, v68
	v_exp_f32_e32 v69, v69
; __device__ __forceinline__ unsigned cvt_pk_bf16(float lo, float hi) { unsigned r; asm volatile("v_cvt_pk_bf16_f32 %0, %1, %2" : "=v"(r) : "v"(lo), "v"(hi)); return r; }
;     template <bool GATE> __device__ __forceinline__ void body(const f32x4 (&acc)[2][2][4][2], const Unit& u, int wr, int wc, int fr, int fq) const {
;     ...
;                 const int row = row0 + ai * HALF + m * 16; const float r = rs[ai][m], nrl = r * -1.44269504089f;
; #pragma unroll
;                 for (int bj = 0; bj < 2; ++bj) {
;                     unsigned pk[4];
; #pragma unroll
;                     for (int q = 0; q < 4; ++q) {
;                         const f32x4 va = acc[ai][bj][m][q >> 1]; const int e0 = 2 * (q & 1);
;                         const f32x2 v = (f32x2){va[e0], va[e0 + 1]};
;                         f32x2 o;
;                         if (GATE) { const f32x2 t = v * nrl; f32x2 ex; ex.x = __builtin_amdgcn_exp2f(t.x); ex.y = __builtin_amdgcn_exp2f(t.y);
;                             const f32x2 d = ex + 1.0f; o.x = __builtin_amdgcn_rcpf(d.x); o.y = __builtin_amdgcn_rcpf(d.y); }
;                         else o = v * r;
;                         pk[q] = cvt_pk_bf16(o.x, o.y);
;                     }
;                     u32x4 w; w.x = pk[0]; w.y = pk[1]; w.z = pk[2]; w.w = pk[3];
;                     *(u32x4*)(P + (size_t)row * PITCH + col0 + bj * HALF) = w;
	v_pk_mul_f32 v[70:71], v[70:71], v[80:81] op_sel_hi:[1,0]
	v_exp_f32_e32 v64, v64
	v_exp_f32_e32 v65, v65
	v_pk_mul_f32 v[66:67], v[66:67], v[80:81] op_sel_hi:[1,0]
	v_pk_add_f32 v[72:73], v[72:73], 1.0 op_sel_hi:[1,0]
	v_exp_f32_e32 v70, v70
	v_exp_f32_e32 v71, v71
	v_exp_f32_e32 v66, v66
	v_exp_f32_e32 v67, v67
	v_rcp_f32_e32 v76, v76
	v_rcp_f32_e32 v77, v77
	v_rcp_f32_e32 v78, v72
	v_rcp_f32_e32 v79, v73
	v_pk_add_f32 v[72:73], v[74:75], 1.0 op_sel_hi:[1,0]
	v_pk_add_f32 v[68:69], v[68:69], 1.0 op_sel_hi:[1,0]
	v_rcp_f32_e32 v75, v72
	v_rcp_f32_e32 v83, v73
	v_cvt_pk_bf16_f32 v72, v81, v82
	v_cvt_pk_bf16_f32 v73, v76, v77
	v_mad_i64_i32 v[76:77], s[2:3], v180, s41, v[120:121]
	v_lshl_add_u64 v[76:77], v[76:77], 0, v[122:123]
	v_pk_add_f32 v[64:65], v[64:65], 1.0 op_sel_hi:[1,0]
	v_cvt_pk_bf16_f32 v74, v78, v79
	v_cvt_pk_bf16_f32 v75, v75, v83
	global_store_dwordx4 v[76:77], v[72:75], off
	s_nop 1
	v_rcp_f32_e32 v72, v68
	v_rcp_f32_e32 v73, v69
	v_pk_add_f32 v[68:69], v[70:71], 1.0 op_sel_hi:[1,0]
	v_rcp_f32_e32 v70, v64
	v_rcp_f32_e32 v71, v65
	v_pk_add_f32 v[64:65], v[66:67], 1.0 op_sel_hi:[1,0]
	v_rcp_f32_e32 v68, v68
	v_rcp_f32_e32 v67, v64
	v_cvt_pk_bf16_f32 v64, v72, v73
	v_rcp_f32_e32 v69, v69
	v_rcp_f32_e32 v74, v65
	v_cvt_pk_bf16_f32 v65, v68, v69
	v_cvt_pk_bf16_f32 v66, v70, v71
	v_cvt_pk_bf16_f32 v67, v67, v74
	global_store_dwordx4 v[76:77], v[64:67], off offset:256
	s_nop 1
	v_mul_f32_e32 v64, 0xbfb8aa3b, v138
	v_pk_mul_f32 v[60:61], v[60:61], v[64:65] op_sel_hi:[1,0]
	v_pk_mul_f32 v[62:63], v[62:63], v[64:65] op_sel_hi:[1,0]
	v_exp_f32_e32 v60, v60
	v_exp_f32_e32 v61, v61
	v_exp_f32_e32 v62, v62
	v_exp_f32_e32 v63, v63
	v_pk_add_f32 v[60:61], v[60:61], 1.0 op_sel_hi:[1,0]
	s_nop 0
	v_rcp_f32_e32 v65, v60
	v_rcp_f32_e32 v66, v61
	v_pk_add_f32 v[60:61], v[62:63], 1.0 op_sel_hi:[1,0]
	v_pk_mul_f32 v[56:57], v[56:57], v[64:65] op_sel_hi:[1,0]
	s_nop 0
	v_exp_f32_e32 v56, v56
	v_exp_f32_e32 v57, v57
	v_pk_mul_f32 v[58:59], v[58:59], v[64:65] op_sel_hi:[1,0]
	v_pk_mul_f32 v[52:53], v[52:53], v[64:65] op_sel_hi:[1,0]
	v_exp_f32_e32 v58, v58
	v_exp_f32_e32 v59, v59
	v_pk_mul_f32 v[48:49], v[48:49], v[64:65] op_sel_hi:[1,0]
	v_exp_f32_e32 v52, v52
	v_exp_f32_e32 v53, v53
	v_pk_mul_f32 v[54:55], v[54:55], v[64:65] op_sel_hi:[1,0]
	v_exp_f32_e32 v48, v48
	v_exp_f32_e32 v49, v49
	v_pk_mul_f32 v[50:51], v[50:51], v[64:65] op_sel_hi:[1,0]
	v_pk_add_f32 v[56:57], v[56:57], 1.0 op_sel_hi:[1,0]
	v_exp_f32_e32 v54, v54
	v_exp_f32_e32 v55, v55
	v_exp_f32_e32 v50, v50
	v_exp_f32_e32 v51, v51
	v_rcp_f32_e32 v60, v60
	v_rcp_f32_e32 v61, v61
	v_rcp_f32_e32 v62, v56
	v_rcp_f32_e32 v63, v57
	v_pk_add_f32 v[56:57], v[58:59], 1.0 op_sel_hi:[1,0]
	v_pk_add_f32 v[52:53], v[52:53], 1.0 op_sel_hi:[1,0]
	v_rcp_f32_e32 v59, v56
	v_rcp_f32_e32 v67, v57
	v_cvt_pk_bf16_f32 v56, v65, v66
	v_cvt_pk_bf16_f32 v57, v60, v61
	v_mad_i64_i32 v[60:61], s[2:3], v178, s41, v[120:121]
	v_lshl_add_u64 v[60:61], v[60:61], 0, v[122:123]
	v_pk_add_f32 v[48:49], v[48:49], 1.0 op_sel_hi:[1,0]
	v_cvt_pk_bf16_f32 v58, v62, v63
	v_cvt_pk_bf16_f32 v59, v59, v67
	global_store_dwordx4 v[60:61], v[56:59], off
	s_nop 1
	v_rcp_f32_e32 v56, v52
	v_rcp_f32_e32 v57, v53
	v_pk_add_f32 v[52:53], v[54:55], 1.0 op_sel_hi:[1,0]
	v_rcp_f32_e32 v54, v48
	v_rcp_f32_e32 v55, v49
	v_pk_add_f32 v[48:49], v[50:51], 1.0 op_sel_hi:[1,0]
	v_rcp_f32_e32 v52, v52
	v_rcp_f32_e32 v51, v48
	v_cvt_pk_bf16_f32 v48, v56, v57
	v_rcp_f32_e32 v53, v53
	v_rcp_f32_e32 v58, v49
	v_cvt_pk_bf16_f32 v49, v52, v53
	v_cvt_pk_bf16_f32 v50, v54, v55
	v_cvt_pk_bf16_f32 v51, v51, v58
	global_store_dwordx4 v[60:61], v[48:51], off offset:256
	s_nop 1
	v_mul_f32_e32 v48, 0xbfb8aa3b, v130
	v_pk_mul_f32 v[44:45], v[44:45], v[48:49] op_sel_hi:[1,0]
	v_pk_mul_f32 v[46:47], v[46:47], v[48:49] op_sel_hi:[1,0]
	v_exp_f32_e32 v44, v44
	v_exp_f32_e32 v45, v45
	v_exp_f32_e32 v46, v46
	v_exp_f32_e32 v47, v47
	v_pk_add_f32 v[44:45], v[44:45], 1.0 op_sel_hi:[1,0]
	s_nop 0
	v_rcp_f32_e32 v49, v44
	v_rcp_f32_e32 v50, v45
	v_pk_add_f32 v[44:45], v[46:47], 1.0 op_sel_hi:[1,0]
	v_pk_mul_f32 v[40:41], v[40:41], v[48:49] op_sel_hi:[1,0]
	s_nop 0
	v_exp_f32_e32 v40, v40
	v_exp_f32_e32 v41, v41
	v_pk_mul_f32 v[42:43], v[42:43], v[48:49] op_sel_hi:[1,0]
	v_pk_mul_f32 v[36:37], v[36:37], v[48:49] op_sel_hi:[1,0]
	v_exp_f32_e32 v42, v42
	v_exp_f32_e32 v43, v43
	v_pk_mul_f32 v[32:33], v[32:33], v[48:49] op_sel_hi:[1,0]
	v_exp_f32_e32 v36, v36
	v_exp_f32_e32 v37, v37
	v_pk_mul_f32 v[38:39], v[38:39], v[48:49] op_sel_hi:[1,0]
	v_exp_f32_e32 v32, v32
	v_exp_f32_e32 v33, v33
	v_pk_mul_f32 v[34:35], v[34:35], v[48:49] op_sel_hi:[1,0]
	v_pk_add_f32 v[40:41], v[40:41], 1.0 op_sel_hi:[1,0]
	v_exp_f32_e32 v38, v38
	v_exp_f32_e32 v39, v39
	v_exp_f32_e32 v34, v34
	v_exp_f32_e32 v35, v35
	v_rcp_f32_e32 v44, v44
	v_rcp_f32_e32 v45, v45
	v_rcp_f32_e32 v46, v40
	v_rcp_f32_e32 v47, v41
	v_pk_add_f32 v[40:41], v[42:43], 1.0 op_sel_hi:[1,0]
	v_pk_add_f32 v[36:37], v[36:37], 1.0 op_sel_hi:[1,0]
	v_rcp_f32_e32 v43, v40
	v_rcp_f32_e32 v51, v41
	v_cvt_pk_bf16_f32 v40, v49, v50
	v_cvt_pk_bf16_f32 v41, v44, v45
; __device__ __forceinline__ unsigned cvt_pk_bf16(float lo, float hi) { unsigned r; asm volatile("v_cvt_pk_bf16_f32 %0, %1, %2" : "=v"(r) : "v"(lo), "v"(hi)); return r; }
;     template <bool GATE> __device__ __forceinline__ void body(const f32x4 (&acc)[2][2][4][2], const Unit& u, int wr, int wc, int fr, int fq) const {
;     ...
;                 const int row = row0 + ai * HALF + m * 16; const float r = rs[ai][m], nrl = r * -1.44269504089f;
; #pragma unroll
;                 for (int bj = 0; bj < 2; ++bj) {
;                     unsigned pk[4];
; #pragma unroll
;                     for (int q = 0; q < 4; ++q) {
;                         const f32x4 va = acc[ai][bj][m][q >> 1]; const int e0 = 2 * (q & 1);
;                         const f32x2 v = (f32x2){va[e0], va[e0 + 1]};
;                         f32x2 o;
;                         if (GATE) { const f32x2 t = v * nrl; f32x2 ex; ex.x = __builtin_amdgcn_exp2f(t.x); ex.y = __builtin_amdgcn_exp2f(t.y);
;                             const f32x2 d = ex + 1.0f; o.x = __builtin_amdgcn_rcpf(d.x); o.y = __builtin_amdgcn_rcpf(d.y); }
;                         else o = v * r;
;                         pk[q] = cvt_pk_bf16(o.x, o.y);
;                     }
;                     u32x4 w; w.x = pk[0]; w.y = pk[1]; w.z = pk[2]; w.w = pk[3];
;                     *(u32x4*)(P + (size_t)row * PITCH + col0 + bj * HALF) = w;
	v_mad_i64_i32 v[44:45], s[2:3], v176, s41, v[120:121]
	v_lshl_add_u64 v[44:45], v[44:45], 0, v[122:123]
	v_pk_add_f32 v[32:33], v[32:33], 1.0 op_sel_hi:[1,0]
	v_cvt_pk_bf16_f32 v42, v46, v47
	v_cvt_pk_bf16_f32 v43, v43, v51
	global_store_dwordx4 v[44:45], v[40:43], off
	s_nop 1
	v_rcp_f32_e32 v40, v36
	v_rcp_f32_e32 v41, v37
	v_pk_add_f32 v[36:37], v[38:39], 1.0 op_sel_hi:[1,0]
	v_rcp_f32_e32 v38, v32
	v_rcp_f32_e32 v39, v33
	v_pk_add_f32 v[32:33], v[34:35], 1.0 op_sel_hi:[1,0]
	v_rcp_f32_e32 v36, v36
	v_rcp_f32_e32 v35, v32
	v_cvt_pk_bf16_f32 v32, v40, v41
	v_rcp_f32_e32 v37, v37
	v_rcp_f32_e32 v42, v33
	v_cvt_pk_bf16_f32 v33, v36, v37
	v_cvt_pk_bf16_f32 v34, v38, v39
	v_cvt_pk_bf16_f32 v35, v35, v42
	global_store_dwordx4 v[44:45], v[32:35], off offset:256
	s_nop 1
	v_mul_f32_e32 v32, 0xbfb8aa3b, v129
	v_pk_mul_f32 v[28:29], v[28:29], v[32:33] op_sel_hi:[1,0]
	v_pk_mul_f32 v[30:31], v[30:31], v[32:33] op_sel_hi:[1,0]
	v_exp_f32_e32 v28, v28
	v_exp_f32_e32 v29, v29
	v_exp_f32_e32 v30, v30
	v_exp_f32_e32 v31, v31
	v_pk_add_f32 v[28:29], v[28:29], 1.0 op_sel_hi:[1,0]
	s_nop 0
	v_rcp_f32_e32 v33, v28
	v_rcp_f32_e32 v34, v29
	v_pk_add_f32 v[28:29], v[30:31], 1.0 op_sel_hi:[1,0]
	v_pk_mul_f32 v[24:25], v[24:25], v[32:33] op_sel_hi:[1,0]
	s_nop 0
	v_exp_f32_e32 v24, v24
	v_exp_f32_e32 v25, v25
	v_pk_mul_f32 v[26:27], v[26:27], v[32:33] op_sel_hi:[1,0]
	v_pk_mul_f32 v[20:21], v[20:21], v[32:33] op_sel_hi:[1,0]
	v_exp_f32_e32 v26, v26
	v_exp_f32_e32 v27, v27
	v_pk_mul_f32 v[16:17], v[16:17], v[32:33] op_sel_hi:[1,0]
	v_exp_f32_e32 v20, v20
	v_exp_f32_e32 v21, v21
	v_pk_mul_f32 v[22:23], v[22:23], v[32:33] op_sel_hi:[1,0]
	v_exp_f32_e32 v16, v16
	v_exp_f32_e32 v17, v17
	v_pk_mul_f32 v[18:19], v[18:19], v[32:33] op_sel_hi:[1,0]
	v_pk_add_f32 v[24:25], v[24:25], 1.0 op_sel_hi:[1,0]
	v_exp_f32_e32 v22, v22
	v_exp_f32_e32 v23, v23
	v_exp_f32_e32 v18, v18
	v_exp_f32_e32 v19, v19
	v_rcp_f32_e32 v28, v28
	v_rcp_f32_e32 v29, v29
	v_rcp_f32_e32 v30, v24
	v_rcp_f32_e32 v31, v25
	v_pk_add_f32 v[24:25], v[26:27], 1.0 op_sel_hi:[1,0]
	v_pk_add_f32 v[20:21], v[20:21], 1.0 op_sel_hi:[1,0]
	v_rcp_f32_e32 v27, v24
	v_rcp_f32_e32 v35, v25
	v_cvt_pk_bf16_f32 v24, v33, v34
	v_cvt_pk_bf16_f32 v25, v28, v29
	v_mad_i64_i32 v[28:29], s[2:3], v174, s41, v[120:121]
	v_lshl_add_u64 v[28:29], v[28:29], 0, v[122:123]
	v_pk_add_f32 v[16:17], v[16:17], 1.0 op_sel_hi:[1,0]
	v_cvt_pk_bf16_f32 v26, v30, v31
	v_cvt_pk_bf16_f32 v27, v27, v35
	global_store_dwordx4 v[28:29], v[24:27], off
	s_nop 1
	v_rcp_f32_e32 v24, v20
	v_rcp_f32_e32 v25, v21
	v_pk_add_f32 v[20:21], v[22:23], 1.0 op_sel_hi:[1,0]
	v_rcp_f32_e32 v22, v16
	v_rcp_f32_e32 v23, v17
	v_pk_add_f32 v[16:17], v[18:19], 1.0 op_sel_hi:[1,0]
	v_rcp_f32_e32 v20, v20
	v_rcp_f32_e32 v19, v16
	v_cvt_pk_bf16_f32 v16, v24, v25
	v_rcp_f32_e32 v21, v21
	v_rcp_f32_e32 v26, v17
	v_cvt_pk_bf16_f32 v17, v20, v21
	v_cvt_pk_bf16_f32 v18, v22, v23
	v_cvt_pk_bf16_f32 v19, v19, v26
	global_store_dwordx4 v[28:29], v[16:19], off offset:256
	s_nop 1
	v_mul_f32_e32 v16, 0xbfb8aa3b, v128
	v_pk_mul_f32 v[12:13], v[12:13], v[16:17] op_sel_hi:[1,0]
	v_pk_mul_f32 v[14:15], v[14:15], v[16:17] op_sel_hi:[1,0]
	v_exp_f32_e32 v12, v12
	v_exp_f32_e32 v13, v13
	v_exp_f32_e32 v14, v14
	v_exp_f32_e32 v15, v15
	v_pk_add_f32 v[12:13], v[12:13], 1.0 op_sel_hi:[1,0]
	s_nop 0
	v_rcp_f32_e32 v17, v12
	v_rcp_f32_e32 v18, v13
	v_pk_add_f32 v[12:13], v[14:15], 1.0 op_sel_hi:[1,0]
	v_pk_mul_f32 v[8:9], v[8:9], v[16:17] op_sel_hi:[1,0]
	s_nop 0
	v_exp_f32_e32 v8, v8
	v_exp_f32_e32 v9, v9
	v_pk_mul_f32 v[10:11], v[10:11], v[16:17] op_sel_hi:[1,0]
	v_pk_mul_f32 v[4:5], v[4:5], v[16:17] op_sel_hi:[1,0]
	v_exp_f32_e32 v10, v10
	v_exp_f32_e32 v11, v11
	v_pk_mul_f32 v[0:1], v[0:1], v[16:17] op_sel_hi:[1,0]
	v_exp_f32_e32 v4, v4
	v_exp_f32_e32 v5, v5
	v_pk_mul_f32 v[6:7], v[6:7], v[16:17] op_sel_hi:[1,0]
	v_exp_f32_e32 v0, v0
	v_exp_f32_e32 v1, v1
	v_pk_mul_f32 v[2:3], v[2:3], v[16:17] op_sel_hi:[1,0]
	v_pk_add_f32 v[8:9], v[8:9], 1.0 op_sel_hi:[1,0]
	v_exp_f32_e32 v6, v6
	v_exp_f32_e32 v7, v7
	v_exp_f32_e32 v2, v2
	v_exp_f32_e32 v3, v3
	v_rcp_f32_e32 v12, v12
	v_rcp_f32_e32 v13, v13
	v_rcp_f32_e32 v14, v8
	v_rcp_f32_e32 v15, v9
	v_pk_add_f32 v[8:9], v[10:11], 1.0 op_sel_hi:[1,0]
	v_pk_add_f32 v[4:5], v[4:5], 1.0 op_sel_hi:[1,0]
	v_rcp_f32_e32 v11, v8
	v_rcp_f32_e32 v19, v9
	v_cvt_pk_bf16_f32 v8, v17, v18
	v_cvt_pk_bf16_f32 v9, v12, v13
	v_mad_i64_i32 v[12:13], s[2:3], v170, s41, v[120:121]
	v_lshl_add_u64 v[12:13], v[12:13], 0, v[122:123]
	v_pk_add_f32 v[0:1], v[0:1], 1.0 op_sel_hi:[1,0]
	v_cvt_pk_bf16_f32 v10, v14, v15
	v_cvt_pk_bf16_f32 v11, v11, v19
	global_store_dwordx4 v[12:13], v[8:11], off
	s_nop 1
	v_rcp_f32_e32 v8, v4
	v_rcp_f32_e32 v9, v5
	v_pk_add_f32 v[4:5], v[6:7], 1.0 op_sel_hi:[1,0]
	v_rcp_f32_e32 v6, v0
	v_rcp_f32_e32 v7, v1
	v_pk_add_f32 v[0:1], v[2:3], 1.0 op_sel_hi:[1,0]
	v_rcp_f32_e32 v4, v4
	v_rcp_f32_e32 v5, v5
	v_rcp_f32_e32 v0, v0
	v_rcp_f32_e32 v1, v1
	v_cvt_pk_bf16_f32 v148, v8, v9
	v_cvt_pk_bf16_f32 v149, v4, v5
	v_cvt_pk_bf16_f32 v150, v6, v7
	v_cvt_pk_bf16_f32 v151, v0, v1

; __device__ __forceinline__ unsigned cvt_pk_bf16(float lo, float hi) { unsigned r; asm volatile("v_cvt_pk_bf16_f32 %0, %1, %2" : "=v"(r) : "v"(lo), "v"(hi)); return r; }
; __device__ __forceinline__ float bf_lo(unsigned w) { return __uint_as_float(w << 16); }
; __device__ __forceinline__ float bf_hi(unsigned w) { return __uint_as_float(w & 0xffff0000u); }
;     __device__ __forceinline__ void operator()(const f32x4 (&acc)[2][2][4][2], const Unit& u, int wr, int wc, int fr, int fq) const {
;     ...
;             for (int mm = 0; mm < RB; ++mm) { const size_t off = (size_t)(row0 + ai * HALF + (mh + mm) * 16) * D_MODEL + col0;
; #pragma unroll
;                 for (int bj = 0; bj < 2; ++bj) {
;                     if (BASE_F32) { bf[mm][bj][0] = *(const f32x4*)(basef + off + bj * HALF); bf[mm][bj][1] = *(const f32x4*)(basef + off + bj * HALF + 4); }
;                     else bb[mm][bj] = *(const u32x4*)(xb + off + bj * HALF);
;                 } }
;             asm volatile("" ::: "memory");
; #pragma unroll
;             for (int mm = 0; mm < RB; ++mm) {
;                 const int m = mh + mm;
;                 const int row = row0 + ai * HALF + m * 16; const size_t off = (size_t)row * D_MODEL + col0; float s = 0.f;
; #pragma unroll
;                 for (int bj = 0; bj < 2; ++bj) {
;                     f32x4 b0, b1;
;                     if (BASE_F32) { b0 = bf[mm][bj][0]; b1 = bf[mm][bj][1]; }
;                     else { const u32x4 w = bb[mm][bj]; b0 = (f32x4){bf_lo(w.x), bf_hi(w.x), bf_lo(w.y), bf_hi(w.y)}; b1 = (f32x4){bf_lo(w.z), bf_hi(w.z), bf_lo(w.w), bf_hi(w.w)}; }
;                     const f32x4 o0 = b0 + acc[ai][bj][m][0] * alpha, o1 = b1 + acc[ai][bj][m][1] * alpha;
;                     if (OUT_F32) { *(f32x4*)(out + off + bj * HALF) = o0; *(f32x4*)(out + off + bj * HALF + 4) = o1; }
;                     else { u32x4 w; w.x = cvt_pk_bf16(o0[0], o0[1]); w.y = cvt_pk_bf16(o0[2], o0[3]); w.z = cvt_pk_bf16(o1[0], o1[1]); w.w = cvt_pk_bf16(o1[2], o1[3]); *(u32x4*)(xb + off + bj * HALF) = w; }
;                     s += ((o0[0] * o0[0] + o0[1] * o0[1]) + (o0[2] * o0[2] + o0[3] * o0[3])) + ((o1[0] * o1[0] + o1[1] * o1[1]) + (o1[2] * o1[2] + o1[3] * o1[3]));
;                 }
;                 if (ssp) { s += __shfl_xor(s, 16); s += __shfl_xor(s, 32); if (fq == 0) ssp[(size_t)row * 16 + u.pn * 4 + wc] = s; }
.LBB0_826:
	s_mov_b32 s98, 0xffff0000
	s_mov_b32 s99, 0xffff0000
	s_mov_b32 s100, 0
	s_mov_b32 s101, -1
	v_lshl_or_b32 v166, s12, 8, v186
	v_lshl_add_u32 v168, s45, 8, v184
	v_ashrrev_i32_e32 v167, 31, v166
	v_readlane_b32 s2, v235, 38
	v_lshlrev_b64 v[194:195], 1, v[166:167]
	v_readlane_b32 s3, v235, 39
	v_ashrrev_i32_e32 v169, 31, v168
	v_lshlrev_b64 v[192:193], 11, v[168:169]
	v_lshl_add_u64 v[170:171], s[2:3], 0, v[194:195]
	v_lshl_add_u64 v[128:129], v[170:171], 0, v[192:193]
	global_load_dwordx4 v[198:201], v[128:129], off
	global_load_dwordx4 v[202:205], v[128:129], off offset:256
	v_or_b32_e32 v180, 16, v168
	v_or_b32_e32 v176, 32, v168
	v_or_b32_e32 v172, 48, v168
	v_ashrrev_i32_e32 v181, 31, v180
	v_ashrrev_i32_e32 v177, 31, v176
	v_ashrrev_i32_e32 v173, 31, v172
	v_lshlrev_b64 v[182:183], 11, v[180:181]
	v_lshlrev_b64 v[178:179], 11, v[176:177]
	v_lshlrev_b64 v[174:175], 11, v[172:173]
	v_lshl_add_u64 v[128:129], v[170:171], 0, v[182:183]
	v_lshl_add_u64 v[130:131], v[170:171], 0, v[178:179]
	v_lshl_add_u64 v[206:207], v[170:171], 0, v[174:175]
	global_load_dwordx4 v[148:151], v[128:129], off
	global_load_dwordx4 v[144:147], v[128:129], off offset:256
	global_load_dwordx4 v[140:143], v[130:131], off
	global_load_dwordx4 v[136:139], v[130:131], off offset:256
	global_load_dwordx4 v[132:135], v[206:207], off
	s_nop 0
	global_load_dwordx4 v[128:131], v[206:207], off offset:256
	v_and_b32_e32 v206, 64, v191
	v_xor_b32_e32 v197, 16, v191
	v_add_u32_e32 v206, 64, v206
	v_xor_b32_e32 v207, 32, v191
	v_cmp_lt_i32_e32 vcc, v197, v206
	s_lshl_b32 s8, s12, 2
	s_ashr_i32 s9, s8, 31
	v_cndmask_b32_e32 v197, v191, v197, vcc
	v_cmp_lt_i32_e32 vcc, v207, v206
	s_waitcnt vmcnt(0)
	v_lshlrev_b32_e32 v208, 16, v200
	v_cndmask_b32_e32 v214, v191, v207, vcc
	v_lshl_add_u64 v[206:207], s[2:3], 0, v[192:193]
	v_lshl_add_u64 v[194:195], v[206:207], 0, v[194:195]
	v_lshlrev_b32_e32 v206, 16, v198
	v_and_b32_e32 v207, 0xffff0000, v198
	v_lshlrev_b32_e32 v198, 16, v199
	v_and_b32_e32 v199, 0xffff0000, v199
	v_and_b32_e32 v209, 0xffff0000, v200
	v_lshlrev_b32_e32 v200, 16, v201
	v_and_b32_e32 v201, 0xffff0000, v201
	v_lshlrev_b32_e32 v210, 16, v202
	v_and_b32_e32 v211, 0xffff0000, v202
	v_lshlrev_b32_e32 v202, 16, v203
	v_and_b32_e32 v203, 0xffff0000, v203
	v_lshlrev_b32_e32 v212, 16, v204
	v_and_b32_e32 v213, 0xffff0000, v204
	v_lshlrev_b32_e32 v204, 16, v205
	v_and_b32_e32 v205, 0xffff0000, v205
	v_pk_add_f32 v[126:127], v[126:127], v[198:199]
	v_pk_add_f32 v[124:125], v[124:125], v[206:207]
	v_pk_add_f32 v[122:123], v[122:123], v[200:201]
	v_pk_add_f32 v[120:121], v[120:121], v[208:209]
	v_pk_add_f32 v[118:119], v[118:119], v[202:203]
	v_pk_add_f32 v[116:117], v[116:117], v[210:211]
	v_pk_add_f32 v[198:199], v[114:115], v[204:205]
	v_pk_add_f32 v[200:201], v[112:113], v[212:213]
	v_lshlrev_b32_e32 v192, 2, v197
	v_cvt_pk_bf16_f32 v112, v124, v125
	v_cvt_pk_bf16_f32 v113, v126, v127
	v_mul_f32_e32 v114, v125, v125
	v_mul_f32_e32 v115, v127, v127
	v_mul_f32_e32 v125, v121, v121
	v_mul_f32_e32 v127, v123, v123
	v_mul_f32_e32 v193, v117, v117
	v_mul_f32_e32 v197, v119, v119
	v_mul_f32_e32 v202, v201, v201
	v_mul_f32_e32 v203, v199, v199
	v_fmac_f32_e32 v114, v124, v124
	v_fmac_f32_e32 v115, v126, v126
	v_fmac_f32_e32 v125, v120, v120
	v_fmac_f32_e32 v127, v122, v122
	v_fmac_f32_e32 v193, v116, v116
	v_fmac_f32_e32 v197, v118, v118
	v_fmac_f32_e32 v202, v200, v200
	v_fmac_f32_e32 v203, v198, v198
	v_add_f32_e32 v114, v114, v115
	v_add_f32_e32 v115, v125, v127
	v_add_f32_e32 v124, v193, v197
	v_add_f32_e32 v125, v202, v203
	v_add_f32_e32 v114, v114, v115
	v_add_f32_e32 v115, v124, v125
	v_add_f32_e32 v124, v114, v115
	v_mov_b32_e32 v236, v124
	s_nop 1
	v_permlane16_swap_b32_e32 v124, v236
	v_cvt_pk_bf16_f32 v114, v120, v121
	v_cvt_pk_bf16_f32 v115, v122, v123
	global_store_dwordx4 v[194:195], v[112:115], off
	v_cvt_pk_bf16_f32 v116, v116, v117
	v_cvt_pk_bf16_f32 v117, v118, v119
	v_cvt_pk_bf16_f32 v118, v200, v201
	v_cvt_pk_bf16_f32 v119, v198, v199
	global_store_dwordx4 v[194:195], v[116:119], off offset:256
	s_waitcnt lgkmcnt(0)
	v_add_f32_e32 v113, v124, v236
	v_lshlrev_b32_e32 v112, 2, v214
	v_mov_b32_e32 v236, v113
	s_nop 1
	v_permlane32_swap_b32_e32 v113, v236
	s_and_saveexec_b64 s[2:3], s[4:5]
	s_cbranch_execz .LBB0_828
	v_lshlrev_b64 v[116:117], 6, v[168:169]
	v_lshl_add_u64 v[116:117], s[10:11], 0, v[116:117]
	v_lshl_add_u64 v[116:117], s[8:9], 2, v[116:117]
	s_lshl_b32 s12, s36, 2
	v_lshl_add_u64 v[116:117], v[116:117], 0, s[12:13]
	s_waitcnt lgkmcnt(0)
	v_add_f32_e32 v113, v113, v236
	global_store_dword v[116:117], v113, off
; __device__ __forceinline__ unsigned cvt_pk_bf16(float lo, float hi) { unsigned r; asm volatile("v_cvt_pk_bf16_f32 %0, %1, %2" : "=v"(r) : "v"(lo), "v"(hi)); return r; }
; __device__ __forceinline__ float bf_lo(unsigned w) { return __uint_as_float(w << 16); }
; __device__ __forceinline__ float bf_hi(unsigned w) { return __uint_as_float(w & 0xffff0000u); }
;     __device__ __forceinline__ void operator()(const f32x4 (&acc)[2][2][4][2], const Unit& u, int wr, int wc, int fr, int fq) const {
;     ...
;             for (int mm = 0; mm < RB; ++mm) {
;                 const int m = mh + mm;
;                 const int row = row0 + ai * HALF + m * 16; const size_t off = (size_t)row * D_MODEL + col0; float s = 0.f;
; #pragma unroll
;                 for (int bj = 0; bj < 2; ++bj) {
;                     f32x4 b0, b1;
;                     if (BASE_F32) { b0 = bf[mm][bj][0]; b1 = bf[mm][bj][1]; }
;                     else { const u32x4 w = bb[mm][bj]; b0 = (f32x4){bf_lo(w.x), bf_hi(w.x), bf_lo(w.y), bf_hi(w.y)}; b1 = (f32x4){bf_lo(w.z), bf_hi(w.z), bf_lo(w.w), bf_hi(w.w)}; }
;                     const f32x4 o0 = b0 + acc[ai][bj][m][0] * alpha, o1 = b1 + acc[ai][bj][m][1] * alpha;
;                     if (OUT_F32) { *(f32x4*)(out + off + bj * HALF) = o0; *(f32x4*)(out + off + bj * HALF + 4) = o1; }
;                     else { u32x4 w; w.x = cvt_pk_bf16(o0[0], o0[1]); w.y = cvt_pk_bf16(o0[2], o0[3]); w.z = cvt_pk_bf16(o1[0], o1[1]); w.w = cvt_pk_bf16(o1[2], o1[3]); *(u32x4*)(xb + off + bj * HALF) = w; }
;                     s += ((o0[0] * o0[0] + o0[1] * o0[1]) + (o0[2] * o0[2] + o0[3] * o0[3])) + ((o1[0] * o1[0] + o1[1] * o1[1]) + (o1[2] * o1[2] + o1[3] * o1[3]));
;                 }
;                 if (ssp) { s += __shfl_xor(s, 16); s += __shfl_xor(s, 32); if (fq == 0) ssp[(size_t)row * 16 + u.pn * 4 + wc] = s; }
.LBB0_828:
	s_or_b64 exec, exec, s[2:3]
	s_waitcnt lgkmcnt(0)
	v_lshlrev_b32_e32 v114, 16, v148
	v_and_b32_e32 v115, 0xffff0000, v148
	v_lshlrev_b32_e32 v116, 16, v149
	v_and_b32_e32 v117, 0xffff0000, v149
	v_lshlrev_b32_e32 v120, 16, v151
	v_and_b32_e32 v121, 0xffff0000, v151
	v_pk_add_f32 v[110:111], v[110:111], v[116:117]
	v_pk_add_f32 v[108:109], v[108:109], v[114:115]
	v_pk_add_f32 v[114:115], v[106:107], v[120:121]
	v_lshlrev_b32_e32 v120, 16, v145
	v_and_b32_e32 v121, 0xffff0000, v145
	v_lshlrev_b32_e32 v122, 16, v146
	v_and_b32_e32 v123, 0xffff0000, v146
	v_lshlrev_b32_e32 v118, 16, v150
	v_and_b32_e32 v119, 0xffff0000, v150
	v_pk_add_f32 v[102:103], v[102:103], v[120:121]
	v_pk_add_f32 v[120:121], v[96:97], v[122:123]
	v_mul_f32_e32 v96, v109, v109
	v_mul_f32_e32 v97, v111, v111
	v_pk_add_f32 v[116:117], v[104:105], v[118:119]
	v_lshlrev_b32_e32 v118, 16, v144
	v_and_b32_e32 v119, 0xffff0000, v144
	v_lshlrev_b32_e32 v124, 16, v147
	v_and_b32_e32 v125, 0xffff0000, v147
	v_fmac_f32_e32 v96, v108, v108
	v_fmac_f32_e32 v97, v110, v110
	v_pk_add_f32 v[100:101], v[100:101], v[118:119]
	v_pk_add_f32 v[118:119], v[98:99], v[124:125]
	v_add_f32_e32 v96, v96, v97
	v_mul_f32_e32 v97, v117, v117
	v_mul_f32_e32 v98, v115, v115
	v_fmac_f32_e32 v97, v116, v116
	v_fmac_f32_e32 v98, v114, v114
	v_add_f32_e32 v97, v97, v98
	v_add_f32_e32 v96, v96, v97
	v_mul_f32_e32 v97, v101, v101
	v_mul_f32_e32 v98, v103, v103
	v_fmac_f32_e32 v97, v100, v100
	v_fmac_f32_e32 v98, v102, v102
	v_add_f32_e32 v97, v97, v98
	v_mul_f32_e32 v98, v121, v121
	v_mul_f32_e32 v99, v119, v119
	v_fmac_f32_e32 v98, v120, v120
	v_fmac_f32_e32 v99, v118, v118
	v_add_f32_e32 v98, v98, v99
	v_add_f32_e32 v97, v97, v98
	v_add_f32_e32 v99, v96, v97
	v_cvt_pk_bf16_f32 v104, v108, v109
	v_cvt_pk_bf16_f32 v105, v110, v111
	v_mov_b32_e32 v236, v99
	s_nop 1
	v_permlane16_swap_b32_e32 v99, v236
	v_readlane_b32 s2, v235, 38
	v_readlane_b32 s3, v235, 39
	v_cvt_pk_bf16_f32 v106, v116, v117
	v_cvt_pk_bf16_f32 v107, v114, v115
	s_nop 1
	v_lshl_add_u64 v[96:97], s[2:3], 0, v[182:183]
	v_lshl_add_u64 v[108:109], v[166:167], 1, v[96:97]
	s_waitcnt lgkmcnt(0)
	v_add_f32_e32 v96, v99, v236
	v_mov_b32_e32 v236, v96
	s_nop 1
	v_permlane32_swap_b32_e32 v96, v236
	global_store_dwordx4 v[108:109], v[104:107], off
	v_cvt_pk_bf16_f32 v98, v100, v101
	v_cvt_pk_bf16_f32 v99, v102, v103
	v_cvt_pk_bf16_f32 v100, v120, v121
	v_cvt_pk_bf16_f32 v101, v118, v119
	global_store_dwordx4 v[108:109], v[98:101], off offset:256
	s_and_saveexec_b64 s[2:3], s[4:5]
	s_cbranch_execz .LBB0_830
	v_lshlrev_b64 v[98:99], 6, v[180:181]
	v_lshl_add_u64 v[98:99], s[10:11], 0, v[98:99]
	v_lshl_add_u64 v[98:99], s[8:9], 2, v[98:99]
	s_lshl_b32 s12, s36, 2
	v_lshl_add_u64 v[98:99], v[98:99], 0, s[12:13]
	s_waitcnt lgkmcnt(0)
	v_add_f32_e32 v96, v96, v236
	global_store_dword v[98:99], v96, off
.LBB0_830:
	s_or_b64 exec, exec, s[2:3]
	v_lshlrev_b32_e32 v96, 16, v140
	s_waitcnt lgkmcnt(0)
	v_and_b32_e32 v97, 0xffff0000, v140
	v_lshlrev_b32_e32 v98, 16, v141
	v_and_b32_e32 v99, 0xffff0000, v141
	v_lshlrev_b32_e32 v102, 16, v143
	v_and_b32_e32 v103, 0xffff0000, v143
	v_pk_add_f32 v[94:95], v[94:95], v[98:99]
	v_pk_add_f32 v[92:93], v[92:93], v[96:97]
	v_pk_add_f32 v[96:97], v[90:91], v[102:103]
	v_lshlrev_b32_e32 v102, 16, v137
	v_and_b32_e32 v103, 0xffff0000, v137
	v_lshlrev_b32_e32 v104, 16, v138
	v_and_b32_e32 v105, 0xffff0000, v138
	v_lshlrev_b32_e32 v100, 16, v142
	v_and_b32_e32 v101, 0xffff0000, v142
	v_pk_add_f32 v[86:87], v[86:87], v[102:103]
	v_pk_add_f32 v[102:103], v[80:81], v[104:105]
	v_mul_f32_e32 v80, v93, v93
	v_mul_f32_e32 v81, v95, v95
	v_pk_add_f32 v[98:99], v[88:89], v[100:101]
	v_lshlrev_b32_e32 v100, 16, v136
	v_and_b32_e32 v101, 0xffff0000, v136
	v_lshlrev_b32_e32 v106, 16, v139
	v_and_b32_e32 v107, 0xffff0000, v139
	v_fmac_f32_e32 v80, v92, v92
	v_fmac_f32_e32 v81, v94, v94
	v_pk_add_f32 v[84:85], v[84:85], v[100:101]
	v_pk_add_f32 v[100:101], v[82:83], v[106:107]
	v_add_f32_e32 v80, v80, v81
	v_mul_f32_e32 v81, v99, v99
	v_mul_f32_e32 v82, v97, v97
	v_fmac_f32_e32 v81, v98, v98
	v_fmac_f32_e32 v82, v96, v96
	v_add_f32_e32 v81, v81, v82
	v_add_f32_e32 v80, v80, v81
	v_mul_f32_e32 v81, v85, v85
	v_mul_f32_e32 v82, v87, v87
	v_fmac_f32_e32 v81, v84, v84
	v_fmac_f32_e32 v82, v86, v86
	v_add_f32_e32 v81, v81, v82
	v_mul_f32_e32 v82, v103, v103
	v_mul_f32_e32 v83, v101, v101
	v_fmac_f32_e32 v82, v102, v102
	v_fmac_f32_e32 v83, v100, v100
	v_add_f32_e32 v82, v82, v83
	v_add_f32_e32 v81, v81, v82
	v_add_f32_e32 v83, v80, v81
	v_cvt_pk_bf16_f32 v88, v92, v93
	v_cvt_pk_bf16_f32 v89, v94, v95
	v_mov_b32_e32 v236, v83
	s_nop 1
	v_permlane16_swap_b32_e32 v83, v236
	v_readlane_b32 s2, v235, 38
	v_readlane_b32 s3, v235, 39
	v_cvt_pk_bf16_f32 v90, v98, v99
	v_cvt_pk_bf16_f32 v91, v96, v97
	s_nop 1
	v_lshl_add_u64 v[80:81], s[2:3], 0, v[178:179]
	v_lshl_add_u64 v[92:93], v[166:167], 1, v[80:81]
	s_waitcnt lgkmcnt(0)
	v_add_f32_e32 v80, v83, v236
	v_mov_b32_e32 v236, v80
	s_nop 1
	v_permlane32_swap_b32_e32 v80, v236
	global_store_dwordx4 v[92:93], v[88:91], off
	v_cvt_pk_bf16_f32 v82, v84, v85
	v_cvt_pk_bf16_f32 v83, v86, v87
	v_cvt_pk_bf16_f32 v84, v102, v103
	v_cvt_pk_bf16_f32 v85, v100, v101
	global_store_dwordx4 v[92:93], v[82:85], off offset:256
	s_and_saveexec_b64 s[2:3], s[4:5]
	s_cbranch_execz .LBB0_832
	v_lshlrev_b64 v[82:83], 6, v[176:177]
	v_lshl_add_u64 v[82:83], s[10:11], 0, v[82:83]
	v_lshl_add_u64 v[82:83], s[8:9], 2, v[82:83]
	s_lshl_b32 s12, s36, 2
	v_lshl_add_u64 v[82:83], v[82:83], 0, s[12:13]
	s_waitcnt lgkmcnt(0)
	v_add_f32_e32 v80, v80, v236
	global_store_dword v[82:83], v80, off
; __device__ __forceinline__ unsigned cvt_pk_bf16(float lo, float hi) { unsigned r; asm volatile("v_cvt_pk_bf16_f32 %0, %1, %2" : "=v"(r) : "v"(lo), "v"(hi)); return r; }
; __device__ __forceinline__ float bf_lo(unsigned w) { return __uint_as_float(w << 16); }
; __device__ __forceinline__ float bf_hi(unsigned w) { return __uint_as_float(w & 0xffff0000u); }
;     __device__ __forceinline__ void operator()(const f32x4 (&acc)[2][2][4][2], const Unit& u, int wr, int wc, int fr, int fq) const {
;     ...
;             for (int mm = 0; mm < RB; ++mm) { const size_t off = (size_t)(row0 + ai * HALF + (mh + mm) * 16) * D_MODEL + col0;
; #pragma unroll
;                 for (int bj = 0; bj < 2; ++bj) {
;                     if (BASE_F32) { bf[mm][bj][0] = *(const f32x4*)(basef + off + bj * HALF); bf[mm][bj][1] = *(const f32x4*)(basef + off + bj * HALF + 4); }
;                     else bb[mm][bj] = *(const u32x4*)(xb + off + bj * HALF);
;                 } }
;             asm volatile("" ::: "memory");
; #pragma unroll
;             for (int mm = 0; mm < RB; ++mm) {
;                 const int m = mh + mm;
;                 const int row = row0 + ai * HALF + m * 16; const size_t off = (size_t)row * D_MODEL + col0; float s = 0.f;
; #pragma unroll
;                 for (int bj = 0; bj < 2; ++bj) {
;                     f32x4 b0, b1;
;                     if (BASE_F32) { b0 = bf[mm][bj][0]; b1 = bf[mm][bj][1]; }
;                     else { const u32x4 w = bb[mm][bj]; b0 = (f32x4){bf_lo(w.x), bf_hi(w.x), bf_lo(w.y), bf_hi(w.y)}; b1 = (f32x4){bf_lo(w.z), bf_hi(w.z), bf_lo(w.w), bf_hi(w.w)}; }
;                     const f32x4 o0 = b0 + acc[ai][bj][m][0] * alpha, o1 = b1 + acc[ai][bj][m][1] * alpha;
;                     if (OUT_F32) { *(f32x4*)(out + off + bj * HALF) = o0; *(f32x4*)(out + off + bj * HALF + 4) = o1; }
;                     else { u32x4 w; w.x = cvt_pk_bf16(o0[0], o0[1]); w.y = cvt_pk_bf16(o0[2], o0[3]); w.z = cvt_pk_bf16(o1[0], o1[1]); w.w = cvt_pk_bf16(o1[2], o1[3]); *(u32x4*)(xb + off + bj * HALF) = w; }
;                     s += ((o0[0] * o0[0] + o0[1] * o0[1]) + (o0[2] * o0[2] + o0[3] * o0[3])) + ((o1[0] * o1[0] + o1[1] * o1[1]) + (o1[2] * o1[2] + o1[3] * o1[3]));
;                 }
;                 if (ssp) { s += __shfl_xor(s, 16); s += __shfl_xor(s, 32); if (fq == 0) ssp[(size_t)row * 16 + u.pn * 4 + wc] = s; }
.LBB0_832:
	s_or_b64 exec, exec, s[2:3]
	v_lshlrev_b32_e32 v80, 16, v132
	s_waitcnt lgkmcnt(0)
	v_and_b32_e32 v81, 0xffff0000, v132
	v_lshlrev_b32_e32 v82, 16, v133
	v_and_b32_e32 v83, 0xffff0000, v133
	v_lshlrev_b32_e32 v86, 16, v135
	v_and_b32_e32 v87, 0xffff0000, v135
	v_pk_add_f32 v[78:79], v[78:79], v[82:83]
	v_pk_add_f32 v[76:77], v[76:77], v[80:81]
	v_pk_add_f32 v[80:81], v[74:75], v[86:87]
	v_lshlrev_b32_e32 v86, 16, v129
	v_and_b32_e32 v87, 0xffff0000, v129
	v_lshlrev_b32_e32 v88, 16, v130
	v_and_b32_e32 v89, 0xffff0000, v130
	v_lshlrev_b32_e32 v84, 16, v134
	v_and_b32_e32 v85, 0xffff0000, v134
	v_pk_add_f32 v[70:71], v[70:71], v[86:87]
	v_pk_add_f32 v[86:87], v[64:65], v[88:89]
	v_mul_f32_e32 v64, v77, v77
	v_mul_f32_e32 v65, v79, v79
	v_pk_add_f32 v[82:83], v[72:73], v[84:85]
	v_lshlrev_b32_e32 v84, 16, v128
	v_and_b32_e32 v85, 0xffff0000, v128
	v_lshlrev_b32_e32 v90, 16, v131
	v_and_b32_e32 v91, 0xffff0000, v131
	v_fmac_f32_e32 v64, v76, v76
	v_fmac_f32_e32 v65, v78, v78
	v_pk_add_f32 v[68:69], v[68:69], v[84:85]
	v_pk_add_f32 v[84:85], v[66:67], v[90:91]
	v_add_f32_e32 v64, v64, v65
	v_mul_f32_e32 v65, v83, v83
	v_mul_f32_e32 v66, v81, v81
	v_fmac_f32_e32 v65, v82, v82
	v_fmac_f32_e32 v66, v80, v80
	v_add_f32_e32 v65, v65, v66
	v_add_f32_e32 v64, v64, v65
	v_mul_f32_e32 v65, v69, v69
	v_mul_f32_e32 v66, v71, v71
	v_fmac_f32_e32 v65, v68, v68
	v_fmac_f32_e32 v66, v70, v70
	v_add_f32_e32 v65, v65, v66
	v_mul_f32_e32 v66, v87, v87
	v_mul_f32_e32 v67, v85, v85
	v_fmac_f32_e32 v66, v86, v86
	v_fmac_f32_e32 v67, v84, v84
	v_add_f32_e32 v66, v66, v67
	v_add_f32_e32 v65, v65, v66
	v_add_f32_e32 v67, v64, v65
	v_cvt_pk_bf16_f32 v72, v76, v77
	v_cvt_pk_bf16_f32 v73, v78, v79
	v_mov_b32_e32 v236, v67
	s_nop 1
	v_permlane16_swap_b32_e32 v67, v236
	v_readlane_b32 s2, v235, 38
	v_readlane_b32 s3, v235, 39
	v_cvt_pk_bf16_f32 v74, v82, v83
	v_cvt_pk_bf16_f32 v75, v80, v81
	s_nop 1
	v_lshl_add_u64 v[64:65], s[2:3], 0, v[174:175]
	v_lshl_add_u64 v[76:77], v[166:167], 1, v[64:65]
	s_waitcnt lgkmcnt(0)
	v_add_f32_e32 v64, v67, v236
	v_mov_b32_e32 v236, v64
	s_nop 1
	v_permlane32_swap_b32_e32 v64, v236
	global_store_dwordx4 v[76:77], v[72:75], off
	v_cvt_pk_bf16_f32 v66, v68, v69
	v_cvt_pk_bf16_f32 v67, v70, v71
	v_cvt_pk_bf16_f32 v68, v86, v87
	v_cvt_pk_bf16_f32 v69, v84, v85
	global_store_dwordx4 v[76:77], v[66:69], off offset:256
	s_and_saveexec_b64 s[2:3], s[4:5]
	s_cbranch_execz .LBB0_834
	v_lshlrev_b64 v[66:67], 6, v[172:173]
	v_lshl_add_u64 v[66:67], s[10:11], 0, v[66:67]
	v_lshl_add_u64 v[66:67], s[8:9], 2, v[66:67]
	s_lshl_b32 s12, s36, 2
	v_lshl_add_u64 v[66:67], v[66:67], 0, s[12:13]
	s_waitcnt lgkmcnt(0)
	v_add_f32_e32 v64, v64, v236
	global_store_dword v[66:67], v64, off
.LBB0_834:
	s_or_b64 exec, exec, s[2:3]
	v_add_u32_e32 v100, 0x80, v168
	v_ashrrev_i32_e32 v101, 31, v100
	v_lshlrev_b64 v[110:111], 11, v[100:101]
	s_waitcnt lgkmcnt(0)
	v_lshl_add_u64 v[64:65], v[170:171], 0, v[110:111]
	global_load_dwordx4 v[102:105], v[64:65], off
	global_load_dwordx4 v[106:109], v[64:65], off offset:256
	v_add_u32_e32 v96, 0x90, v168
	v_add_u32_e32 v92, 0xa0, v168
	v_add_u32_e32 v88, 0xb0, v168
	v_ashrrev_i32_e32 v97, 31, v96
	v_ashrrev_i32_e32 v93, 31, v92
	v_ashrrev_i32_e32 v89, 31, v88
	v_lshlrev_b64 v[98:99], 11, v[96:97]
	v_lshlrev_b64 v[94:95], 11, v[92:93]
	v_lshlrev_b64 v[90:91], 11, v[88:89]
	v_lshl_add_u64 v[64:65], v[170:171], 0, v[98:99]
	v_lshl_add_u64 v[66:67], v[170:171], 0, v[94:95]
	v_lshl_add_u64 v[114:115], v[170:171], 0, v[90:91]
	global_load_dwordx4 v[84:87], v[64:65], off
	global_load_dwordx4 v[80:83], v[64:65], off offset:256
	global_load_dwordx4 v[76:79], v[66:67], off
	global_load_dwordx4 v[72:75], v[66:67], off offset:256
	global_load_dwordx4 v[68:71], v[114:115], off
	s_nop 0
	global_load_dwordx4 v[64:67], v[114:115], off offset:256
	v_readlane_b32 s2, v235, 38
	v_readlane_b32 s3, v235, 39
	s_waitcnt vmcnt(7)
	v_lshlrev_b32_e32 v114, 16, v102
	v_and_b32_e32 v115, 0xffff0000, v102
	v_lshlrev_b32_e32 v102, 16, v103
	v_and_b32_e32 v103, 0xffff0000, v103
	v_lshlrev_b32_e32 v116, 16, v104
	v_and_b32_e32 v117, 0xffff0000, v104
	v_lshlrev_b32_e32 v104, 16, v105
	v_and_b32_e32 v105, 0xffff0000, v105
	s_waitcnt vmcnt(6)
	v_lshlrev_b32_e32 v118, 16, v106
	v_and_b32_e32 v119, 0xffff0000, v106
	v_lshlrev_b32_e32 v106, 16, v107
	v_and_b32_e32 v107, 0xffff0000, v107
	v_lshlrev_b32_e32 v120, 16, v108
	v_and_b32_e32 v121, 0xffff0000, v108
	v_lshlrev_b32_e32 v108, 16, v109
	v_and_b32_e32 v109, 0xffff0000, v109
	v_pk_add_f32 v[62:63], v[62:63], v[102:103]
	v_pk_add_f32 v[60:61], v[60:61], v[114:115]
	v_pk_add_f32 v[58:59], v[58:59], v[104:105]
	v_pk_add_f32 v[56:57], v[56:57], v[116:117]
	v_pk_add_f32 v[54:55], v[54:55], v[106:107]
	v_pk_add_f32 v[52:53], v[52:53], v[118:119]
	v_pk_add_f32 v[102:103], v[50:51], v[108:109]
	v_pk_add_f32 v[104:105], v[48:49], v[120:121]
	v_cvt_pk_bf16_f32 v48, v60, v61
	v_cvt_pk_bf16_f32 v49, v62, v63
	v_cvt_pk_bf16_f32 v50, v56, v57
	v_cvt_pk_bf16_f32 v51, v58, v59
	v_mul_f32_e32 v61, v61, v61
	v_mul_f32_e32 v63, v63, v63
	v_mul_f32_e32 v57, v57, v57
	v_mul_f32_e32 v59, v59, v59
	v_mul_f32_e32 v106, v53, v53
	v_mul_f32_e32 v107, v55, v55
	v_mul_f32_e32 v108, v105, v105
	v_mul_f32_e32 v109, v103, v103
	v_fmac_f32_e32 v61, v60, v60
	v_fmac_f32_e32 v63, v62, v62
	v_fmac_f32_e32 v57, v56, v56
	v_fmac_f32_e32 v59, v58, v58
	v_fmac_f32_e32 v106, v52, v52
	v_fmac_f32_e32 v107, v54, v54
	v_fmac_f32_e32 v108, v104, v104
	v_fmac_f32_e32 v109, v102, v102
	v_add_f32_e32 v56, v61, v63
	v_add_f32_e32 v57, v57, v59
	v_add_f32_e32 v58, v106, v107
	v_add_f32_e32 v59, v108, v109
	v_add_f32_e32 v56, v56, v57
	v_add_f32_e32 v57, v58, v59
	v_add_f32_e32 v58, v56, v57
	v_mov_b32_e32 v236, v58
	s_nop 1
	v_permlane16_swap_b32_e32 v58, v236
	v_lshl_add_u64 v[56:57], s[2:3], 0, v[110:111]
	v_lshl_add_u64 v[56:57], v[166:167], 1, v[56:57]
	global_store_dwordx4 v[56:57], v[48:51], off
	s_waitcnt lgkmcnt(0)
	s_nop 0
	v_add_f32_e32 v48, v58, v236
	v_mov_b32_e32 v236, v48
	s_nop 1
	v_permlane32_swap_b32_e32 v48, v236
	v_cvt_pk_bf16_f32 v50, v52, v53
	v_cvt_pk_bf16_f32 v51, v54, v55
	v_cvt_pk_bf16_f32 v52, v104, v105
	v_cvt_pk_bf16_f32 v53, v102, v103
	global_store_dwordx4 v[56:57], v[50:53], off offset:256
	s_and_saveexec_b64 s[2:3], s[4:5]
	s_cbranch_execz .LBB0_836
	v_lshlrev_b64 v[50:51], 6, v[100:101]
	v_lshl_add_u64 v[50:51], s[10:11], 0, v[50:51]
	v_lshl_add_u64 v[50:51], s[8:9], 2, v[50:51]
	s_lshl_b32 s12, s36, 2
	v_lshl_add_u64 v[50:51], v[50:51], 0, s[12:13]
	s_waitcnt lgkmcnt(0)
	v_add_f32_e32 v48, v48, v236
	global_store_dword v[50:51], v48, off
; __device__ __forceinline__ unsigned cvt_pk_bf16(float lo, float hi) { unsigned r; asm volatile("v_cvt_pk_bf16_f32 %0, %1, %2" : "=v"(r) : "v"(lo), "v"(hi)); return r; }
; __device__ __forceinline__ float bf_lo(unsigned w) { return __uint_as_float(w << 16); }
; __device__ __forceinline__ float bf_hi(unsigned w) { return __uint_as_float(w & 0xffff0000u); }
;     __device__ __forceinline__ void operator()(const f32x4 (&acc)[2][2][4][2], const Unit& u, int wr, int wc, int fr, int fq) const {
;     ...
;             for (int mm = 0; mm < RB; ++mm) {
;                 const int m = mh + mm;
;                 const int row = row0 + ai * HALF + m * 16; const size_t off = (size_t)row * D_MODEL + col0; float s = 0.f;
; #pragma unroll
;                 for (int bj = 0; bj < 2; ++bj) {
;                     f32x4 b0, b1;
;                     if (BASE_F32) { b0 = bf[mm][bj][0]; b1 = bf[mm][bj][1]; }
;                     else { const u32x4 w = bb[mm][bj]; b0 = (f32x4){bf_lo(w.x), bf_hi(w.x), bf_lo(w.y), bf_hi(w.y)}; b1 = (f32x4){bf_lo(w.z), bf_hi(w.z), bf_lo(w.w), bf_hi(w.w)}; }
;                     const f32x4 o0 = b0 + acc[ai][bj][m][0] * alpha, o1 = b1 + acc[ai][bj][m][1] * alpha;
;                     if (OUT_F32) { *(f32x4*)(out + off + bj * HALF) = o0; *(f32x4*)(out + off + bj * HALF + 4) = o1; }
;                     else { u32x4 w; w.x = cvt_pk_bf16(o0[0], o0[1]); w.y = cvt_pk_bf16(o0[2], o0[3]); w.z = cvt_pk_bf16(o1[0], o1[1]); w.w = cvt_pk_bf16(o1[2], o1[3]); *(u32x4*)(xb + off + bj * HALF) = w; }
;                     s += ((o0[0] * o0[0] + o0[1] * o0[1]) + (o0[2] * o0[2] + o0[3] * o0[3])) + ((o1[0] * o1[0] + o1[1] * o1[1]) + (o1[2] * o1[2] + o1[3] * o1[3]));
;                 }
;                 if (ssp) { s += __shfl_xor(s, 16); s += __shfl_xor(s, 32); if (fq == 0) ssp[(size_t)row * 16 + u.pn * 4 + wc] = s; }
.LBB0_836:
	s_or_b64 exec, exec, s[2:3]
	s_waitcnt vmcnt(7)
	v_lshlrev_b32_e32 v48, 16, v84
	s_waitcnt lgkmcnt(0)
	v_and_b32_e32 v49, 0xffff0000, v84
	v_lshlrev_b32_e32 v50, 16, v85
	v_and_b32_e32 v51, 0xffff0000, v85
	v_lshlrev_b32_e32 v54, 16, v87
	v_and_b32_e32 v55, 0xffff0000, v87
	v_pk_add_f32 v[46:47], v[46:47], v[50:51]
	v_pk_add_f32 v[44:45], v[44:45], v[48:49]
	v_pk_add_f32 v[48:49], v[42:43], v[54:55]
	s_waitcnt vmcnt(6)
	v_lshlrev_b32_e32 v54, 16, v81
	v_and_b32_e32 v55, 0xffff0000, v81
	v_lshlrev_b32_e32 v56, 16, v82
	v_and_b32_e32 v57, 0xffff0000, v82
	v_lshlrev_b32_e32 v52, 16, v86
	v_and_b32_e32 v53, 0xffff0000, v86
	v_pk_add_f32 v[38:39], v[38:39], v[54:55]
	v_pk_add_f32 v[54:55], v[32:33], v[56:57]
	v_mul_f32_e32 v32, v45, v45
	v_mul_f32_e32 v33, v47, v47
	v_pk_add_f32 v[50:51], v[40:41], v[52:53]
	v_lshlrev_b32_e32 v52, 16, v80
	v_and_b32_e32 v53, 0xffff0000, v80
	v_lshlrev_b32_e32 v58, 16, v83
	v_and_b32_e32 v59, 0xffff0000, v83
	v_fmac_f32_e32 v32, v44, v44
	v_fmac_f32_e32 v33, v46, v46
	v_pk_add_f32 v[36:37], v[36:37], v[52:53]
	v_pk_add_f32 v[52:53], v[34:35], v[58:59]
	v_add_f32_e32 v32, v32, v33
	v_mul_f32_e32 v33, v51, v51
	v_mul_f32_e32 v34, v49, v49
	v_fmac_f32_e32 v33, v50, v50
	v_fmac_f32_e32 v34, v48, v48
	v_add_f32_e32 v33, v33, v34
	v_add_f32_e32 v32, v32, v33
	v_mul_f32_e32 v33, v37, v37
	v_mul_f32_e32 v34, v39, v39
	v_fmac_f32_e32 v33, v36, v36
	v_fmac_f32_e32 v34, v38, v38
	v_add_f32_e32 v33, v33, v34
	v_mul_f32_e32 v34, v55, v55
	v_mul_f32_e32 v35, v53, v53
	v_fmac_f32_e32 v34, v54, v54
	v_fmac_f32_e32 v35, v52, v52
	v_add_f32_e32 v34, v34, v35
	v_add_f32_e32 v33, v33, v34
	v_add_f32_e32 v35, v32, v33
	v_cvt_pk_bf16_f32 v40, v44, v45
	v_cvt_pk_bf16_f32 v41, v46, v47
	v_mov_b32_e32 v236, v35
	s_nop 1
	v_permlane16_swap_b32_e32 v35, v236
	v_readlane_b32 s2, v235, 38
	v_readlane_b32 s3, v235, 39
	v_cvt_pk_bf16_f32 v42, v50, v51
	v_cvt_pk_bf16_f32 v43, v48, v49
	s_nop 1
	v_lshl_add_u64 v[32:33], s[2:3], 0, v[98:99]
	v_lshl_add_u64 v[44:45], v[166:167], 1, v[32:33]
	s_waitcnt lgkmcnt(0)
	v_add_f32_e32 v32, v35, v236
	v_mov_b32_e32 v236, v32
	s_nop 1
	v_permlane32_swap_b32_e32 v32, v236
	global_store_dwordx4 v[44:45], v[40:43], off
	v_cvt_pk_bf16_f32 v34, v36, v37
	v_cvt_pk_bf16_f32 v35, v38, v39
	v_cvt_pk_bf16_f32 v36, v54, v55
	v_cvt_pk_bf16_f32 v37, v52, v53
	global_store_dwordx4 v[44:45], v[34:37], off offset:256
	s_and_saveexec_b64 s[2:3], s[4:5]
	s_cbranch_execz .LBB0_838
	v_lshlrev_b64 v[34:35], 6, v[96:97]
	v_lshl_add_u64 v[34:35], s[10:11], 0, v[34:35]
	v_lshl_add_u64 v[34:35], s[8:9], 2, v[34:35]
	s_lshl_b32 s12, s36, 2
	v_lshl_add_u64 v[34:35], v[34:35], 0, s[12:13]
	s_waitcnt lgkmcnt(0)
	v_add_f32_e32 v32, v32, v236
	global_store_dword v[34:35], v32, off
; __device__ __forceinline__ unsigned cvt_pk_bf16(float lo, float hi) { unsigned r; asm volatile("v_cvt_pk_bf16_f32 %0, %1, %2" : "=v"(r) : "v"(lo), "v"(hi)); return r; }
; __device__ __forceinline__ float bf_lo(unsigned w) { return __uint_as_float(w << 16); }
; __device__ __forceinline__ float bf_hi(unsigned w) { return __uint_as_float(w & 0xffff0000u); }
;     __device__ __forceinline__ void operator()(const f32x4 (&acc)[2][2][4][2], const Unit& u, int wr, int wc, int fr, int fq) const {
;     ...
;             for (int mm = 0; mm < RB; ++mm) {
;                 const int m = mh + mm;
;                 const int row = row0 + ai * HALF + m * 16; const size_t off = (size_t)row * D_MODEL + col0; float s = 0.f;
; #pragma unroll
;                 for (int bj = 0; bj < 2; ++bj) {
;                     f32x4 b0, b1;
;                     if (BASE_F32) { b0 = bf[mm][bj][0]; b1 = bf[mm][bj][1]; }
;                     else { const u32x4 w = bb[mm][bj]; b0 = (f32x4){bf_lo(w.x), bf_hi(w.x), bf_lo(w.y), bf_hi(w.y)}; b1 = (f32x4){bf_lo(w.z), bf_hi(w.z), bf_lo(w.w), bf_hi(w.w)}; }
;                     const f32x4 o0 = b0 + acc[ai][bj][m][0] * alpha, o1 = b1 + acc[ai][bj][m][1] * alpha;
;                     if (OUT_F32) { *(f32x4*)(out + off + bj * HALF) = o0; *(f32x4*)(out + off + bj * HALF + 4) = o1; }
;                     else { u32x4 w; w.x = cvt_pk_bf16(o0[0], o0[1]); w.y = cvt_pk_bf16(o0[2], o0[3]); w.z = cvt_pk_bf16(o1[0], o1[1]); w.w = cvt_pk_bf16(o1[2], o1[3]); *(u32x4*)(xb + off + bj * HALF) = w; }
;                     s += ((o0[0] * o0[0] + o0[1] * o0[1]) + (o0[2] * o0[2] + o0[3] * o0[3])) + ((o1[0] * o1[0] + o1[1] * o1[1]) + (o1[2] * o1[2] + o1[3] * o1[3]));
;                 }
;                 if (ssp) { s += __shfl_xor(s, 16); s += __shfl_xor(s, 32); if (fq == 0) ssp[(size_t)row * 16 + u.pn * 4 + wc] = s; }
.LBB0_838:
	s_or_b64 exec, exec, s[2:3]
	s_waitcnt vmcnt(7)
	v_lshlrev_b32_e32 v32, 16, v76
	s_waitcnt lgkmcnt(0)
	v_and_b32_e32 v33, 0xffff0000, v76
	v_lshlrev_b32_e32 v34, 16, v77
	v_and_b32_e32 v35, 0xffff0000, v77
	v_lshlrev_b32_e32 v38, 16, v79
	v_and_b32_e32 v39, 0xffff0000, v79
	v_pk_add_f32 v[30:31], v[30:31], v[34:35]
	v_pk_add_f32 v[28:29], v[28:29], v[32:33]
	v_pk_add_f32 v[32:33], v[26:27], v[38:39]
	s_waitcnt vmcnt(6)
	v_lshlrev_b32_e32 v38, 16, v73
	v_and_b32_e32 v39, 0xffff0000, v73
	v_lshlrev_b32_e32 v40, 16, v74
	v_and_b32_e32 v41, 0xffff0000, v74
	v_lshlrev_b32_e32 v36, 16, v78
	v_and_b32_e32 v37, 0xffff0000, v78
	v_pk_add_f32 v[22:23], v[22:23], v[38:39]
	v_pk_add_f32 v[38:39], v[16:17], v[40:41]
	v_mul_f32_e32 v16, v29, v29
	v_mul_f32_e32 v17, v31, v31
	v_pk_add_f32 v[34:35], v[24:25], v[36:37]
	v_lshlrev_b32_e32 v36, 16, v72
	v_and_b32_e32 v37, 0xffff0000, v72
	v_lshlrev_b32_e32 v42, 16, v75
	v_and_b32_e32 v43, 0xffff0000, v75
	v_fmac_f32_e32 v16, v28, v28
	v_fmac_f32_e32 v17, v30, v30
	v_pk_add_f32 v[20:21], v[20:21], v[36:37]
	v_pk_add_f32 v[36:37], v[18:19], v[42:43]
	v_add_f32_e32 v16, v16, v17
	v_mul_f32_e32 v17, v35, v35
	v_mul_f32_e32 v18, v33, v33
	v_fmac_f32_e32 v17, v34, v34
	v_fmac_f32_e32 v18, v32, v32
	v_add_f32_e32 v17, v17, v18
	v_add_f32_e32 v16, v16, v17
	v_mul_f32_e32 v17, v21, v21
	v_mul_f32_e32 v18, v23, v23
	v_fmac_f32_e32 v17, v20, v20
	v_fmac_f32_e32 v18, v22, v22
	v_add_f32_e32 v17, v17, v18
	v_mul_f32_e32 v18, v39, v39
	v_mul_f32_e32 v19, v37, v37
	v_fmac_f32_e32 v18, v38, v38
	v_fmac_f32_e32 v19, v36, v36
	v_add_f32_e32 v18, v18, v19
	v_add_f32_e32 v17, v17, v18
	v_add_f32_e32 v19, v16, v17
	v_cvt_pk_bf16_f32 v24, v28, v29
	v_cvt_pk_bf16_f32 v25, v30, v31
	v_mov_b32_e32 v236, v19
	s_nop 1
	v_permlane16_swap_b32_e32 v19, v236
	v_readlane_b32 s2, v235, 38
	v_readlane_b32 s3, v235, 39
	v_cvt_pk_bf16_f32 v26, v34, v35
	v_cvt_pk_bf16_f32 v27, v32, v33
	s_nop 1
	v_lshl_add_u64 v[16:17], s[2:3], 0, v[94:95]
	v_lshl_add_u64 v[28:29], v[166:167], 1, v[16:17]
	s_waitcnt lgkmcnt(0)
	v_add_f32_e32 v16, v19, v236
	v_mov_b32_e32 v236, v16
	s_nop 1
	v_permlane32_swap_b32_e32 v16, v236
	global_store_dwordx4 v[28:29], v[24:27], off
	v_cvt_pk_bf16_f32 v18, v20, v21
	v_cvt_pk_bf16_f32 v19, v22, v23
	v_cvt_pk_bf16_f32 v20, v38, v39
	v_cvt_pk_bf16_f32 v21, v36, v37
	global_store_dwordx4 v[28:29], v[18:21], off offset:256
	s_and_saveexec_b64 s[2:3], s[4:5]
	s_cbranch_execz .LBB0_840
	v_lshlrev_b64 v[18:19], 6, v[92:93]
	v_lshl_add_u64 v[18:19], s[10:11], 0, v[18:19]
	v_lshl_add_u64 v[18:19], s[8:9], 2, v[18:19]
	s_lshl_b32 s12, s36, 2
	v_lshl_add_u64 v[18:19], v[18:19], 0, s[12:13]
	s_waitcnt lgkmcnt(0)
	v_add_f32_e32 v16, v16, v236
	global_store_dword v[18:19], v16, off
.LBB0_840:
	s_or_b64 exec, exec, s[2:3]
	s_waitcnt vmcnt(7)
	v_lshlrev_b32_e32 v16, 16, v68
	s_waitcnt lgkmcnt(0)
	v_and_b32_e32 v17, 0xffff0000, v68
	v_lshlrev_b32_e32 v18, 16, v69
	v_and_b32_e32 v19, 0xffff0000, v69
	v_lshlrev_b32_e32 v22, 16, v71
	v_and_b32_e32 v23, 0xffff0000, v71
	v_pk_add_f32 v[14:15], v[14:15], v[18:19]
	v_pk_add_f32 v[12:13], v[12:13], v[16:17]
	v_pk_add_f32 v[16:17], v[10:11], v[22:23]
	s_waitcnt vmcnt(6)
	v_lshlrev_b32_e32 v22, 16, v65
	v_and_b32_e32 v23, 0xffff0000, v65
	v_lshlrev_b32_e32 v24, 16, v66
	v_and_b32_e32 v25, 0xffff0000, v66
	v_lshlrev_b32_e32 v20, 16, v70
	v_and_b32_e32 v21, 0xffff0000, v70
	v_pk_add_f32 v[6:7], v[6:7], v[22:23]
	v_pk_add_f32 v[22:23], v[0:1], v[24:25]
	v_mul_f32_e32 v0, v13, v13
	v_mul_f32_e32 v1, v15, v15
	v_pk_add_f32 v[18:19], v[8:9], v[20:21]
	v_lshlrev_b32_e32 v20, 16, v64
	v_and_b32_e32 v21, 0xffff0000, v64
	v_lshlrev_b32_e32 v26, 16, v67
	v_and_b32_e32 v27, 0xffff0000, v67
	v_fmac_f32_e32 v0, v12, v12
	v_fmac_f32_e32 v1, v14, v14
	v_pk_add_f32 v[4:5], v[4:5], v[20:21]
	v_pk_add_f32 v[20:21], v[2:3], v[26:27]
	v_add_f32_e32 v0, v0, v1
	v_mul_f32_e32 v1, v19, v19
	v_mul_f32_e32 v2, v17, v17
	v_fmac_f32_e32 v1, v18, v18
	v_fmac_f32_e32 v2, v16, v16
	v_add_f32_e32 v1, v1, v2
	v_add_f32_e32 v0, v0, v1
	v_mul_f32_e32 v1, v5, v5
	v_mul_f32_e32 v2, v7, v7
	v_fmac_f32_e32 v1, v4, v4
	v_fmac_f32_e32 v2, v6, v6
	v_add_f32_e32 v1, v1, v2
	v_mul_f32_e32 v2, v23, v23
	v_mul_f32_e32 v3, v21, v21
	v_fmac_f32_e32 v2, v22, v22
	v_fmac_f32_e32 v3, v20, v20
	v_add_f32_e32 v2, v2, v3
	v_add_f32_e32 v1, v1, v2
	v_add_f32_e32 v3, v0, v1
	v_cvt_pk_bf16_f32 v8, v12, v13
	v_cvt_pk_bf16_f32 v9, v14, v15
	v_mov_b32_e32 v236, v3
	s_nop 1
	v_permlane16_swap_b32_e32 v3, v236
	v_readlane_b32 s2, v235, 38
	v_readlane_b32 s3, v235, 39
	v_cvt_pk_bf16_f32 v10, v18, v19
	v_cvt_pk_bf16_f32 v11, v16, v17
	s_nop 1
	v_lshl_add_u64 v[0:1], s[2:3], 0, v[90:91]
	v_lshl_add_u64 v[12:13], v[166:167], 1, v[0:1]
	s_waitcnt lgkmcnt(0)
	v_add_f32_e32 v0, v3, v236
	v_mov_b32_e32 v236, v0
	s_nop 1
	v_permlane32_swap_b32_e32 v0, v236
	global_store_dwordx4 v[12:13], v[8:11], off
	v_cvt_pk_bf16_f32 v2, v4, v5
	v_cvt_pk_bf16_f32 v3, v6, v7
	v_cvt_pk_bf16_f32 v4, v22, v23
	v_cvt_pk_bf16_f32 v5, v20, v21
	global_store_dwordx4 v[12:13], v[2:5], off offset:256
	s_and_saveexec_b64 s[2:3], s[4:5]
	s_cbranch_execz .LBB0_842
	v_lshlrev_b64 v[2:3], 6, v[88:89]
	v_lshl_add_u64 v[2:3], s[10:11], 0, v[2:3]
	v_lshl_add_u64 v[2:3], s[8:9], 2, v[2:3]
	s_lshl_b32 s12, s36, 2
	v_lshl_add_u64 v[2:3], v[2:3], 0, s[12:13]
	s_waitcnt lgkmcnt(0)
	v_add_f32_e32 v0, v0, v236
	global_store_dword v[2:3], v0, off

; template <int NP> __device__ __forceinline__ void load_rs(const float* ssp, int row0, int fq, float (&rs)[2][4]) {
;     ...
;             for (int m = 0; m < 4; ++m) p[ai][m] = *(const f32x4*)(ssp + (size_t)(row0 + ai * HALF + m * 16) * 16 + 4 * fq);
; #pragma unroll
;         for (int ai = 0; ai < 2; ++ai)
; #pragma unroll
;             for (int m = 0; m < 4; ++m) { float s = (p[ai][m][0] + p[ai][m][1]) + (p[ai][m][2] + p[ai][m][3]); s += __shfl_xor(s, 16); s += __shfl_xor(s, 32); rs[ai][m] = s; }
;     __device__ __forceinline__ void operator()(const f32x4 (&acc)[2][2][4][2], const Unit& u, int wr, int wc, int fr, int fq) const {
;     ...
;                     const f32x4 ga = acc[ai][0][m][q >> 1], ua = acc[ai][1][m][q >> 1]; const int e0 = 2 * (q & 1);
;                     const f32x2 g = (f32x2){ga[e0], ga[e0 + 1]}, up = (f32x2){ua[e0], ua[e0 + 1]};
;                     const f32x2 t = g * nrl; f32x2 ex; ex.x = __builtin_amdgcn_exp2f(t.x); ex.y = __builtin_amdgcn_exp2f(t.y);
;                     const f32x2 d = ex + 1.0f; f32x2 rc; rc.x = __builtin_amdgcn_rcpf(d.x); rc.y = __builtin_amdgcn_rcpf(d.y);
;                     const f32x2 o = (g * up) * (rc * r2);
.LBB0_932:
	s_mov_b32 s98, 0xffff0000
	s_mov_b32 s99, 0xffff0000
	s_mov_b32 s100, 0
	s_mov_b32 s101, -1
	s_lshl_b32 s2, s41, 8
	s_add_i32 s2, s2, s29
	v_or_b32_e32 v146, s2, v150
	v_ashrrev_i32_e32 v147, 31, v146
	v_or_b32_e32 v160, 16, v146
	v_lshlrev_b64 v[148:149], 6, v[146:147]
	v_ashrrev_i32_e32 v161, 31, v160
	v_or_b32_e32 v168, 32, v146
	v_or_b32_e32 v170, 48, v146
	v_add_u32_e32 v146, 0x80, v146
	v_lshlrev_b64 v[160:161], 6, v[160:161]
	v_ashrrev_i32_e32 v169, 31, v168
	v_ashrrev_i32_e32 v171, 31, v170
	v_ashrrev_i32_e32 v147, 31, v146
	v_lshl_add_u64 v[148:149], v[138:139], 0, v[148:149]
	v_lshl_add_u64 v[164:165], v[138:139], 0, v[160:161]
	v_lshlrev_b64 v[168:169], 6, v[168:169]
	v_lshlrev_b64 v[170:171], 6, v[170:171]
	v_lshlrev_b64 v[176:177], 6, v[146:147]
	global_load_dwordx4 v[160:163], v[148:149], off
	s_nop 0
	global_load_dwordx4 v[164:167], v[164:165], off
	v_lshl_add_u64 v[168:169], v[138:139], 0, v[168:169]
	v_lshl_add_u64 v[172:173], v[138:139], 0, v[170:171]
	v_lshl_add_u64 v[176:177], v[138:139], 0, v[176:177]
	global_load_dwordx4 v[168:171], v[168:169], off
	s_nop 0
	global_load_dwordx4 v[172:175], v[172:173], off
	v_add_co_u32_e32 v148, vcc, s26, v148
	global_load_dwordx4 v[176:179], v[176:177], off
	s_nop 0
	v_addc_co_u32_e32 v149, vcc, 0, v149, vcc
	global_load_dwordx4 v[180:183], v[148:149], off offset:1024
	global_load_dwordx4 v[184:187], v[148:149], off offset:2048
	global_load_dwordx4 v[190:193], v[148:149], off offset:3072
	v_and_b32_e32 v147, 64, v156
	v_add_u32_e32 v147, 64, v147
	v_pk_mul_f32 v[120:121], v[124:125], v[120:121]
	v_pk_mul_f32 v[122:123], v[126:127], v[122:123]
	v_pk_mul_f32 v[112:113], v[116:117], v[112:113]
	v_pk_mul_f32 v[114:115], v[118:119], v[114:115]
	v_pk_mul_f32 v[104:105], v[108:109], v[104:105]
	s_ashr_i32 s3, s2, 13
	s_mul_hi_i32 s11, s3, 0x4400000
	s_mul_i32 s3, s3, 0x4400000
	v_readlane_b32 s16, v235, 44
	v_lshl_or_b32 v148, s42, 7, v152
	v_readlane_b32 s17, v235, 45
	v_pk_mul_f32 v[106:107], v[110:111], v[106:107]
	v_pk_mul_f32 v[96:97], v[100:101], v[96:97]
	v_pk_mul_f32 v[98:99], v[102:103], v[98:99]
	v_pk_mul_f32 v[88:89], v[92:93], v[88:89]
	v_pk_mul_f32 v[90:91], v[94:95], v[90:91]
	v_pk_mul_f32 v[80:81], v[84:85], v[80:81]
	v_pk_mul_f32 v[82:83], v[86:87], v[82:83]
	v_pk_mul_f32 v[72:73], v[76:77], v[72:73]
	v_pk_mul_f32 v[74:75], v[78:79], v[74:75]
	v_pk_mul_f32 v[64:65], v[68:69], v[64:65]
	v_pk_mul_f32 v[66:67], v[70:71], v[66:67]
	v_pk_mul_f32 v[56:57], v[60:61], v[56:57]
	v_pk_mul_f32 v[58:59], v[62:63], v[58:59]
	v_pk_mul_f32 v[48:49], v[52:53], v[48:49]
	v_pk_mul_f32 v[50:51], v[54:55], v[50:51]
	v_pk_mul_f32 v[40:41], v[44:45], v[40:41]
	v_pk_mul_f32 v[42:43], v[46:47], v[42:43]
	v_pk_mul_f32 v[32:33], v[36:37], v[32:33]
	v_pk_mul_f32 v[34:35], v[38:39], v[34:35]
	v_pk_mul_f32 v[24:25], v[28:29], v[24:25]
	v_pk_mul_f32 v[26:27], v[30:31], v[26:27]
	v_pk_mul_f32 v[16:17], v[20:21], v[16:17]
	v_pk_mul_f32 v[18:19], v[22:23], v[18:19]
	v_pk_mul_f32 v[8:9], v[12:13], v[8:9]
	v_pk_mul_f32 v[10:11], v[14:15], v[10:11]
	v_pk_mul_f32 v[0:1], v[4:5], v[0:1]
	v_pk_mul_f32 v[2:3], v[6:7], v[2:3]
	s_waitcnt vmcnt(0)
	v_mov_b32_e32 v194, v161
	v_mov_b32_e32 v195, v162
	v_mov_b32_e32 v161, v163
	v_pk_add_f32 v[160:161], v[194:195], v[160:161]
	v_mov_b32_e32 v162, v165
	v_mov_b32_e32 v163, v166
	v_mov_b32_e32 v165, v167
	v_mov_b32_e32 v166, v169
	v_mov_b32_e32 v167, v170
	v_mov_b32_e32 v169, v171
	v_mov_b32_e32 v170, v173
	v_mov_b32_e32 v171, v174
	v_mov_b32_e32 v173, v175
	v_mov_b32_e32 v174, v177
	v_mov_b32_e32 v175, v178
	v_mov_b32_e32 v177, v179
	v_add_f32_e32 v149, v160, v161
	v_pk_add_f32 v[160:161], v[162:163], v[164:165]
	v_pk_add_f32 v[162:163], v[166:167], v[168:169]
	v_pk_add_f32 v[166:167], v[174:175], v[176:177]
	v_add_f32_e32 v160, v160, v161
	v_add_f32_e32 v161, v162, v163
	v_mov_b32_e32 v236, v149
	s_nop 1
	v_permlane16_swap_b32_e32 v149, v236
	v_add_f32_e32 v163, v166, v167
	v_mov_b32_e32 v237, v160
	s_nop 1
	v_permlane16_swap_b32_e32 v160, v237
	v_mov_b32_e32 v238, v161
	s_nop 1
	v_permlane16_swap_b32_e32 v161, v238
	v_mov_b32_e32 v178, v181
	s_waitcnt lgkmcnt(2)
	v_add_f32_e32 v149, v149, v236
	v_mov_b32_e32 v236, v149
	s_nop 1
	v_permlane32_swap_b32_e32 v149, v236
	s_waitcnt lgkmcnt(2)
	v_add_f32_e32 v160, v160, v237
	s_waitcnt lgkmcnt(1)
	v_add_f32_e32 v161, v161, v238
	v_mov_b32_e32 v237, v160
	s_nop 1
	v_permlane32_swap_b32_e32 v160, v237
	v_mov_b32_e32 v238, v161
	s_nop 1
	v_permlane32_swap_b32_e32 v161, v238
	v_mov_b32_e32 v179, v182
	v_mov_b32_e32 v181, v183
	v_mov_b32_e32 v182, v185
	v_mov_b32_e32 v183, v186
	v_mov_b32_e32 v185, v187
	v_mov_b32_e32 v186, v191
	v_mov_b32_e32 v187, v192
	v_mov_b32_e32 v191, v193
	v_pk_add_f32 v[164:165], v[170:171], v[172:173]
	v_pk_add_f32 v[168:169], v[178:179], v[180:181]
	v_pk_add_f32 v[170:171], v[182:183], v[184:185]
	s_waitcnt lgkmcnt(2)
	v_add_f32_e32 v149, v149, v236
	s_waitcnt lgkmcnt(1)
	v_add_f32_e32 v159, v160, v237
	s_waitcnt lgkmcnt(0)
	v_add_f32_e32 v166, v161, v238
	v_pk_add_f32 v[160:161], v[186:187], v[190:191]
	v_add_f32_e32 v162, v164, v165
	v_add_f32_e32 v164, v168, v169
	v_add_f32_e32 v165, v170, v171
	v_add_f32_e32 v160, v160, v161
	v_mov_b32_e32 v236, v162
	s_nop 1
	v_permlane16_swap_b32_e32 v162, v236
	v_mov_b32_e32 v237, v163
	s_nop 1
	v_permlane16_swap_b32_e32 v163, v237
	v_mov_b32_e32 v238, v164
	s_nop 1
	v_permlane16_swap_b32_e32 v164, v238
	v_mov_b32_e32 v239, v165
	s_nop 1
	v_permlane16_swap_b32_e32 v165, v239
	v_mov_b32_e32 v240, v160
	s_nop 1
	v_permlane16_swap_b32_e32 v160, v240
	s_waitcnt lgkmcnt(4)
	v_add_f32_e32 v162, v162, v236
	s_waitcnt lgkmcnt(3)
; __device__ __forceinline__ unsigned cvt_pk_bf16(float lo, float hi) { unsigned r; asm volatile("v_cvt_pk_bf16_f32 %0, %1, %2" : "=v"(r) : "v"(lo), "v"(hi)); return r; }
; template <int NP> __device__ __forceinline__ void load_rs(const float* ssp, int row0, int fq, float (&rs)[2][4]) {
;     ...
;             for (int m = 0; m < 4; ++m) { float s = (p[ai][m][0] + p[ai][m][1]) + (p[ai][m][2] + p[ai][m][3]); s += __shfl_xor(s, 16); s += __shfl_xor(s, 32); rs[ai][m] = s; }
;     }
; #pragma unroll
;     for (int ai = 0; ai < 2; ++ai)
; #pragma unroll
;         for (int m = 0; m < 4; ++m) rs[ai][m] = __builtin_amdgcn_rsqf(rs[ai][m] * (1.0f / D_MODEL) + RMS_EPS);
;     __device__ __forceinline__ void operator()(const f32x4 (&acc)[2][2][4][2], const Unit& u, int wr, int wc, int fr, int fq) const {
;     ...
;                 const int row = row0 + ai * HALF + m * 16; const float r = rs[ai][m];
;                 const float nrl = r * -1.44269504089f, r2 = r * r;
;                 unsigned pk[4];
; #pragma unroll
;                 for (int q = 0; q < 4; ++q) {
;                     const f32x4 ga = acc[ai][0][m][q >> 1], ua = acc[ai][1][m][q >> 1]; const int e0 = 2 * (q & 1);
;                     const f32x2 g = (f32x2){ga[e0], ga[e0 + 1]}, up = (f32x2){ua[e0], ua[e0 + 1]};
;                     const f32x2 t = g * nrl; f32x2 ex; ex.x = __builtin_amdgcn_exp2f(t.x); ex.y = __builtin_amdgcn_exp2f(t.y);
;                     const f32x2 d = ex + 1.0f; f32x2 rc; rc.x = __builtin_amdgcn_rcpf(d.x); rc.y = __builtin_amdgcn_rcpf(d.y);
;                     const f32x2 o = (g * up) * (rc * r2);
;                     pk[q] = cvt_pk_bf16(o.x, o.y);
;                 }
;                 u32x4 w; w.x = pk[0]; w.y = pk[1]; w.z = pk[2]; w.w = pk[3];
;                 *(u32x4*)(U + (size_t)(row >> 13) * U_SLAB + (size_t)(row & (SEQ - 1)) * U_PITCH + col0) = w;
	v_add_f32_e32 v163, v163, v237
	s_waitcnt lgkmcnt(2)
	v_add_f32_e32 v161, v164, v238
	s_waitcnt lgkmcnt(1)
	v_add_f32_e32 v165, v165, v239
	s_waitcnt lgkmcnt(0)
	v_add_f32_e32 v136, v160, v240
	v_mov_b32_e32 v236, v162
	s_nop 1
	v_permlane32_swap_b32_e32 v162, v236
	v_mov_b32_e32 v237, v163
	s_nop 1
	v_permlane32_swap_b32_e32 v163, v237
	v_mov_b32_e32 v238, v161
	s_nop 1
	v_permlane32_swap_b32_e32 v161, v238
	v_mov_b32_e32 v239, v165
	s_nop 1
	v_permlane32_swap_b32_e32 v165, v239
	v_mov_b32_e32 v240, v136
	s_nop 1
	v_permlane32_swap_b32_e32 v136, v240
	s_waitcnt lgkmcnt(4)
	v_add_f32_e32 v160, v162, v236
	s_waitcnt lgkmcnt(3)
	v_add_f32_e32 v162, v163, v237
	s_waitcnt lgkmcnt(2)
	v_add_f32_e32 v161, v161, v238
	s_waitcnt lgkmcnt(1)
	v_add_f32_e32 v163, v165, v239
	s_waitcnt lgkmcnt(0)
	v_add_f32_e32 v136, v136, v240
	v_fmamk_f32 v147, v149, 0x3a800000, v157
	v_rsq_f32_e32 v164, v147
	v_fmamk_f32 v147, v159, 0x3a800000, v157
	v_rsq_f32_e32 v165, v147
	v_fmamk_f32 v147, v166, 0x3a800000, v157
	v_rsq_f32_e32 v166, v147
	v_fmamk_f32 v147, v160, 0x3a800000, v157
	v_rsq_f32_e32 v167, v147
	v_fmamk_f32 v147, v162, 0x3a800000, v157
	v_rsq_f32_e32 v168, v147
	v_fmamk_f32 v147, v161, 0x3a800000, v157
	v_rsq_f32_e32 v160, v147
	v_fmamk_f32 v147, v163, 0x3a800000, v157
	v_fmamk_f32 v136, v136, 0x3a800000, v157
	v_rsq_f32_e32 v159, v147
	v_rsq_f32_e32 v147, v136
	v_mul_f32_e32 v136, 0xbfb8aa3b, v164
	v_pk_mul_f32 v[162:163], v[124:125], v[136:137] op_sel_hi:[1,0]
	v_pk_mul_f32 v[124:125], v[126:127], v[136:137] op_sel_hi:[1,0]
	v_exp_f32_e32 v162, v162
	v_exp_f32_e32 v163, v163
	v_exp_f32_e32 v124, v124
	v_exp_f32_e32 v125, v125
	v_mul_f32_e32 v164, v164, v164
	v_pk_add_f32 v[162:163], v[162:163], 1.0 op_sel_hi:[1,0]
	v_bitop3_b32 v161, s2, v158, v150 bitop3:0xc8
	v_rcp_f32_e32 v162, v162
	v_rcp_f32_e32 v163, v163
	v_pk_add_f32 v[124:125], v[124:125], 1.0 op_sel_hi:[1,0]
	s_add_u32 s2, s16, s3
	v_rcp_f32_e32 v124, v124
	v_rcp_f32_e32 v125, v125
	v_pk_mul_f32 v[126:127], v[164:165], v[162:163] op_sel_hi:[0,1]
	v_pk_mul_f32 v[120:121], v[120:121], v[126:127]
	v_pk_mul_f32 v[126:127], v[116:117], v[136:137] op_sel_hi:[1,0]
	v_pk_mul_f32 v[124:125], v[164:165], v[124:125] op_sel_hi:[0,1]
	v_exp_f32_e32 v126, v126
	v_exp_f32_e32 v127, v127
	v_pk_mul_f32 v[122:123], v[122:123], v[124:125]
	v_pk_mul_f32 v[124:125], v[118:119], v[136:137] op_sel_hi:[1,0]
	v_cvt_pk_bf16_f32 v120, v120, v121
	v_cvt_pk_bf16_f32 v121, v122, v123
	v_pk_add_f32 v[122:123], v[126:127], 1.0 op_sel_hi:[1,0]
	v_exp_f32_e32 v124, v124
	v_exp_f32_e32 v125, v125
	v_rcp_f32_e32 v122, v122
	v_rcp_f32_e32 v123, v123
	v_ashrrev_i32_e32 v149, 31, v148
	v_pk_add_f32 v[116:117], v[124:125], 1.0 op_sel_hi:[1,0]
	s_addc_u32 s3, s17, s11
	v_rcp_f32_e32 v116, v116
	v_rcp_f32_e32 v117, v117
	v_pk_mul_f32 v[118:119], v[164:165], v[122:123] op_sel_hi:[0,1]
	v_pk_mul_f32 v[112:113], v[112:113], v[118:119]
	s_nop 0
	v_cvt_pk_bf16_f32 v122, v112, v113
	v_pk_mul_f32 v[112:113], v[164:165], v[116:117] op_sel_hi:[0,1]
	v_mul_f32_e32 v116, 0xbfb8aa3b, v165
	v_pk_mul_f32 v[118:119], v[108:109], v[116:117] op_sel_hi:[1,0]
	v_pk_mul_f32 v[108:109], v[110:111], v[116:117] op_sel_hi:[1,0]
	v_exp_f32_e32 v118, v118
	v_exp_f32_e32 v119, v119
	v_exp_f32_e32 v108, v108
	v_exp_f32_e32 v109, v109
	v_pk_mul_f32 v[112:113], v[114:115], v[112:113]
	v_pk_add_f32 v[118:119], v[118:119], 1.0 op_sel_hi:[1,0]
	v_cvt_pk_bf16_f32 v123, v112, v113
	v_mul_u32_u24_e32 v112, 0xb40, v161
	v_lshlrev_b32_e32 v136, 1, v112
	v_rcp_f32_e32 v118, v118
	v_rcp_f32_e32 v119, v119
	v_lshl_add_u64 v[114:115], s[2:3], 0, v[136:137]
	v_lshlrev_b64 v[112:113], 1, v[148:149]
	v_pk_add_f32 v[108:109], v[108:109], 1.0 op_sel_hi:[1,0]
	v_lshl_add_u64 v[114:115], v[114:115], 0, v[112:113]
	v_rcp_f32_e32 v108, v108
	v_rcp_f32_e32 v109, v109
	global_store_dwordx4 v[114:115], v[120:123], off
	s_nop 1
	v_mul_f32_e32 v120, v165, v165
	v_pk_mul_f32 v[110:111], v[120:121], v[118:119] op_sel_hi:[0,1]
	v_pk_mul_f32 v[104:105], v[104:105], v[110:111]
	v_pk_mul_f32 v[110:111], v[100:101], v[116:117] op_sel_hi:[1,0]
	v_pk_mul_f32 v[108:109], v[120:121], v[108:109] op_sel_hi:[0,1]
	v_exp_f32_e32 v110, v110
	v_exp_f32_e32 v111, v111
	v_pk_mul_f32 v[106:107], v[106:107], v[108:109]
	v_pk_mul_f32 v[108:109], v[102:103], v[116:117] op_sel_hi:[1,0]
	v_cvt_pk_bf16_f32 v104, v104, v105
	v_cvt_pk_bf16_f32 v105, v106, v107
	v_pk_add_f32 v[106:107], v[110:111], 1.0 op_sel_hi:[1,0]
	v_exp_f32_e32 v108, v108
	v_exp_f32_e32 v109, v109
	v_rcp_f32_e32 v106, v106
	v_rcp_f32_e32 v107, v107
	v_pk_add_f32 v[100:101], v[108:109], 1.0 op_sel_hi:[1,0]
	s_nop 0
	v_rcp_f32_e32 v100, v100
	v_rcp_f32_e32 v101, v101
	v_pk_mul_f32 v[102:103], v[120:121], v[106:107] op_sel_hi:[0,1]
	v_pk_mul_f32 v[96:97], v[96:97], v[102:103]
	s_nop 0
	v_cvt_pk_bf16_f32 v106, v96, v97
	v_pk_mul_f32 v[96:97], v[120:121], v[100:101] op_sel_hi:[0,1]
	v_pk_mul_f32 v[96:97], v[98:99], v[96:97]
	v_add_co_u32_e32 v100, vcc, s28, v114
	v_cvt_pk_bf16_f32 v107, v96, v97
	v_mul_f32_e32 v96, 0xbfb8aa3b, v166
	v_pk_mul_f32 v[98:99], v[92:93], v[96:97] op_sel_hi:[1,0]
	v_pk_mul_f32 v[92:93], v[94:95], v[96:97] op_sel_hi:[1,0]
	v_exp_f32_e32 v98, v98
	v_exp_f32_e32 v99, v99
	v_exp_f32_e32 v92, v92
	v_exp_f32_e32 v93, v93
	v_addc_co_u32_e32 v101, vcc, 0, v115, vcc
	v_pk_add_f32 v[98:99], v[98:99], 1.0 op_sel_hi:[1,0]
	v_pk_add_f32 v[92:93], v[92:93], 1.0 op_sel_hi:[1,0]
	v_rcp_f32_e32 v98, v98
	v_rcp_f32_e32 v99, v99
	v_rcp_f32_e32 v92, v92
	v_rcp_f32_e32 v93, v93
	global_store_dwordx4 v[100:101], v[104:107], off offset:2048
	v_mul_f32_e32 v100, v166, v166
	v_pk_mul_f32 v[94:95], v[100:101], v[98:99] op_sel_hi:[0,1]
; __device__ __forceinline__ unsigned cvt_pk_bf16(float lo, float hi) { unsigned r; asm volatile("v_cvt_pk_bf16_f32 %0, %1, %2" : "=v"(r) : "v"(lo), "v"(hi)); return r; }
;     __device__ __forceinline__ void operator()(const f32x4 (&acc)[2][2][4][2], const Unit& u, int wr, int wc, int fr, int fq) const {
;     ...
;                 const int row = row0 + ai * HALF + m * 16; const float r = rs[ai][m];
;                 const float nrl = r * -1.44269504089f, r2 = r * r;
;                 unsigned pk[4];
; #pragma unroll
;                 for (int q = 0; q < 4; ++q) {
;                     const f32x4 ga = acc[ai][0][m][q >> 1], ua = acc[ai][1][m][q >> 1]; const int e0 = 2 * (q & 1);
;                     const f32x2 g = (f32x2){ga[e0], ga[e0 + 1]}, up = (f32x2){ua[e0], ua[e0 + 1]};
;                     const f32x2 t = g * nrl; f32x2 ex; ex.x = __builtin_amdgcn_exp2f(t.x); ex.y = __builtin_amdgcn_exp2f(t.y);
;                     const f32x2 d = ex + 1.0f; f32x2 rc; rc.x = __builtin_amdgcn_rcpf(d.x); rc.y = __builtin_amdgcn_rcpf(d.y);
;                     const f32x2 o = (g * up) * (rc * r2);
;                     pk[q] = cvt_pk_bf16(o.x, o.y);
;                 }
;                 u32x4 w; w.x = pk[0]; w.y = pk[1]; w.z = pk[2]; w.w = pk[3];
;                 *(u32x4*)(U + (size_t)(row >> 13) * U_SLAB + (size_t)(row & (SEQ - 1)) * U_PITCH + col0) = w;
	v_pk_mul_f32 v[88:89], v[88:89], v[94:95]
	v_pk_mul_f32 v[94:95], v[84:85], v[96:97] op_sel_hi:[1,0]
	v_pk_mul_f32 v[92:93], v[100:101], v[92:93] op_sel_hi:[0,1]
	v_exp_f32_e32 v94, v94
	v_exp_f32_e32 v95, v95
	v_pk_mul_f32 v[90:91], v[90:91], v[92:93]
	v_pk_mul_f32 v[92:93], v[86:87], v[96:97] op_sel_hi:[1,0]
	v_cvt_pk_bf16_f32 v88, v88, v89
	v_cvt_pk_bf16_f32 v89, v90, v91
	v_pk_add_f32 v[90:91], v[94:95], 1.0 op_sel_hi:[1,0]
	v_exp_f32_e32 v92, v92
	v_exp_f32_e32 v93, v93
	v_rcp_f32_e32 v90, v90
	v_rcp_f32_e32 v91, v91
	v_pk_add_f32 v[84:85], v[92:93], 1.0 op_sel_hi:[1,0]
	s_nop 0
	v_rcp_f32_e32 v84, v84
	v_rcp_f32_e32 v85, v85
	v_pk_mul_f32 v[86:87], v[100:101], v[90:91] op_sel_hi:[0,1]
	v_pk_mul_f32 v[80:81], v[80:81], v[86:87]
	s_nop 0
	v_cvt_pk_bf16_f32 v90, v80, v81
	v_pk_mul_f32 v[80:81], v[100:101], v[84:85] op_sel_hi:[0,1]
	v_pk_mul_f32 v[80:81], v[82:83], v[80:81]
	v_add_co_u32_e32 v84, vcc, s38, v114
	v_cvt_pk_bf16_f32 v91, v80, v81
	v_mul_f32_e32 v80, 0xbfb8aa3b, v167
	v_pk_mul_f32 v[82:83], v[76:77], v[80:81] op_sel_hi:[1,0]
	v_pk_mul_f32 v[76:77], v[78:79], v[80:81] op_sel_hi:[1,0]
	v_exp_f32_e32 v82, v82
	v_exp_f32_e32 v83, v83
	v_exp_f32_e32 v76, v76
	v_exp_f32_e32 v77, v77
	v_addc_co_u32_e32 v85, vcc, 0, v115, vcc
	v_pk_add_f32 v[82:83], v[82:83], 1.0 op_sel_hi:[1,0]
	v_pk_add_f32 v[76:77], v[76:77], 1.0 op_sel_hi:[1,0]
	v_rcp_f32_e32 v82, v82
	v_rcp_f32_e32 v83, v83
	v_rcp_f32_e32 v76, v76
	v_rcp_f32_e32 v77, v77
	global_store_dwordx4 v[84:85], v[88:91], off
	v_mul_f32_e32 v84, v167, v167
	v_pk_mul_f32 v[78:79], v[84:85], v[82:83] op_sel_hi:[0,1]
	v_pk_mul_f32 v[72:73], v[72:73], v[78:79]
	v_pk_mul_f32 v[78:79], v[68:69], v[80:81] op_sel_hi:[1,0]
	v_pk_mul_f32 v[76:77], v[84:85], v[76:77] op_sel_hi:[0,1]
	v_exp_f32_e32 v78, v78
	v_exp_f32_e32 v79, v79
	v_pk_mul_f32 v[74:75], v[74:75], v[76:77]
	v_pk_mul_f32 v[76:77], v[70:71], v[80:81] op_sel_hi:[1,0]
	v_cvt_pk_bf16_f32 v72, v72, v73
	v_cvt_pk_bf16_f32 v73, v74, v75
	v_pk_add_f32 v[74:75], v[78:79], 1.0 op_sel_hi:[1,0]
	v_exp_f32_e32 v76, v76
	v_exp_f32_e32 v77, v77
	v_rcp_f32_e32 v74, v74
	v_rcp_f32_e32 v75, v75
	v_pk_add_f32 v[68:69], v[76:77], 1.0 op_sel_hi:[1,0]
	s_nop 0
	v_rcp_f32_e32 v68, v68
	v_rcp_f32_e32 v69, v69
	v_pk_mul_f32 v[70:71], v[84:85], v[74:75] op_sel_hi:[0,1]
	v_pk_mul_f32 v[64:65], v[64:65], v[70:71]
	s_nop 0
	v_cvt_pk_bf16_f32 v74, v64, v65
	v_pk_mul_f32 v[64:65], v[84:85], v[68:69] op_sel_hi:[0,1]
	v_pk_mul_f32 v[64:65], v[66:67], v[64:65]
	v_and_b32_e32 v69, 0x1fcf, v146
	v_cvt_pk_bf16_f32 v75, v64, v65
	v_add_co_u32_e32 v64, vcc, s39, v114
	v_mul_f32_e32 v68, v168, v168
	s_nop 0
	v_addc_co_u32_e32 v65, vcc, 0, v115, vcc
	global_store_dwordx4 v[64:65], v[72:75], off offset:2048
	v_mul_f32_e32 v64, 0xbfb8aa3b, v168
	v_pk_mul_f32 v[66:67], v[60:61], v[64:65] op_sel_hi:[1,0]
	v_ashrrev_i32_e32 v65, 13, v146
	v_exp_f32_e32 v66, v66
	v_exp_f32_e32 v67, v67
	v_pk_mul_f32 v[60:61], v[62:63], v[64:65] op_sel_hi:[1,0]
	v_pk_add_f32 v[66:67], v[66:67], 1.0 op_sel_hi:[1,0]
	v_exp_f32_e32 v60, v60
	v_exp_f32_e32 v61, v61
	v_rcp_f32_e32 v66, v66
	v_rcp_f32_e32 v67, v67
	v_pk_add_f32 v[60:61], v[60:61], 1.0 op_sel_hi:[1,0]
	s_nop 0
	v_rcp_f32_e32 v60, v60
	v_rcp_f32_e32 v61, v61
	v_pk_mul_f32 v[62:63], v[68:69], v[66:67] op_sel_hi:[0,1]
	v_pk_mul_f32 v[56:57], v[56:57], v[62:63]
	v_pk_mul_f32 v[62:63], v[52:53], v[64:65] op_sel_hi:[1,0]
	v_pk_mul_f32 v[60:61], v[68:69], v[60:61] op_sel_hi:[0,1]
	v_exp_f32_e32 v62, v62
	v_exp_f32_e32 v63, v63
	v_pk_mul_f32 v[58:59], v[58:59], v[60:61]
	v_pk_mul_f32 v[60:61], v[54:55], v[64:65] op_sel_hi:[1,0]
	v_cvt_pk_bf16_f32 v56, v56, v57
	v_cvt_pk_bf16_f32 v57, v58, v59
	v_pk_add_f32 v[58:59], v[62:63], 1.0 op_sel_hi:[1,0]
	v_exp_f32_e32 v60, v60
	v_exp_f32_e32 v61, v61
	v_rcp_f32_e32 v58, v58
	v_rcp_f32_e32 v59, v59
	v_pk_add_f32 v[52:53], v[60:61], 1.0 op_sel_hi:[1,0]
	s_nop 0
	v_rcp_f32_e32 v52, v52
	v_rcp_f32_e32 v53, v53
	v_pk_mul_f32 v[54:55], v[68:69], v[58:59] op_sel_hi:[0,1]
	v_pk_mul_f32 v[48:49], v[48:49], v[54:55]
	v_mul_f32_e32 v54, v160, v160
	v_cvt_pk_bf16_f32 v58, v48, v49
	v_pk_mul_f32 v[48:49], v[68:69], v[52:53] op_sel_hi:[0,1]
	v_pk_mul_f32 v[48:49], v[50:51], v[48:49]
	v_mul_u32_u24_e32 v50, 0xb40, v69
	v_lshlrev_b32_e32 v136, 1, v50
	v_mul_f32_e32 v50, 0xbfb8aa3b, v160
	v_pk_mul_f32 v[52:53], v[44:45], v[50:51] op_sel_hi:[1,0]
	v_pk_mul_f32 v[44:45], v[46:47], v[50:51] op_sel_hi:[1,0]
	v_exp_f32_e32 v52, v52
	v_exp_f32_e32 v53, v53
	v_exp_f32_e32 v44, v44
	v_exp_f32_e32 v45, v45
	v_cvt_pk_bf16_f32 v59, v48, v49
	v_pk_add_f32 v[52:53], v[52:53], 1.0 op_sel_hi:[1,0]
	v_mov_b64_e32 v[48:49], s[16:17]
	v_rcp_f32_e32 v52, v52
	v_rcp_f32_e32 v53, v53
	v_pk_add_f32 v[44:45], v[44:45], 1.0 op_sel_hi:[1,0]
; __device__ __forceinline__ unsigned cvt_pk_bf16(float lo, float hi) { unsigned r; asm volatile("v_cvt_pk_bf16_f32 %0, %1, %2" : "=v"(r) : "v"(lo), "v"(hi)); return r; }
;     __device__ __forceinline__ void operator()(const f32x4 (&acc)[2][2][4][2], const Unit& u, int wr, int wc, int fr, int fq) const {
;     ...
;                 const int row = row0 + ai * HALF + m * 16; const float r = rs[ai][m];
;                 const float nrl = r * -1.44269504089f, r2 = r * r;
;                 unsigned pk[4];
; #pragma unroll
;                 for (int q = 0; q < 4; ++q) {
;                     const f32x4 ga = acc[ai][0][m][q >> 1], ua = acc[ai][1][m][q >> 1]; const int e0 = 2 * (q & 1);
;                     const f32x2 g = (f32x2){ga[e0], ga[e0 + 1]}, up = (f32x2){ua[e0], ua[e0 + 1]};
;                     const f32x2 t = g * nrl; f32x2 ex; ex.x = __builtin_amdgcn_exp2f(t.x); ex.y = __builtin_amdgcn_exp2f(t.y);
;                     const f32x2 d = ex + 1.0f; f32x2 rc; rc.x = __builtin_amdgcn_rcpf(d.x); rc.y = __builtin_amdgcn_rcpf(d.y);
;                     const f32x2 o = (g * up) * (rc * r2);
;                     pk[q] = cvt_pk_bf16(o.x, o.y);
;                 }
;                 u32x4 w; w.x = pk[0]; w.y = pk[1]; w.z = pk[2]; w.w = pk[3];
;                 *(u32x4*)(U + (size_t)(row >> 13) * U_SLAB + (size_t)(row & (SEQ - 1)) * U_PITCH + col0) = w;
	v_mad_i64_i32 v[48:49], s[2:3], v65, s37, v[48:49]
	v_rcp_f32_e32 v44, v44
	v_rcp_f32_e32 v45, v45
	v_pk_mul_f32 v[46:47], v[54:55], v[52:53] op_sel_hi:[0,1]
	v_pk_mul_f32 v[40:41], v[40:41], v[46:47]
	v_pk_mul_f32 v[46:47], v[36:37], v[50:51] op_sel_hi:[1,0]
	v_pk_mul_f32 v[44:45], v[54:55], v[44:45] op_sel_hi:[0,1]
	v_exp_f32_e32 v46, v46
	v_exp_f32_e32 v47, v47
	v_pk_mul_f32 v[42:43], v[42:43], v[44:45]
	v_pk_mul_f32 v[44:45], v[38:39], v[50:51] op_sel_hi:[1,0]
	v_lshl_add_u64 v[48:49], v[48:49], 0, v[136:137]
	v_exp_f32_e32 v44, v44
	v_exp_f32_e32 v45, v45
	v_lshl_add_u64 v[48:49], v[48:49], 0, v[112:113]
	global_store_dwordx4 v[48:49], v[56:59], off
	v_cvt_pk_bf16_f32 v40, v40, v41
	v_cvt_pk_bf16_f32 v41, v42, v43
	v_pk_add_f32 v[42:43], v[46:47], 1.0 op_sel_hi:[1,0]
	v_pk_add_f32 v[36:37], v[44:45], 1.0 op_sel_hi:[1,0]
	v_rcp_f32_e32 v42, v42
	v_rcp_f32_e32 v43, v43
	v_rcp_f32_e32 v36, v36
	v_rcp_f32_e32 v37, v37
	s_mov_b64 s[2:3], -1
	v_pk_mul_f32 v[38:39], v[54:55], v[42:43] op_sel_hi:[0,1]
	v_pk_mul_f32 v[32:33], v[32:33], v[38:39]
	s_nop 0
	v_cvt_pk_bf16_f32 v42, v32, v33
	v_pk_mul_f32 v[32:33], v[54:55], v[36:37] op_sel_hi:[0,1]
	v_pk_mul_f32 v[32:33], v[34:35], v[32:33]
	v_add_co_u32_e32 v36, vcc, s28, v48
	v_cvt_pk_bf16_f32 v43, v32, v33
	v_mul_f32_e32 v32, 0xbfb8aa3b, v159
	v_pk_mul_f32 v[34:35], v[28:29], v[32:33] op_sel_hi:[1,0]
	v_pk_mul_f32 v[28:29], v[30:31], v[32:33] op_sel_hi:[1,0]
	v_exp_f32_e32 v34, v34
	v_exp_f32_e32 v35, v35
	v_exp_f32_e32 v28, v28
	v_exp_f32_e32 v29, v29
	v_addc_co_u32_e32 v37, vcc, 0, v49, vcc
	v_pk_add_f32 v[34:35], v[34:35], 1.0 op_sel_hi:[1,0]
	v_pk_add_f32 v[28:29], v[28:29], 1.0 op_sel_hi:[1,0]
	v_rcp_f32_e32 v34, v34
	v_rcp_f32_e32 v35, v35
	v_rcp_f32_e32 v28, v28
	v_rcp_f32_e32 v29, v29
	global_store_dwordx4 v[36:37], v[40:43], off offset:2048
	v_mul_f32_e32 v36, v159, v159
	v_pk_mul_f32 v[30:31], v[36:37], v[34:35] op_sel_hi:[0,1]
	v_pk_mul_f32 v[24:25], v[24:25], v[30:31]
	v_pk_mul_f32 v[30:31], v[20:21], v[32:33] op_sel_hi:[1,0]
	v_pk_mul_f32 v[28:29], v[36:37], v[28:29] op_sel_hi:[0,1]
	v_exp_f32_e32 v30, v30
	v_exp_f32_e32 v31, v31
	v_pk_mul_f32 v[26:27], v[26:27], v[28:29]
	v_pk_mul_f32 v[28:29], v[22:23], v[32:33] op_sel_hi:[1,0]
	v_cvt_pk_bf16_f32 v24, v24, v25
	v_cvt_pk_bf16_f32 v25, v26, v27
	v_pk_add_f32 v[26:27], v[30:31], 1.0 op_sel_hi:[1,0]
	v_exp_f32_e32 v28, v28
	v_exp_f32_e32 v29, v29
	v_rcp_f32_e32 v26, v26
	v_rcp_f32_e32 v27, v27
	v_pk_add_f32 v[20:21], v[28:29], 1.0 op_sel_hi:[1,0]
	s_nop 0
	v_rcp_f32_e32 v20, v20
	v_rcp_f32_e32 v21, v21
	v_pk_mul_f32 v[22:23], v[36:37], v[26:27] op_sel_hi:[0,1]
	v_pk_mul_f32 v[16:17], v[16:17], v[22:23]
	s_nop 0
	v_cvt_pk_bf16_f32 v26, v16, v17
	v_pk_mul_f32 v[16:17], v[36:37], v[20:21] op_sel_hi:[0,1]
	v_pk_mul_f32 v[16:17], v[18:19], v[16:17]
	v_add_co_u32_e32 v20, vcc, s38, v48
	v_cvt_pk_bf16_f32 v27, v16, v17
	v_mul_f32_e32 v16, 0xbfb8aa3b, v147
	v_pk_mul_f32 v[18:19], v[12:13], v[16:17] op_sel_hi:[1,0]
	v_pk_mul_f32 v[12:13], v[14:15], v[16:17] op_sel_hi:[1,0]
	v_exp_f32_e32 v18, v18
	v_exp_f32_e32 v19, v19
	v_exp_f32_e32 v12, v12
	v_exp_f32_e32 v13, v13
	v_addc_co_u32_e32 v21, vcc, 0, v49, vcc
	v_pk_add_f32 v[18:19], v[18:19], 1.0 op_sel_hi:[1,0]
	v_pk_add_f32 v[12:13], v[12:13], 1.0 op_sel_hi:[1,0]
	v_rcp_f32_e32 v18, v18
	v_rcp_f32_e32 v19, v19
	v_rcp_f32_e32 v12, v12
	v_rcp_f32_e32 v13, v13
	global_store_dwordx4 v[20:21], v[24:27], off
	v_mul_f32_e32 v20, v147, v147
	v_pk_mul_f32 v[14:15], v[20:21], v[18:19] op_sel_hi:[0,1]
	v_pk_mul_f32 v[8:9], v[8:9], v[14:15]
	v_pk_mul_f32 v[14:15], v[4:5], v[16:17] op_sel_hi:[1,0]
	v_pk_mul_f32 v[12:13], v[20:21], v[12:13] op_sel_hi:[0,1]
	v_exp_f32_e32 v14, v14
	v_exp_f32_e32 v15, v15
	v_pk_mul_f32 v[10:11], v[10:11], v[12:13]
	v_pk_mul_f32 v[12:13], v[6:7], v[16:17] op_sel_hi:[1,0]
	v_cvt_pk_bf16_f32 v8, v8, v9
	v_cvt_pk_bf16_f32 v9, v10, v11
	v_pk_add_f32 v[10:11], v[14:15], 1.0 op_sel_hi:[1,0]
	v_exp_f32_e32 v12, v12
	v_exp_f32_e32 v13, v13
	v_rcp_f32_e32 v10, v10
	v_rcp_f32_e32 v11, v11
	v_pk_add_f32 v[4:5], v[12:13], 1.0 op_sel_hi:[1,0]
	s_nop 0
	v_rcp_f32_e32 v4, v4
	v_rcp_f32_e32 v5, v5
	v_pk_mul_f32 v[6:7], v[20:21], v[10:11] op_sel_hi:[0,1]
	v_pk_mul_f32 v[0:1], v[0:1], v[6:7]
	s_nop 0
	v_cvt_pk_bf16_f32 v10, v0, v1
	v_pk_mul_f32 v[0:1], v[20:21], v[4:5] op_sel_hi:[0,1]
	v_pk_mul_f32 v[0:1], v[2:3], v[0:1]
	s_nop 0
	v_cvt_pk_bf16_f32 v11, v0, v1
	v_add_co_u32_e32 v0, vcc, 0x43000, v48
	s_nop 1
	v_addc_co_u32_e32 v1, vcc, 0, v49, vcc
	s_andn2_b64 vcc, exec, s[4:5]
	global_store_dwordx4 v[0:1], v[8:11], off offset:2048
	s_cbranch_vccnz .LBB0_925
	s_andn2_b64 vcc, exec, s[0:1]
	s_cbranch_vccnz .LBB0_924
	s_barrier
	s_branch .LBB0_924

; __device__ __forceinline__ unsigned cvt_pk_bf16(float lo, float hi) { unsigned r; asm volatile("v_cvt_pk_bf16_f32 %0, %1, %2" : "=v"(r) : "v"(lo), "v"(hi)); return r; }
; __device__ __forceinline__ float bf_lo(unsigned w) { return __uint_as_float(w << 16); }
; __device__ __forceinline__ float bf_hi(unsigned w) { return __uint_as_float(w & 0xffff0000u); }
;     __device__ __forceinline__ void operator()(const f32x4 (&acc)[2][2][4][2], const Unit& u, int wr, int wc, int fr, int fq) const {
;     ...
;             for (int mm = 0; mm < RB; ++mm) { const size_t off = (size_t)(row0 + ai * HALF + (mh + mm) * 16) * D_MODEL + col0;
; #pragma unroll
;                 for (int bj = 0; bj < 2; ++bj) {
;                     if (BASE_F32) { bf[mm][bj][0] = *(const f32x4*)(basef + off + bj * HALF); bf[mm][bj][1] = *(const f32x4*)(basef + off + bj * HALF + 4); }
;                     else bb[mm][bj] = *(const u32x4*)(xb + off + bj * HALF);
;                 } }
;             asm volatile("" ::: "memory");
; #pragma unroll
;             for (int mm = 0; mm < RB; ++mm) {
;                 const int m = mh + mm;
;                 const int row = row0 + ai * HALF + m * 16; const size_t off = (size_t)row * D_MODEL + col0; float s = 0.f;
; #pragma unroll
;                 for (int bj = 0; bj < 2; ++bj) {
;                     f32x4 b0, b1;
;                     if (BASE_F32) { b0 = bf[mm][bj][0]; b1 = bf[mm][bj][1]; }
;                     else { const u32x4 w = bb[mm][bj]; b0 = (f32x4){bf_lo(w.x), bf_hi(w.x), bf_lo(w.y), bf_hi(w.y)}; b1 = (f32x4){bf_lo(w.z), bf_hi(w.z), bf_lo(w.w), bf_hi(w.w)}; }
;                     const f32x4 o0 = b0 + acc[ai][bj][m][0] * alpha, o1 = b1 + acc[ai][bj][m][1] * alpha;
;                     if (OUT_F32) { *(f32x4*)(out + off + bj * HALF) = o0; *(f32x4*)(out + off + bj * HALF + 4) = o1; }
;                     else { u32x4 w; w.x = cvt_pk_bf16(o0[0], o0[1]); w.y = cvt_pk_bf16(o0[2], o0[3]); w.z = cvt_pk_bf16(o1[0], o1[1]); w.w = cvt_pk_bf16(o1[2], o1[3]); *(u32x4*)(xb + off + bj * HALF) = w; }
;                     s += ((o0[0] * o0[0] + o0[1] * o0[1]) + (o0[2] * o0[2] + o0[3] * o0[3])) + ((o1[0] * o1[0] + o1[1] * o1[1]) + (o1[2] * o1[2] + o1[3] * o1[3]));
;                 }
;                 if (ssp) { s += __shfl_xor(s, 16); s += __shfl_xor(s, 32); if (fq == 0) ssp[(size_t)row * 16 + u.pn * 4 + wc] = s; }
.LBB0_1037:
	s_mov_b32 s98, 0xffff0000
	s_mov_b32 s99, 0xffff0000
	s_mov_b32 s100, 0
	s_mov_b32 s101, -1
	v_lshl_or_b32 v166, s10, 8, v186
	v_lshl_add_u32 v168, s41, 8, v184
	v_ashrrev_i32_e32 v167, 31, v166
	v_readlane_b32 s2, v235, 38
	v_lshlrev_b64 v[202:203], 1, v[166:167]
	v_readlane_b32 s3, v235, 39
	v_ashrrev_i32_e32 v169, 31, v168
	v_or_b32_e32 v180, 16, v168
	v_or_b32_e32 v176, 32, v168
	v_lshl_add_u64 v[170:171], s[2:3], 0, v[202:203]
	v_lshlrev_b64 v[204:205], 11, v[168:169]
	v_or_b32_e32 v172, 48, v168
	v_ashrrev_i32_e32 v181, 31, v180
	v_ashrrev_i32_e32 v177, 31, v176
	v_lshl_add_u64 v[128:129], v[170:171], 0, v[204:205]
	v_ashrrev_i32_e32 v173, 31, v172
	v_lshlrev_b64 v[182:183], 11, v[180:181]
	v_lshlrev_b64 v[178:179], 11, v[176:177]
	global_load_dwordx4 v[192:195], v[128:129], off
	global_load_dwordx4 v[198:201], v[128:129], off offset:256
	v_lshlrev_b64 v[174:175], 11, v[172:173]
	v_lshl_add_u64 v[128:129], v[170:171], 0, v[182:183]
	v_lshl_add_u64 v[130:131], v[170:171], 0, v[178:179]
	v_lshl_add_u64 v[206:207], v[170:171], 0, v[174:175]
	global_load_dwordx4 v[148:151], v[128:129], off
	global_load_dwordx4 v[144:147], v[128:129], off offset:256
	global_load_dwordx4 v[140:143], v[130:131], off
	global_load_dwordx4 v[136:139], v[130:131], off offset:256
	global_load_dwordx4 v[132:135], v[206:207], off
	s_nop 0
	global_load_dwordx4 v[128:131], v[206:207], off offset:256
	v_readlane_b32 s22, v235, 42
	v_readlane_b32 s23, v235, 43
	v_lshl_add_u64 v[204:205], s[2:3], 0, v[204:205]
	s_lshl_b32 s20, s10, 2
	v_cndmask_b32_e64 v197, 0, 1, s[22:23]
	v_lshl_add_u64 v[202:203], v[204:205], 0, v[202:203]
	s_ashr_i32 s21, s20, 31
	v_cmp_ne_u32_e64 s[8:9], 1, v197
	s_andn2_b64 vcc, exec, s[22:23]
	s_waitcnt vmcnt(0)
	v_lshlrev_b32_e32 v204, 16, v192
	v_and_b32_e32 v205, 0xffff0000, v192
	v_lshlrev_b32_e32 v192, 16, v193
	v_and_b32_e32 v193, 0xffff0000, v193
	v_lshlrev_b32_e32 v206, 16, v194
	v_and_b32_e32 v207, 0xffff0000, v194
	v_lshlrev_b32_e32 v194, 16, v195
	v_and_b32_e32 v195, 0xffff0000, v195
	v_lshlrev_b32_e32 v208, 16, v198
	v_and_b32_e32 v209, 0xffff0000, v198
	v_lshlrev_b32_e32 v198, 16, v199
	v_and_b32_e32 v199, 0xffff0000, v199
	v_lshlrev_b32_e32 v210, 16, v200
	v_and_b32_e32 v211, 0xffff0000, v200
	v_lshlrev_b32_e32 v200, 16, v201
	v_and_b32_e32 v201, 0xffff0000, v201
	v_pk_fma_f32 v[126:127], v[126:127], 0.5, v[192:193] op_sel_hi:[1,0,1]
	v_pk_fma_f32 v[124:125], v[124:125], 0.5, v[204:205] op_sel_hi:[1,0,1]
	v_pk_fma_f32 v[122:123], v[122:123], 0.5, v[194:195] op_sel_hi:[1,0,1]
	v_pk_fma_f32 v[120:121], v[120:121], 0.5, v[206:207] op_sel_hi:[1,0,1]
	v_pk_fma_f32 v[118:119], v[118:119], 0.5, v[198:199] op_sel_hi:[1,0,1]
	v_pk_fma_f32 v[116:117], v[116:117], 0.5, v[208:209] op_sel_hi:[1,0,1]
	v_pk_fma_f32 v[114:115], v[114:115], 0.5, v[200:201] op_sel_hi:[1,0,1]
	v_pk_fma_f32 v[112:113], v[112:113], 0.5, v[210:211] op_sel_hi:[1,0,1]
	v_cvt_pk_bf16_f32 v192, v124, v125
	v_cvt_pk_bf16_f32 v193, v126, v127
	v_cvt_pk_bf16_f32 v194, v120, v121
	v_cvt_pk_bf16_f32 v195, v122, v123
	global_store_dwordx4 v[202:203], v[192:195], off
	s_nop 1
	v_cvt_pk_bf16_f32 v192, v116, v117
	v_cvt_pk_bf16_f32 v193, v118, v119
	v_cvt_pk_bf16_f32 v194, v112, v113
	v_cvt_pk_bf16_f32 v195, v114, v115
	global_store_dwordx4 v[202:203], v[192:195], off offset:256
	s_cbranch_vccnz .LBB0_1041
	v_mul_f32_e32 v113, v113, v113
	v_mul_f32_e32 v125, v125, v125
	v_mul_f32_e32 v121, v121, v121
	v_mul_f32_e32 v117, v117, v117
	v_fmac_f32_e32 v113, v112, v112
	v_mul_f32_e32 v112, v115, v115
	v_fmac_f32_e32 v125, v124, v124
	v_mul_f32_e32 v124, v127, v127
	v_fmac_f32_e32 v121, v120, v120
	v_mul_f32_e32 v120, v123, v123
	v_fmac_f32_e32 v117, v116, v116
	v_mul_f32_e32 v116, v119, v119
	v_fmac_f32_e32 v112, v114, v114
	v_and_b32_e32 v114, 64, v191
	v_fmac_f32_e32 v124, v126, v126
	v_fmac_f32_e32 v120, v122, v122
	v_fmac_f32_e32 v116, v118, v118
	v_add_f32_e32 v112, v113, v112
	v_add_u32_e32 v114, 64, v114
	v_add_f32_e32 v124, v125, v124
	v_add_f32_e32 v120, v121, v120
	v_add_f32_e32 v116, v117, v116
	v_add_f32_e32 v120, v124, v120
	v_add_f32_e32 v112, v116, v112
	v_add_f32_e32 v112, v120, v112
	v_mov_b32_e32 v236, v112
	s_nop 1
	v_permlane16_swap_b32_e32 v112, v236
	s_waitcnt lgkmcnt(0)
	v_add_f32_e32 v112, v112, v236
	s_nop 1
	v_mov_b32_e32 v236, v112
	s_nop 1
	v_permlane32_swap_b32_e32 v112, v236
	s_and_saveexec_b64 s[2:3], s[4:5]
	s_cbranch_execz .LBB0_1040
	v_readlane_b32 s22, v235, 50
	v_lshlrev_b64 v[114:115], 6, v[168:169]
	v_readlane_b32 s23, v235, 51
	s_lshl_b32 s10, s29, 2
	s_waitcnt lgkmcnt(0)
	v_add_f32_e32 v112, v112, v236
	v_lshl_add_u64 v[114:115], s[22:23], 0, v[114:115]
	v_lshl_add_u64 v[114:115], s[20:21], 2, v[114:115]
	v_lshl_add_u64 v[114:115], v[114:115], 0, s[10:11]
	global_store_dword v[114:115], v112, off

; __device__ __forceinline__ unsigned cvt_pk_bf16(float lo, float hi) { unsigned r; asm volatile("v_cvt_pk_bf16_f32 %0, %1, %2" : "=v"(r) : "v"(lo), "v"(hi)); return r; }
; __device__ __forceinline__ float bf_lo(unsigned w) { return __uint_as_float(w << 16); }
; __device__ __forceinline__ float bf_hi(unsigned w) { return __uint_as_float(w & 0xffff0000u); }
;     __device__ __forceinline__ void operator()(const f32x4 (&acc)[2][2][4][2], const Unit& u, int wr, int wc, int fr, int fq) const {
;     ...
;             for (int mm = 0; mm < RB; ++mm) { const size_t off = (size_t)(row0 + ai * HALF + (mh + mm) * 16) * D_MODEL + col0;
; #pragma unroll
;                 for (int bj = 0; bj < 2; ++bj) {
;                     if (BASE_F32) { bf[mm][bj][0] = *(const f32x4*)(basef + off + bj * HALF); bf[mm][bj][1] = *(const f32x4*)(basef + off + bj * HALF + 4); }
;                     else bb[mm][bj] = *(const u32x4*)(xb + off + bj * HALF);
;                 } }
;             asm volatile("" ::: "memory");
; #pragma unroll
;             for (int mm = 0; mm < RB; ++mm) {
;                 const int m = mh + mm;
;                 const int row = row0 + ai * HALF + m * 16; const size_t off = (size_t)row * D_MODEL + col0; float s = 0.f;
; #pragma unroll
;                 for (int bj = 0; bj < 2; ++bj) {
;                     f32x4 b0, b1;
;                     if (BASE_F32) { b0 = bf[mm][bj][0]; b1 = bf[mm][bj][1]; }
;                     else { const u32x4 w = bb[mm][bj]; b0 = (f32x4){bf_lo(w.x), bf_hi(w.x), bf_lo(w.y), bf_hi(w.y)}; b1 = (f32x4){bf_lo(w.z), bf_hi(w.z), bf_lo(w.w), bf_hi(w.w)}; }
;                     const f32x4 o0 = b0 + acc[ai][bj][m][0] * alpha, o1 = b1 + acc[ai][bj][m][1] * alpha;
;                     if (OUT_F32) { *(f32x4*)(out + off + bj * HALF) = o0; *(f32x4*)(out + off + bj * HALF + 4) = o1; }
;                     else { u32x4 w; w.x = cvt_pk_bf16(o0[0], o0[1]); w.y = cvt_pk_bf16(o0[2], o0[3]); w.z = cvt_pk_bf16(o1[0], o1[1]); w.w = cvt_pk_bf16(o1[2], o1[3]); *(u32x4*)(xb + off + bj * HALF) = w; }
;                     s += ((o0[0] * o0[0] + o0[1] * o0[1]) + (o0[2] * o0[2] + o0[3] * o0[3])) + ((o1[0] * o1[0] + o1[1] * o1[1]) + (o1[2] * o1[2] + o1[3] * o1[3]));
;                 }
;                 if (ssp) { s += __shfl_xor(s, 16); s += __shfl_xor(s, 32); if (fq == 0) ssp[(size_t)row * 16 + u.pn * 4 + wc] = s; }
.LBB0_1041:
	v_readlane_b32 s2, v235, 38
	v_lshlrev_b32_e32 v116, 16, v150
	v_and_b32_e32 v117, 0xffff0000, v150
	v_readlane_b32 s3, v235, 39
	v_lshlrev_b32_e32 v112, 16, v148
	s_waitcnt lgkmcnt(0)
	v_and_b32_e32 v113, 0xffff0000, v148
	v_lshlrev_b32_e32 v114, 16, v149
	v_and_b32_e32 v115, 0xffff0000, v149
	v_lshlrev_b32_e32 v118, 16, v151
	v_and_b32_e32 v119, 0xffff0000, v151
	v_pk_fma_f32 v[104:105], v[104:105], 0.5, v[116:117] op_sel_hi:[1,0,1]
	v_lshl_add_u64 v[116:117], s[2:3], 0, v[182:183]
	v_pk_fma_f32 v[110:111], v[110:111], 0.5, v[114:115] op_sel_hi:[1,0,1]
	v_pk_fma_f32 v[108:109], v[108:109], 0.5, v[112:113] op_sel_hi:[1,0,1]
	v_pk_fma_f32 v[106:107], v[106:107], 0.5, v[118:119] op_sel_hi:[1,0,1]
	v_cvt_pk_bf16_f32 v112, v108, v109
	v_cvt_pk_bf16_f32 v113, v110, v111
	v_cvt_pk_bf16_f32 v114, v104, v105
	v_lshl_add_u64 v[116:117], v[166:167], 1, v[116:117]
	v_cvt_pk_bf16_f32 v115, v106, v107
	global_store_dwordx4 v[116:117], v[112:115], off
	v_lshlrev_b32_e32 v118, 16, v146
	v_and_b32_e32 v119, 0xffff0000, v146
	v_lshlrev_b32_e32 v112, 16, v144
	v_and_b32_e32 v113, 0xffff0000, v144
	v_lshlrev_b32_e32 v114, 16, v145
	v_and_b32_e32 v115, 0xffff0000, v145
	v_lshlrev_b32_e32 v120, 16, v147
	v_and_b32_e32 v121, 0xffff0000, v147
	v_pk_fma_f32 v[102:103], v[102:103], 0.5, v[114:115] op_sel_hi:[1,0,1]
	v_pk_fma_f32 v[100:101], v[100:101], 0.5, v[112:113] op_sel_hi:[1,0,1]
	v_pk_fma_f32 v[98:99], v[98:99], 0.5, v[120:121] op_sel_hi:[1,0,1]
	v_pk_fma_f32 v[96:97], v[96:97], 0.5, v[118:119] op_sel_hi:[1,0,1]
	s_and_b64 vcc, exec, s[8:9]
	v_cvt_pk_bf16_f32 v112, v100, v101
	v_cvt_pk_bf16_f32 v113, v102, v103
	v_cvt_pk_bf16_f32 v114, v96, v97
	v_cvt_pk_bf16_f32 v115, v98, v99
	global_store_dwordx4 v[116:117], v[112:115], off offset:256
	s_cbranch_vccnz .LBB0_1045
	v_mul_f32_e32 v97, v97, v97
	v_mul_f32_e32 v109, v109, v109
	v_mul_f32_e32 v105, v105, v105
	v_mul_f32_e32 v101, v101, v101
	v_fmac_f32_e32 v97, v96, v96
	v_mul_f32_e32 v96, v99, v99
	v_fmac_f32_e32 v109, v108, v108
	v_mul_f32_e32 v108, v111, v111
	v_fmac_f32_e32 v105, v104, v104
	v_mul_f32_e32 v104, v107, v107
	v_fmac_f32_e32 v101, v100, v100
	v_mul_f32_e32 v100, v103, v103
	v_fmac_f32_e32 v96, v98, v98
	v_and_b32_e32 v98, 64, v191
	v_fmac_f32_e32 v108, v110, v110
	v_fmac_f32_e32 v104, v106, v106
	v_fmac_f32_e32 v100, v102, v102
	v_add_f32_e32 v96, v97, v96
	v_add_u32_e32 v98, 64, v98
	v_add_f32_e32 v108, v109, v108
	v_add_f32_e32 v104, v105, v104
	v_add_f32_e32 v100, v101, v100
	v_add_f32_e32 v104, v108, v104
	v_add_f32_e32 v96, v100, v96
	v_add_f32_e32 v96, v104, v96
	v_mov_b32_e32 v236, v96
	s_nop 1
	v_permlane16_swap_b32_e32 v96, v236
	s_waitcnt lgkmcnt(0)
	v_add_f32_e32 v96, v96, v236
	s_nop 1
	v_mov_b32_e32 v236, v96
	s_nop 1
	v_permlane32_swap_b32_e32 v96, v236
	s_and_saveexec_b64 s[2:3], s[4:5]
	s_cbranch_execz .LBB0_1044
	v_readlane_b32 s22, v235, 50
	v_lshlrev_b64 v[98:99], 6, v[180:181]
	v_readlane_b32 s23, v235, 51
	s_lshl_b32 s10, s29, 2
	s_waitcnt lgkmcnt(0)
	v_add_f32_e32 v96, v96, v236
	v_lshl_add_u64 v[98:99], s[22:23], 0, v[98:99]
	v_lshl_add_u64 v[98:99], s[20:21], 2, v[98:99]
	v_lshl_add_u64 v[98:99], v[98:99], 0, s[10:11]
	global_store_dword v[98:99], v96, off

; __device__ __forceinline__ unsigned cvt_pk_bf16(float lo, float hi) { unsigned r; asm volatile("v_cvt_pk_bf16_f32 %0, %1, %2" : "=v"(r) : "v"(lo), "v"(hi)); return r; }
; __device__ __forceinline__ float bf_lo(unsigned w) { return __uint_as_float(w << 16); }
; __device__ __forceinline__ float bf_hi(unsigned w) { return __uint_as_float(w & 0xffff0000u); }
;     __device__ __forceinline__ void operator()(const f32x4 (&acc)[2][2][4][2], const Unit& u, int wr, int wc, int fr, int fq) const {
;     ...
;             for (int mm = 0; mm < RB; ++mm) { const size_t off = (size_t)(row0 + ai * HALF + (mh + mm) * 16) * D_MODEL + col0;
; #pragma unroll
;                 for (int bj = 0; bj < 2; ++bj) {
;                     if (BASE_F32) { bf[mm][bj][0] = *(const f32x4*)(basef + off + bj * HALF); bf[mm][bj][1] = *(const f32x4*)(basef + off + bj * HALF + 4); }
;                     else bb[mm][bj] = *(const u32x4*)(xb + off + bj * HALF);
;                 } }
;             asm volatile("" ::: "memory");
; #pragma unroll
;             for (int mm = 0; mm < RB; ++mm) {
;                 const int m = mh + mm;
;                 const int row = row0 + ai * HALF + m * 16; const size_t off = (size_t)row * D_MODEL + col0; float s = 0.f;
; #pragma unroll
;                 for (int bj = 0; bj < 2; ++bj) {
;                     f32x4 b0, b1;
;                     if (BASE_F32) { b0 = bf[mm][bj][0]; b1 = bf[mm][bj][1]; }
;                     else { const u32x4 w = bb[mm][bj]; b0 = (f32x4){bf_lo(w.x), bf_hi(w.x), bf_lo(w.y), bf_hi(w.y)}; b1 = (f32x4){bf_lo(w.z), bf_hi(w.z), bf_lo(w.w), bf_hi(w.w)}; }
;                     const f32x4 o0 = b0 + acc[ai][bj][m][0] * alpha, o1 = b1 + acc[ai][bj][m][1] * alpha;
;                     if (OUT_F32) { *(f32x4*)(out + off + bj * HALF) = o0; *(f32x4*)(out + off + bj * HALF + 4) = o1; }
;                     else { u32x4 w; w.x = cvt_pk_bf16(o0[0], o0[1]); w.y = cvt_pk_bf16(o0[2], o0[3]); w.z = cvt_pk_bf16(o1[0], o1[1]); w.w = cvt_pk_bf16(o1[2], o1[3]); *(u32x4*)(xb + off + bj * HALF) = w; }
;                     s += ((o0[0] * o0[0] + o0[1] * o0[1]) + (o0[2] * o0[2] + o0[3] * o0[3])) + ((o1[0] * o1[0] + o1[1] * o1[1]) + (o1[2] * o1[2] + o1[3] * o1[3]));
;                 }
;                 if (ssp) { s += __shfl_xor(s, 16); s += __shfl_xor(s, 32); if (fq == 0) ssp[(size_t)row * 16 + u.pn * 4 + wc] = s; }
.LBB0_1045:
	v_readlane_b32 s2, v235, 38
	v_lshlrev_b32_e32 v100, 16, v142
	v_and_b32_e32 v101, 0xffff0000, v142
	v_readlane_b32 s3, v235, 39
	v_lshlrev_b32_e32 v96, 16, v140
	s_waitcnt lgkmcnt(0)
	v_and_b32_e32 v97, 0xffff0000, v140
	v_lshlrev_b32_e32 v98, 16, v141
	v_and_b32_e32 v99, 0xffff0000, v141
	v_lshlrev_b32_e32 v102, 16, v143
	v_and_b32_e32 v103, 0xffff0000, v143
	v_pk_fma_f32 v[88:89], v[88:89], 0.5, v[100:101] op_sel_hi:[1,0,1]
	v_lshl_add_u64 v[100:101], s[2:3], 0, v[178:179]
	v_pk_fma_f32 v[94:95], v[94:95], 0.5, v[98:99] op_sel_hi:[1,0,1]
	v_pk_fma_f32 v[92:93], v[92:93], 0.5, v[96:97] op_sel_hi:[1,0,1]
	v_pk_fma_f32 v[90:91], v[90:91], 0.5, v[102:103] op_sel_hi:[1,0,1]
	v_cvt_pk_bf16_f32 v96, v92, v93
	v_cvt_pk_bf16_f32 v97, v94, v95
	v_cvt_pk_bf16_f32 v98, v88, v89
	v_lshl_add_u64 v[100:101], v[166:167], 1, v[100:101]
	v_cvt_pk_bf16_f32 v99, v90, v91
	global_store_dwordx4 v[100:101], v[96:99], off
	v_lshlrev_b32_e32 v102, 16, v138
	v_and_b32_e32 v103, 0xffff0000, v138
	v_lshlrev_b32_e32 v96, 16, v136
	v_and_b32_e32 v97, 0xffff0000, v136
	v_lshlrev_b32_e32 v98, 16, v137
	v_and_b32_e32 v99, 0xffff0000, v137
	v_lshlrev_b32_e32 v104, 16, v139
	v_and_b32_e32 v105, 0xffff0000, v139
	v_pk_fma_f32 v[86:87], v[86:87], 0.5, v[98:99] op_sel_hi:[1,0,1]
	v_pk_fma_f32 v[84:85], v[84:85], 0.5, v[96:97] op_sel_hi:[1,0,1]
	v_pk_fma_f32 v[82:83], v[82:83], 0.5, v[104:105] op_sel_hi:[1,0,1]
	v_pk_fma_f32 v[80:81], v[80:81], 0.5, v[102:103] op_sel_hi:[1,0,1]
	s_and_b64 vcc, exec, s[8:9]
	v_cvt_pk_bf16_f32 v96, v84, v85
	v_cvt_pk_bf16_f32 v97, v86, v87
	v_cvt_pk_bf16_f32 v98, v80, v81
	v_cvt_pk_bf16_f32 v99, v82, v83
	global_store_dwordx4 v[100:101], v[96:99], off offset:256
	s_cbranch_vccnz .LBB0_1049
	v_mul_f32_e32 v81, v81, v81
	v_mul_f32_e32 v93, v93, v93
	v_mul_f32_e32 v89, v89, v89
	v_mul_f32_e32 v85, v85, v85
	v_fmac_f32_e32 v81, v80, v80
	v_mul_f32_e32 v80, v83, v83
	v_fmac_f32_e32 v93, v92, v92
	v_mul_f32_e32 v92, v95, v95
	v_fmac_f32_e32 v89, v88, v88
	v_mul_f32_e32 v88, v91, v91
	v_fmac_f32_e32 v85, v84, v84
	v_mul_f32_e32 v84, v87, v87
	v_fmac_f32_e32 v80, v82, v82
	v_and_b32_e32 v82, 64, v191
	v_fmac_f32_e32 v92, v94, v94
	v_fmac_f32_e32 v88, v90, v90
	v_fmac_f32_e32 v84, v86, v86
	v_add_f32_e32 v80, v81, v80
	v_add_u32_e32 v82, 64, v82
	v_add_f32_e32 v92, v93, v92
	v_add_f32_e32 v88, v89, v88
	v_add_f32_e32 v84, v85, v84
	v_add_f32_e32 v88, v92, v88
	v_add_f32_e32 v80, v84, v80
	v_add_f32_e32 v80, v88, v80
	v_mov_b32_e32 v236, v80
	s_nop 1
	v_permlane16_swap_b32_e32 v80, v236
	s_waitcnt lgkmcnt(0)
	v_add_f32_e32 v80, v80, v236
	s_nop 1
	v_mov_b32_e32 v236, v80
	s_nop 1
	v_permlane32_swap_b32_e32 v80, v236
	s_and_saveexec_b64 s[2:3], s[4:5]
	s_cbranch_execz .LBB0_1048
	v_readlane_b32 s22, v235, 50
	v_lshlrev_b64 v[82:83], 6, v[176:177]
	v_readlane_b32 s23, v235, 51
	s_lshl_b32 s10, s29, 2
	s_waitcnt lgkmcnt(0)
	v_add_f32_e32 v80, v80, v236
	v_lshl_add_u64 v[82:83], s[22:23], 0, v[82:83]
	v_lshl_add_u64 v[82:83], s[20:21], 2, v[82:83]
	v_lshl_add_u64 v[82:83], v[82:83], 0, s[10:11]
	global_store_dword v[82:83], v80, off

; __device__ __forceinline__ unsigned cvt_pk_bf16(float lo, float hi) { unsigned r; asm volatile("v_cvt_pk_bf16_f32 %0, %1, %2" : "=v"(r) : "v"(lo), "v"(hi)); return r; }
; __device__ __forceinline__ float bf_lo(unsigned w) { return __uint_as_float(w << 16); }
; __device__ __forceinline__ float bf_hi(unsigned w) { return __uint_as_float(w & 0xffff0000u); }
;     __device__ __forceinline__ void operator()(const f32x4 (&acc)[2][2][4][2], const Unit& u, int wr, int wc, int fr, int fq) const {
;     ...
;             for (int mm = 0; mm < RB; ++mm) { const size_t off = (size_t)(row0 + ai * HALF + (mh + mm) * 16) * D_MODEL + col0;
; #pragma unroll
;                 for (int bj = 0; bj < 2; ++bj) {
;                     if (BASE_F32) { bf[mm][bj][0] = *(const f32x4*)(basef + off + bj * HALF); bf[mm][bj][1] = *(const f32x4*)(basef + off + bj * HALF + 4); }
;                     else bb[mm][bj] = *(const u32x4*)(xb + off + bj * HALF);
;                 } }
;             asm volatile("" ::: "memory");
; #pragma unroll
;             for (int mm = 0; mm < RB; ++mm) {
;                 const int m = mh + mm;
;                 const int row = row0 + ai * HALF + m * 16; const size_t off = (size_t)row * D_MODEL + col0; float s = 0.f;
; #pragma unroll
;                 for (int bj = 0; bj < 2; ++bj) {
;                     f32x4 b0, b1;
;                     if (BASE_F32) { b0 = bf[mm][bj][0]; b1 = bf[mm][bj][1]; }
;                     else { const u32x4 w = bb[mm][bj]; b0 = (f32x4){bf_lo(w.x), bf_hi(w.x), bf_lo(w.y), bf_hi(w.y)}; b1 = (f32x4){bf_lo(w.z), bf_hi(w.z), bf_lo(w.w), bf_hi(w.w)}; }
;                     const f32x4 o0 = b0 + acc[ai][bj][m][0] * alpha, o1 = b1 + acc[ai][bj][m][1] * alpha;
;                     if (OUT_F32) { *(f32x4*)(out + off + bj * HALF) = o0; *(f32x4*)(out + off + bj * HALF + 4) = o1; }
;                     else { u32x4 w; w.x = cvt_pk_bf16(o0[0], o0[1]); w.y = cvt_pk_bf16(o0[2], o0[3]); w.z = cvt_pk_bf16(o1[0], o1[1]); w.w = cvt_pk_bf16(o1[2], o1[3]); *(u32x4*)(xb + off + bj * HALF) = w; }
;                     s += ((o0[0] * o0[0] + o0[1] * o0[1]) + (o0[2] * o0[2] + o0[3] * o0[3])) + ((o1[0] * o1[0] + o1[1] * o1[1]) + (o1[2] * o1[2] + o1[3] * o1[3]));
;                 }
;                 if (ssp) { s += __shfl_xor(s, 16); s += __shfl_xor(s, 32); if (fq == 0) ssp[(size_t)row * 16 + u.pn * 4 + wc] = s; }
.LBB0_1049:
	v_readlane_b32 s2, v235, 38
	v_lshlrev_b32_e32 v84, 16, v134
	v_and_b32_e32 v85, 0xffff0000, v134
	v_readlane_b32 s3, v235, 39
	v_lshlrev_b32_e32 v80, 16, v132
	s_waitcnt lgkmcnt(0)
	v_and_b32_e32 v81, 0xffff0000, v132
	v_lshlrev_b32_e32 v82, 16, v133
	v_and_b32_e32 v83, 0xffff0000, v133
	v_lshlrev_b32_e32 v86, 16, v135
	v_and_b32_e32 v87, 0xffff0000, v135
	v_pk_fma_f32 v[72:73], v[72:73], 0.5, v[84:85] op_sel_hi:[1,0,1]
	v_lshl_add_u64 v[84:85], s[2:3], 0, v[174:175]
	v_pk_fma_f32 v[78:79], v[78:79], 0.5, v[82:83] op_sel_hi:[1,0,1]
	v_pk_fma_f32 v[76:77], v[76:77], 0.5, v[80:81] op_sel_hi:[1,0,1]
	v_pk_fma_f32 v[74:75], v[74:75], 0.5, v[86:87] op_sel_hi:[1,0,1]
	v_cvt_pk_bf16_f32 v80, v76, v77
	v_cvt_pk_bf16_f32 v81, v78, v79
	v_cvt_pk_bf16_f32 v82, v72, v73
	v_lshl_add_u64 v[84:85], v[166:167], 1, v[84:85]
	v_cvt_pk_bf16_f32 v83, v74, v75
	global_store_dwordx4 v[84:85], v[80:83], off
	v_lshlrev_b32_e32 v86, 16, v130
	v_and_b32_e32 v87, 0xffff0000, v130
	v_lshlrev_b32_e32 v80, 16, v128
	v_and_b32_e32 v81, 0xffff0000, v128
	v_lshlrev_b32_e32 v82, 16, v129
	v_and_b32_e32 v83, 0xffff0000, v129
	v_lshlrev_b32_e32 v88, 16, v131
	v_and_b32_e32 v89, 0xffff0000, v131
	v_pk_fma_f32 v[70:71], v[70:71], 0.5, v[82:83] op_sel_hi:[1,0,1]
	v_pk_fma_f32 v[68:69], v[68:69], 0.5, v[80:81] op_sel_hi:[1,0,1]
	v_pk_fma_f32 v[66:67], v[66:67], 0.5, v[88:89] op_sel_hi:[1,0,1]
	v_pk_fma_f32 v[64:65], v[64:65], 0.5, v[86:87] op_sel_hi:[1,0,1]
	s_and_b64 vcc, exec, s[8:9]
	v_cvt_pk_bf16_f32 v80, v68, v69
	v_cvt_pk_bf16_f32 v81, v70, v71
	v_cvt_pk_bf16_f32 v82, v64, v65
	v_cvt_pk_bf16_f32 v83, v66, v67
	global_store_dwordx4 v[84:85], v[80:83], off offset:256
	s_cbranch_vccnz .LBB0_1053
	v_mul_f32_e32 v65, v65, v65
	v_mul_f32_e32 v77, v77, v77
	v_mul_f32_e32 v73, v73, v73
	v_mul_f32_e32 v69, v69, v69
	v_fmac_f32_e32 v65, v64, v64
	v_mul_f32_e32 v64, v67, v67
	v_fmac_f32_e32 v77, v76, v76
	v_mul_f32_e32 v76, v79, v79
	v_fmac_f32_e32 v73, v72, v72
	v_mul_f32_e32 v72, v75, v75
	v_fmac_f32_e32 v69, v68, v68
	v_mul_f32_e32 v68, v71, v71
	v_fmac_f32_e32 v64, v66, v66
	v_and_b32_e32 v66, 64, v191
	v_fmac_f32_e32 v76, v78, v78
	v_fmac_f32_e32 v72, v74, v74
	v_fmac_f32_e32 v68, v70, v70
	v_add_f32_e32 v64, v65, v64
	v_add_u32_e32 v66, 64, v66
	v_add_f32_e32 v76, v77, v76
	v_add_f32_e32 v72, v73, v72
	v_add_f32_e32 v68, v69, v68
	v_add_f32_e32 v72, v76, v72
	v_add_f32_e32 v64, v68, v64
	v_add_f32_e32 v64, v72, v64
	v_mov_b32_e32 v236, v64
	s_nop 1
	v_permlane16_swap_b32_e32 v64, v236
	s_waitcnt lgkmcnt(0)
	v_add_f32_e32 v64, v64, v236
	s_nop 1
	v_mov_b32_e32 v236, v64
	s_nop 1
	v_permlane32_swap_b32_e32 v64, v236
	s_and_saveexec_b64 s[2:3], s[4:5]
	s_cbranch_execz .LBB0_1052
	v_readlane_b32 s22, v235, 50
	v_lshlrev_b64 v[66:67], 6, v[172:173]
	v_readlane_b32 s23, v235, 51
	s_lshl_b32 s10, s29, 2
	s_waitcnt lgkmcnt(0)
	v_add_f32_e32 v64, v64, v236
	v_lshl_add_u64 v[66:67], s[22:23], 0, v[66:67]
	v_lshl_add_u64 v[66:67], s[20:21], 2, v[66:67]
	v_lshl_add_u64 v[66:67], v[66:67], 0, s[10:11]
	global_store_dword v[66:67], v64, off

; __device__ __forceinline__ unsigned cvt_pk_bf16(float lo, float hi) { unsigned r; asm volatile("v_cvt_pk_bf16_f32 %0, %1, %2" : "=v"(r) : "v"(lo), "v"(hi)); return r; }
; __device__ __forceinline__ float bf_lo(unsigned w) { return __uint_as_float(w << 16); }
; __device__ __forceinline__ float bf_hi(unsigned w) { return __uint_as_float(w & 0xffff0000u); }
;     __device__ __forceinline__ void operator()(const f32x4 (&acc)[2][2][4][2], const Unit& u, int wr, int wc, int fr, int fq) const {
;     ...
;             for (int mm = 0; mm < RB; ++mm) { const size_t off = (size_t)(row0 + ai * HALF + (mh + mm) * 16) * D_MODEL + col0;
; #pragma unroll
;                 for (int bj = 0; bj < 2; ++bj) {
;                     if (BASE_F32) { bf[mm][bj][0] = *(const f32x4*)(basef + off + bj * HALF); bf[mm][bj][1] = *(const f32x4*)(basef + off + bj * HALF + 4); }
;                     else bb[mm][bj] = *(const u32x4*)(xb + off + bj * HALF);
;                 } }
;             asm volatile("" ::: "memory");
; #pragma unroll
;             for (int mm = 0; mm < RB; ++mm) {
;                 const int m = mh + mm;
;                 const int row = row0 + ai * HALF + m * 16; const size_t off = (size_t)row * D_MODEL + col0; float s = 0.f;
; #pragma unroll
;                 for (int bj = 0; bj < 2; ++bj) {
;                     f32x4 b0, b1;
;                     if (BASE_F32) { b0 = bf[mm][bj][0]; b1 = bf[mm][bj][1]; }
;                     else { const u32x4 w = bb[mm][bj]; b0 = (f32x4){bf_lo(w.x), bf_hi(w.x), bf_lo(w.y), bf_hi(w.y)}; b1 = (f32x4){bf_lo(w.z), bf_hi(w.z), bf_lo(w.w), bf_hi(w.w)}; }
;                     const f32x4 o0 = b0 + acc[ai][bj][m][0] * alpha, o1 = b1 + acc[ai][bj][m][1] * alpha;
;                     if (OUT_F32) { *(f32x4*)(out + off + bj * HALF) = o0; *(f32x4*)(out + off + bj * HALF + 4) = o1; }
;                     else { u32x4 w; w.x = cvt_pk_bf16(o0[0], o0[1]); w.y = cvt_pk_bf16(o0[2], o0[3]); w.z = cvt_pk_bf16(o1[0], o1[1]); w.w = cvt_pk_bf16(o1[2], o1[3]); *(u32x4*)(xb + off + bj * HALF) = w; }
;                     s += ((o0[0] * o0[0] + o0[1] * o0[1]) + (o0[2] * o0[2] + o0[3] * o0[3])) + ((o1[0] * o1[0] + o1[1] * o1[1]) + (o1[2] * o1[2] + o1[3] * o1[3]));
;                 }
;                 if (ssp) { s += __shfl_xor(s, 16); s += __shfl_xor(s, 32); if (fq == 0) ssp[(size_t)row * 16 + u.pn * 4 + wc] = s; }
.LBB0_1053:
	v_add_u32_e32 v100, 0x80, v168
	v_ashrrev_i32_e32 v101, 31, v100
	v_add_u32_e32 v96, 0x90, v168
	v_add_u32_e32 v92, 0xa0, v168
	v_lshlrev_b64 v[110:111], 11, v[100:101]
	v_add_u32_e32 v88, 0xb0, v168
	v_ashrrev_i32_e32 v97, 31, v96
	v_ashrrev_i32_e32 v93, 31, v92
	s_waitcnt lgkmcnt(0)
	v_lshl_add_u64 v[64:65], v[170:171], 0, v[110:111]
	v_ashrrev_i32_e32 v89, 31, v88
	v_lshlrev_b64 v[98:99], 11, v[96:97]
	v_lshlrev_b64 v[94:95], 11, v[92:93]
	global_load_dwordx4 v[102:105], v[64:65], off
	global_load_dwordx4 v[106:109], v[64:65], off offset:256
	v_lshlrev_b64 v[90:91], 11, v[88:89]
	v_lshl_add_u64 v[64:65], v[170:171], 0, v[98:99]
	v_lshl_add_u64 v[66:67], v[170:171], 0, v[94:95]
	v_lshl_add_u64 v[112:113], v[170:171], 0, v[90:91]
	global_load_dwordx4 v[84:87], v[64:65], off
	global_load_dwordx4 v[80:83], v[64:65], off offset:256
	global_load_dwordx4 v[76:79], v[66:67], off
	global_load_dwordx4 v[72:75], v[66:67], off offset:256
	global_load_dwordx4 v[68:71], v[112:113], off
	s_nop 0
	global_load_dwordx4 v[64:67], v[112:113], off offset:256
	v_readlane_b32 s2, v235, 38
	v_readlane_b32 s3, v235, 39
	s_and_b64 vcc, exec, s[8:9]
	s_waitcnt vmcnt(7)
	v_lshlrev_b32_e32 v112, 16, v102
	v_lshl_add_u64 v[110:111], s[2:3], 0, v[110:111]
	v_and_b32_e32 v113, 0xffff0000, v102
	v_lshlrev_b32_e32 v102, 16, v103
	v_and_b32_e32 v103, 0xffff0000, v103
	v_lshlrev_b32_e32 v114, 16, v104
	v_and_b32_e32 v115, 0xffff0000, v104
	v_lshlrev_b32_e32 v104, 16, v105
	v_and_b32_e32 v105, 0xffff0000, v105
	s_waitcnt vmcnt(6)
	v_lshlrev_b32_e32 v116, 16, v106
	v_and_b32_e32 v117, 0xffff0000, v106
	v_lshlrev_b32_e32 v106, 16, v107
	v_and_b32_e32 v107, 0xffff0000, v107
	v_lshlrev_b32_e32 v118, 16, v108
	v_and_b32_e32 v119, 0xffff0000, v108
	v_lshlrev_b32_e32 v108, 16, v109
	v_and_b32_e32 v109, 0xffff0000, v109
	v_lshl_add_u64 v[110:111], v[166:167], 1, v[110:111]
	v_pk_fma_f32 v[62:63], v[62:63], 0.5, v[102:103] op_sel_hi:[1,0,1]
	v_pk_fma_f32 v[60:61], v[60:61], 0.5, v[112:113] op_sel_hi:[1,0,1]
	v_pk_fma_f32 v[58:59], v[58:59], 0.5, v[104:105] op_sel_hi:[1,0,1]
	v_pk_fma_f32 v[56:57], v[56:57], 0.5, v[114:115] op_sel_hi:[1,0,1]
	v_pk_fma_f32 v[54:55], v[54:55], 0.5, v[106:107] op_sel_hi:[1,0,1]
	v_pk_fma_f32 v[52:53], v[52:53], 0.5, v[116:117] op_sel_hi:[1,0,1]
	v_pk_fma_f32 v[50:51], v[50:51], 0.5, v[108:109] op_sel_hi:[1,0,1]
	v_pk_fma_f32 v[48:49], v[48:49], 0.5, v[118:119] op_sel_hi:[1,0,1]
	v_cvt_pk_bf16_f32 v102, v60, v61
	v_cvt_pk_bf16_f32 v103, v62, v63
	v_cvt_pk_bf16_f32 v104, v56, v57
	v_cvt_pk_bf16_f32 v105, v58, v59
	global_store_dwordx4 v[110:111], v[102:105], off
	s_nop 1
	v_cvt_pk_bf16_f32 v102, v52, v53
	v_cvt_pk_bf16_f32 v103, v54, v55
	v_cvt_pk_bf16_f32 v104, v48, v49
	v_cvt_pk_bf16_f32 v105, v50, v51
	global_store_dwordx4 v[110:111], v[102:105], off offset:256
	s_cbranch_vccnz .LBB0_1057
	v_mul_f32_e32 v49, v49, v49
	v_mul_f32_e32 v61, v61, v61
	v_mul_f32_e32 v57, v57, v57
	v_mul_f32_e32 v53, v53, v53
	v_fmac_f32_e32 v49, v48, v48
	v_mul_f32_e32 v48, v51, v51
	v_fmac_f32_e32 v61, v60, v60
	v_mul_f32_e32 v60, v63, v63
	v_fmac_f32_e32 v57, v56, v56
	v_mul_f32_e32 v56, v59, v59
	v_fmac_f32_e32 v53, v52, v52
	v_mul_f32_e32 v52, v55, v55
	v_fmac_f32_e32 v48, v50, v50
	v_and_b32_e32 v50, 64, v191
	v_fmac_f32_e32 v60, v62, v62
	v_fmac_f32_e32 v56, v58, v58
	v_fmac_f32_e32 v52, v54, v54
	v_add_f32_e32 v48, v49, v48
	v_add_u32_e32 v50, 64, v50
	v_add_f32_e32 v60, v61, v60
	v_add_f32_e32 v56, v57, v56
	v_add_f32_e32 v52, v53, v52
	v_add_f32_e32 v56, v60, v56
	v_add_f32_e32 v48, v52, v48
	v_add_f32_e32 v48, v56, v48
	v_mov_b32_e32 v236, v48
	s_nop 1
	v_permlane16_swap_b32_e32 v48, v236
	s_waitcnt lgkmcnt(0)
	v_add_f32_e32 v48, v48, v236
	s_nop 1
	v_mov_b32_e32 v236, v48
	s_nop 1
	v_permlane32_swap_b32_e32 v48, v236
	s_and_saveexec_b64 s[2:3], s[4:5]
	s_cbranch_execz .LBB0_1056
	v_readlane_b32 s22, v235, 50
	v_lshlrev_b64 v[50:51], 6, v[100:101]
	v_readlane_b32 s23, v235, 51
	s_lshl_b32 s10, s29, 2
	s_waitcnt lgkmcnt(0)
	v_add_f32_e32 v48, v48, v236
	v_lshl_add_u64 v[50:51], s[22:23], 0, v[50:51]
	v_lshl_add_u64 v[50:51], s[20:21], 2, v[50:51]
	v_lshl_add_u64 v[50:51], v[50:51], 0, s[10:11]
	global_store_dword v[50:51], v48, off

; __device__ __forceinline__ unsigned cvt_pk_bf16(float lo, float hi) { unsigned r; asm volatile("v_cvt_pk_bf16_f32 %0, %1, %2" : "=v"(r) : "v"(lo), "v"(hi)); return r; }
; __device__ __forceinline__ float bf_lo(unsigned w) { return __uint_as_float(w << 16); }
; __device__ __forceinline__ float bf_hi(unsigned w) { return __uint_as_float(w & 0xffff0000u); }
;     __device__ __forceinline__ void operator()(const f32x4 (&acc)[2][2][4][2], const Unit& u, int wr, int wc, int fr, int fq) const {
;     ...
;             for (int mm = 0; mm < RB; ++mm) { const size_t off = (size_t)(row0 + ai * HALF + (mh + mm) * 16) * D_MODEL + col0;
; #pragma unroll
;                 for (int bj = 0; bj < 2; ++bj) {
;                     if (BASE_F32) { bf[mm][bj][0] = *(const f32x4*)(basef + off + bj * HALF); bf[mm][bj][1] = *(const f32x4*)(basef + off + bj * HALF + 4); }
;                     else bb[mm][bj] = *(const u32x4*)(xb + off + bj * HALF);
;                 } }
;             asm volatile("" ::: "memory");
; #pragma unroll
;             for (int mm = 0; mm < RB; ++mm) {
;                 const int m = mh + mm;
;                 const int row = row0 + ai * HALF + m * 16; const size_t off = (size_t)row * D_MODEL + col0; float s = 0.f;
; #pragma unroll
;                 for (int bj = 0; bj < 2; ++bj) {
;                     f32x4 b0, b1;
;                     if (BASE_F32) { b0 = bf[mm][bj][0]; b1 = bf[mm][bj][1]; }
;                     else { const u32x4 w = bb[mm][bj]; b0 = (f32x4){bf_lo(w.x), bf_hi(w.x), bf_lo(w.y), bf_hi(w.y)}; b1 = (f32x4){bf_lo(w.z), bf_hi(w.z), bf_lo(w.w), bf_hi(w.w)}; }
;                     const f32x4 o0 = b0 + acc[ai][bj][m][0] * alpha, o1 = b1 + acc[ai][bj][m][1] * alpha;
;                     if (OUT_F32) { *(f32x4*)(out + off + bj * HALF) = o0; *(f32x4*)(out + off + bj * HALF + 4) = o1; }
;                     else { u32x4 w; w.x = cvt_pk_bf16(o0[0], o0[1]); w.y = cvt_pk_bf16(o0[2], o0[3]); w.z = cvt_pk_bf16(o1[0], o1[1]); w.w = cvt_pk_bf16(o1[2], o1[3]); *(u32x4*)(xb + off + bj * HALF) = w; }
;                     s += ((o0[0] * o0[0] + o0[1] * o0[1]) + (o0[2] * o0[2] + o0[3] * o0[3])) + ((o1[0] * o1[0] + o1[1] * o1[1]) + (o1[2] * o1[2] + o1[3] * o1[3]));
;                 }
;                 if (ssp) { s += __shfl_xor(s, 16); s += __shfl_xor(s, 32); if (fq == 0) ssp[(size_t)row * 16 + u.pn * 4 + wc] = s; }
.LBB0_1057:
	v_readlane_b32 s2, v235, 38
	s_waitcnt vmcnt(7)
	v_lshlrev_b32_e32 v52, 16, v86
	v_and_b32_e32 v53, 0xffff0000, v86
	v_readlane_b32 s3, v235, 39
	v_lshlrev_b32_e32 v48, 16, v84
	s_waitcnt lgkmcnt(0)
	v_and_b32_e32 v49, 0xffff0000, v84
	v_lshlrev_b32_e32 v50, 16, v85
	v_and_b32_e32 v51, 0xffff0000, v85
	v_lshlrev_b32_e32 v54, 16, v87
	v_and_b32_e32 v55, 0xffff0000, v87
	v_pk_fma_f32 v[40:41], v[40:41], 0.5, v[52:53] op_sel_hi:[1,0,1]
	v_lshl_add_u64 v[52:53], s[2:3], 0, v[98:99]
	v_pk_fma_f32 v[46:47], v[46:47], 0.5, v[50:51] op_sel_hi:[1,0,1]
	v_pk_fma_f32 v[44:45], v[44:45], 0.5, v[48:49] op_sel_hi:[1,0,1]
	v_pk_fma_f32 v[42:43], v[42:43], 0.5, v[54:55] op_sel_hi:[1,0,1]
	v_cvt_pk_bf16_f32 v48, v44, v45
	v_cvt_pk_bf16_f32 v49, v46, v47
	v_cvt_pk_bf16_f32 v50, v40, v41
	v_lshl_add_u64 v[52:53], v[166:167], 1, v[52:53]
	v_cvt_pk_bf16_f32 v51, v42, v43
	global_store_dwordx4 v[52:53], v[48:51], off
	s_waitcnt vmcnt(7)
	v_lshlrev_b32_e32 v54, 16, v82
	v_and_b32_e32 v55, 0xffff0000, v82
	v_lshlrev_b32_e32 v48, 16, v80
	v_and_b32_e32 v49, 0xffff0000, v80
	v_lshlrev_b32_e32 v50, 16, v81
	v_and_b32_e32 v51, 0xffff0000, v81
	v_lshlrev_b32_e32 v56, 16, v83
	v_and_b32_e32 v57, 0xffff0000, v83
	v_pk_fma_f32 v[38:39], v[38:39], 0.5, v[50:51] op_sel_hi:[1,0,1]
	v_pk_fma_f32 v[36:37], v[36:37], 0.5, v[48:49] op_sel_hi:[1,0,1]
	v_pk_fma_f32 v[34:35], v[34:35], 0.5, v[56:57] op_sel_hi:[1,0,1]
	v_pk_fma_f32 v[32:33], v[32:33], 0.5, v[54:55] op_sel_hi:[1,0,1]
	s_and_b64 vcc, exec, s[8:9]
	v_cvt_pk_bf16_f32 v48, v36, v37
	v_cvt_pk_bf16_f32 v49, v38, v39
	v_cvt_pk_bf16_f32 v50, v32, v33
	v_cvt_pk_bf16_f32 v51, v34, v35
	global_store_dwordx4 v[52:53], v[48:51], off offset:256
	s_cbranch_vccnz .LBB0_1061
	v_mul_f32_e32 v33, v33, v33
	v_mul_f32_e32 v45, v45, v45
	v_mul_f32_e32 v41, v41, v41
	v_mul_f32_e32 v37, v37, v37
	v_fmac_f32_e32 v33, v32, v32
	v_mul_f32_e32 v32, v35, v35
	v_fmac_f32_e32 v45, v44, v44
	v_mul_f32_e32 v44, v47, v47
	v_fmac_f32_e32 v41, v40, v40
	v_mul_f32_e32 v40, v43, v43
	v_fmac_f32_e32 v37, v36, v36
	v_mul_f32_e32 v36, v39, v39
	v_fmac_f32_e32 v32, v34, v34
	v_and_b32_e32 v34, 64, v191
	v_fmac_f32_e32 v44, v46, v46
	v_fmac_f32_e32 v40, v42, v42
	v_fmac_f32_e32 v36, v38, v38
	v_add_f32_e32 v32, v33, v32
	v_add_u32_e32 v34, 64, v34
	v_add_f32_e32 v44, v45, v44
	v_add_f32_e32 v40, v41, v40
	v_add_f32_e32 v36, v37, v36
	v_add_f32_e32 v40, v44, v40
	v_add_f32_e32 v32, v36, v32
	v_add_f32_e32 v32, v40, v32
	v_mov_b32_e32 v236, v32
	s_nop 1
	v_permlane16_swap_b32_e32 v32, v236
	s_waitcnt lgkmcnt(0)
	v_add_f32_e32 v32, v32, v236
	s_nop 1
	v_mov_b32_e32 v236, v32
	s_nop 1
	v_permlane32_swap_b32_e32 v32, v236
	s_and_saveexec_b64 s[2:3], s[4:5]
	s_cbranch_execz .LBB0_1060
	v_readlane_b32 s22, v235, 50
	v_lshlrev_b64 v[34:35], 6, v[96:97]
	v_readlane_b32 s23, v235, 51
	s_lshl_b32 s10, s29, 2
	s_waitcnt lgkmcnt(0)
	v_add_f32_e32 v32, v32, v236
	v_lshl_add_u64 v[34:35], s[22:23], 0, v[34:35]
	v_lshl_add_u64 v[34:35], s[20:21], 2, v[34:35]
	v_lshl_add_u64 v[34:35], v[34:35], 0, s[10:11]
	global_store_dword v[34:35], v32, off

; __device__ __forceinline__ unsigned cvt_pk_bf16(float lo, float hi) { unsigned r; asm volatile("v_cvt_pk_bf16_f32 %0, %1, %2" : "=v"(r) : "v"(lo), "v"(hi)); return r; }
; __device__ __forceinline__ float bf_lo(unsigned w) { return __uint_as_float(w << 16); }
; __device__ __forceinline__ float bf_hi(unsigned w) { return __uint_as_float(w & 0xffff0000u); }
;     __device__ __forceinline__ void operator()(const f32x4 (&acc)[2][2][4][2], const Unit& u, int wr, int wc, int fr, int fq) const {
;     ...
;             for (int mm = 0; mm < RB; ++mm) { const size_t off = (size_t)(row0 + ai * HALF + (mh + mm) * 16) * D_MODEL + col0;
; #pragma unroll
;                 for (int bj = 0; bj < 2; ++bj) {
;                     if (BASE_F32) { bf[mm][bj][0] = *(const f32x4*)(basef + off + bj * HALF); bf[mm][bj][1] = *(const f32x4*)(basef + off + bj * HALF + 4); }
;                     else bb[mm][bj] = *(const u32x4*)(xb + off + bj * HALF);
;                 } }
;             asm volatile("" ::: "memory");
; #pragma unroll
;             for (int mm = 0; mm < RB; ++mm) {
;                 const int m = mh + mm;
;                 const int row = row0 + ai * HALF + m * 16; const size_t off = (size_t)row * D_MODEL + col0; float s = 0.f;
; #pragma unroll
;                 for (int bj = 0; bj < 2; ++bj) {
;                     f32x4 b0, b1;
;                     if (BASE_F32) { b0 = bf[mm][bj][0]; b1 = bf[mm][bj][1]; }
;                     else { const u32x4 w = bb[mm][bj]; b0 = (f32x4){bf_lo(w.x), bf_hi(w.x), bf_lo(w.y), bf_hi(w.y)}; b1 = (f32x4){bf_lo(w.z), bf_hi(w.z), bf_lo(w.w), bf_hi(w.w)}; }
;                     const f32x4 o0 = b0 + acc[ai][bj][m][0] * alpha, o1 = b1 + acc[ai][bj][m][1] * alpha;
;                     if (OUT_F32) { *(f32x4*)(out + off + bj * HALF) = o0; *(f32x4*)(out + off + bj * HALF + 4) = o1; }
;                     else { u32x4 w; w.x = cvt_pk_bf16(o0[0], o0[1]); w.y = cvt_pk_bf16(o0[2], o0[3]); w.z = cvt_pk_bf16(o1[0], o1[1]); w.w = cvt_pk_bf16(o1[2], o1[3]); *(u32x4*)(xb + off + bj * HALF) = w; }
;                     s += ((o0[0] * o0[0] + o0[1] * o0[1]) + (o0[2] * o0[2] + o0[3] * o0[3])) + ((o1[0] * o1[0] + o1[1] * o1[1]) + (o1[2] * o1[2] + o1[3] * o1[3]));
;                 }
;                 if (ssp) { s += __shfl_xor(s, 16); s += __shfl_xor(s, 32); if (fq == 0) ssp[(size_t)row * 16 + u.pn * 4 + wc] = s; }
.LBB0_1061:
	v_readlane_b32 s2, v235, 38
	s_waitcnt vmcnt(7)
	v_lshlrev_b32_e32 v36, 16, v78
	v_and_b32_e32 v37, 0xffff0000, v78
	v_readlane_b32 s3, v235, 39
	v_lshlrev_b32_e32 v32, 16, v76
	s_waitcnt lgkmcnt(0)
	v_and_b32_e32 v33, 0xffff0000, v76
	v_lshlrev_b32_e32 v34, 16, v77
	v_and_b32_e32 v35, 0xffff0000, v77
	v_lshlrev_b32_e32 v38, 16, v79
	v_and_b32_e32 v39, 0xffff0000, v79
	v_pk_fma_f32 v[24:25], v[24:25], 0.5, v[36:37] op_sel_hi:[1,0,1]
	v_lshl_add_u64 v[36:37], s[2:3], 0, v[94:95]
	v_pk_fma_f32 v[30:31], v[30:31], 0.5, v[34:35] op_sel_hi:[1,0,1]
	v_pk_fma_f32 v[28:29], v[28:29], 0.5, v[32:33] op_sel_hi:[1,0,1]
	v_pk_fma_f32 v[26:27], v[26:27], 0.5, v[38:39] op_sel_hi:[1,0,1]
	v_cvt_pk_bf16_f32 v32, v28, v29
	v_cvt_pk_bf16_f32 v33, v30, v31
	v_cvt_pk_bf16_f32 v34, v24, v25
	v_lshl_add_u64 v[36:37], v[166:167], 1, v[36:37]
	v_cvt_pk_bf16_f32 v35, v26, v27
	global_store_dwordx4 v[36:37], v[32:35], off
	s_waitcnt vmcnt(7)
	v_lshlrev_b32_e32 v38, 16, v74
	v_and_b32_e32 v39, 0xffff0000, v74
	v_lshlrev_b32_e32 v32, 16, v72
	v_and_b32_e32 v33, 0xffff0000, v72
	v_lshlrev_b32_e32 v34, 16, v73
	v_and_b32_e32 v35, 0xffff0000, v73
	v_lshlrev_b32_e32 v40, 16, v75
	v_and_b32_e32 v41, 0xffff0000, v75
	v_pk_fma_f32 v[22:23], v[22:23], 0.5, v[34:35] op_sel_hi:[1,0,1]
	v_pk_fma_f32 v[20:21], v[20:21], 0.5, v[32:33] op_sel_hi:[1,0,1]
	v_pk_fma_f32 v[18:19], v[18:19], 0.5, v[40:41] op_sel_hi:[1,0,1]
	v_pk_fma_f32 v[16:17], v[16:17], 0.5, v[38:39] op_sel_hi:[1,0,1]
	s_and_b64 vcc, exec, s[8:9]
	v_cvt_pk_bf16_f32 v32, v20, v21
	v_cvt_pk_bf16_f32 v33, v22, v23
	v_cvt_pk_bf16_f32 v34, v16, v17
	v_cvt_pk_bf16_f32 v35, v18, v19
	global_store_dwordx4 v[36:37], v[32:35], off offset:256
	s_cbranch_vccnz .LBB0_1065
	v_mul_f32_e32 v17, v17, v17
	v_mul_f32_e32 v29, v29, v29
	v_mul_f32_e32 v25, v25, v25
	v_mul_f32_e32 v21, v21, v21
	v_fmac_f32_e32 v17, v16, v16
	v_mul_f32_e32 v16, v19, v19
	v_fmac_f32_e32 v29, v28, v28
	v_mul_f32_e32 v28, v31, v31
	v_fmac_f32_e32 v25, v24, v24
	v_mul_f32_e32 v24, v27, v27
	v_fmac_f32_e32 v21, v20, v20
	v_mul_f32_e32 v20, v23, v23
	v_fmac_f32_e32 v16, v18, v18
	v_and_b32_e32 v18, 64, v191
	v_fmac_f32_e32 v28, v30, v30
	v_fmac_f32_e32 v24, v26, v26
	v_fmac_f32_e32 v20, v22, v22
	v_add_f32_e32 v16, v17, v16
	v_add_u32_e32 v18, 64, v18
	v_add_f32_e32 v28, v29, v28
	v_add_f32_e32 v24, v25, v24
	v_add_f32_e32 v20, v21, v20
	v_add_f32_e32 v24, v28, v24
	v_add_f32_e32 v16, v20, v16
	v_add_f32_e32 v16, v24, v16
	v_mov_b32_e32 v236, v16
	s_nop 1
	v_permlane16_swap_b32_e32 v16, v236
	s_waitcnt lgkmcnt(0)
	v_add_f32_e32 v16, v16, v236
	s_nop 1
	v_mov_b32_e32 v236, v16
	s_nop 1
	v_permlane32_swap_b32_e32 v16, v236
	s_and_saveexec_b64 s[2:3], s[4:5]
	s_cbranch_execz .LBB0_1064
	v_readlane_b32 s22, v235, 50
	v_lshlrev_b64 v[18:19], 6, v[92:93]
	v_readlane_b32 s23, v235, 51
	s_lshl_b32 s10, s29, 2
	s_waitcnt lgkmcnt(0)
	v_add_f32_e32 v16, v16, v236
	v_lshl_add_u64 v[18:19], s[22:23], 0, v[18:19]
	v_lshl_add_u64 v[18:19], s[20:21], 2, v[18:19]
	v_lshl_add_u64 v[18:19], v[18:19], 0, s[10:11]
	global_store_dword v[18:19], v16, off

; __device__ __forceinline__ unsigned cvt_pk_bf16(float lo, float hi) { unsigned r; asm volatile("v_cvt_pk_bf16_f32 %0, %1, %2" : "=v"(r) : "v"(lo), "v"(hi)); return r; }
; __device__ __forceinline__ float bf_lo(unsigned w) { return __uint_as_float(w << 16); }
; __device__ __forceinline__ float bf_hi(unsigned w) { return __uint_as_float(w & 0xffff0000u); }
;     __device__ __forceinline__ void operator()(const f32x4 (&acc)[2][2][4][2], const Unit& u, int wr, int wc, int fr, int fq) const {
;     ...
;             for (int mm = 0; mm < RB; ++mm) { const size_t off = (size_t)(row0 + ai * HALF + (mh + mm) * 16) * D_MODEL + col0;
; #pragma unroll
;                 for (int bj = 0; bj < 2; ++bj) {
;                     if (BASE_F32) { bf[mm][bj][0] = *(const f32x4*)(basef + off + bj * HALF); bf[mm][bj][1] = *(const f32x4*)(basef + off + bj * HALF + 4); }
;                     else bb[mm][bj] = *(const u32x4*)(xb + off + bj * HALF);
;                 } }
;             asm volatile("" ::: "memory");
; #pragma unroll
;             for (int mm = 0; mm < RB; ++mm) {
;                 const int m = mh + mm;
;                 const int row = row0 + ai * HALF + m * 16; const size_t off = (size_t)row * D_MODEL + col0; float s = 0.f;
; #pragma unroll
;                 for (int bj = 0; bj < 2; ++bj) {
;                     f32x4 b0, b1;
;                     if (BASE_F32) { b0 = bf[mm][bj][0]; b1 = bf[mm][bj][1]; }
;                     else { const u32x4 w = bb[mm][bj]; b0 = (f32x4){bf_lo(w.x), bf_hi(w.x), bf_lo(w.y), bf_hi(w.y)}; b1 = (f32x4){bf_lo(w.z), bf_hi(w.z), bf_lo(w.w), bf_hi(w.w)}; }
;                     const f32x4 o0 = b0 + acc[ai][bj][m][0] * alpha, o1 = b1 + acc[ai][bj][m][1] * alpha;
;                     if (OUT_F32) { *(f32x4*)(out + off + bj * HALF) = o0; *(f32x4*)(out + off + bj * HALF + 4) = o1; }
;                     else { u32x4 w; w.x = cvt_pk_bf16(o0[0], o0[1]); w.y = cvt_pk_bf16(o0[2], o0[3]); w.z = cvt_pk_bf16(o1[0], o1[1]); w.w = cvt_pk_bf16(o1[2], o1[3]); *(u32x4*)(xb + off + bj * HALF) = w; }
;                     s += ((o0[0] * o0[0] + o0[1] * o0[1]) + (o0[2] * o0[2] + o0[3] * o0[3])) + ((o1[0] * o1[0] + o1[1] * o1[1]) + (o1[2] * o1[2] + o1[3] * o1[3]));
;                 }
;                 if (ssp) { s += __shfl_xor(s, 16); s += __shfl_xor(s, 32); if (fq == 0) ssp[(size_t)row * 16 + u.pn * 4 + wc] = s; }
.LBB0_1065:
	v_readlane_b32 s2, v235, 38
	s_waitcnt vmcnt(7)
	v_lshlrev_b32_e32 v20, 16, v70
	v_and_b32_e32 v21, 0xffff0000, v70
	v_readlane_b32 s3, v235, 39
	v_lshlrev_b32_e32 v16, 16, v68
	s_waitcnt lgkmcnt(0)
	v_and_b32_e32 v17, 0xffff0000, v68
	v_lshlrev_b32_e32 v18, 16, v69
	v_and_b32_e32 v19, 0xffff0000, v69
	v_lshlrev_b32_e32 v22, 16, v71
	v_and_b32_e32 v23, 0xffff0000, v71
	v_pk_fma_f32 v[8:9], v[8:9], 0.5, v[20:21] op_sel_hi:[1,0,1]
	v_lshl_add_u64 v[20:21], s[2:3], 0, v[90:91]
	v_pk_fma_f32 v[14:15], v[14:15], 0.5, v[18:19] op_sel_hi:[1,0,1]
	v_pk_fma_f32 v[12:13], v[12:13], 0.5, v[16:17] op_sel_hi:[1,0,1]
	v_pk_fma_f32 v[10:11], v[10:11], 0.5, v[22:23] op_sel_hi:[1,0,1]
	v_cvt_pk_bf16_f32 v16, v12, v13
	v_cvt_pk_bf16_f32 v17, v14, v15
	v_cvt_pk_bf16_f32 v18, v8, v9
	v_lshl_add_u64 v[20:21], v[166:167], 1, v[20:21]
	v_cvt_pk_bf16_f32 v19, v10, v11
	global_store_dwordx4 v[20:21], v[16:19], off
	s_waitcnt vmcnt(7)
	v_lshlrev_b32_e32 v22, 16, v66
	v_and_b32_e32 v23, 0xffff0000, v66
	v_lshlrev_b32_e32 v16, 16, v64
	v_and_b32_e32 v17, 0xffff0000, v64
	v_lshlrev_b32_e32 v18, 16, v65
	v_and_b32_e32 v19, 0xffff0000, v65
	v_lshlrev_b32_e32 v24, 16, v67
	v_and_b32_e32 v25, 0xffff0000, v67
	v_pk_fma_f32 v[6:7], v[6:7], 0.5, v[18:19] op_sel_hi:[1,0,1]
	v_pk_fma_f32 v[4:5], v[4:5], 0.5, v[16:17] op_sel_hi:[1,0,1]
	v_pk_fma_f32 v[2:3], v[2:3], 0.5, v[24:25] op_sel_hi:[1,0,1]
	v_pk_fma_f32 v[0:1], v[0:1], 0.5, v[22:23] op_sel_hi:[1,0,1]
	s_and_b64 vcc, exec, s[8:9]
	v_cvt_pk_bf16_f32 v16, v4, v5
	v_cvt_pk_bf16_f32 v17, v6, v7
	v_cvt_pk_bf16_f32 v18, v0, v1
	v_cvt_pk_bf16_f32 v19, v2, v3
	global_store_dwordx4 v[20:21], v[16:19], off offset:256
	s_cbranch_vccnz .LBB0_1069
	v_mul_f32_e32 v1, v1, v1
	v_mul_f32_e32 v13, v13, v13
	v_mul_f32_e32 v9, v9, v9
	v_mul_f32_e32 v5, v5, v5
	v_fmac_f32_e32 v1, v0, v0
	v_mul_f32_e32 v0, v3, v3
	v_fmac_f32_e32 v13, v12, v12
	v_mul_f32_e32 v12, v15, v15
	v_fmac_f32_e32 v9, v8, v8
	v_mul_f32_e32 v8, v11, v11
	v_fmac_f32_e32 v5, v4, v4
	v_mul_f32_e32 v4, v7, v7
	v_fmac_f32_e32 v0, v2, v2
	v_and_b32_e32 v2, 64, v191
	v_fmac_f32_e32 v12, v14, v14
	v_fmac_f32_e32 v8, v10, v10
	v_fmac_f32_e32 v4, v6, v6
	v_add_f32_e32 v0, v1, v0
	v_add_u32_e32 v2, 64, v2
	v_add_f32_e32 v12, v13, v12
	v_add_f32_e32 v8, v9, v8
	v_add_f32_e32 v4, v5, v4
	v_add_f32_e32 v8, v12, v8
	v_add_f32_e32 v0, v4, v0
	v_add_f32_e32 v0, v8, v0
	v_mov_b32_e32 v236, v0
	s_nop 1
	v_permlane16_swap_b32_e32 v0, v236
	s_waitcnt lgkmcnt(0)
	v_add_f32_e32 v0, v0, v236
	s_nop 1
	v_mov_b32_e32 v236, v0
	s_nop 1
	v_permlane32_swap_b32_e32 v0, v236
	s_and_saveexec_b64 s[2:3], s[4:5]
	s_cbranch_execz .LBB0_1068
	v_readlane_b32 s8, v235, 50
	v_lshlrev_b64 v[2:3], 6, v[88:89]
	v_readlane_b32 s9, v235, 51
	s_lshl_b32 s10, s29, 2
	s_waitcnt lgkmcnt(0)
	v_add_f32_e32 v0, v0, v236
	v_lshl_add_u64 v[2:3], s[8:9], 0, v[2:3]
	v_lshl_add_u64 v[2:3], s[20:21], 2, v[2:3]
	v_lshl_add_u64 v[2:3], v[2:3], 0, s[10:11]
	global_store_dword v[2:3], v0, off

; __device__ __forceinline__ float bf_lo(unsigned w) { return __uint_as_float(w << 16); }
; __device__ __forceinline__ float bf_hi(unsigned w) { return __uint_as_float(w & 0xffff0000u); }
;     __device__ __forceinline__ void operator()(const f32x4 (&acc)[2][2][4][2], const Unit& u, int wr, int wc, int fr, int fq) const {
;     ...
;         for (int ai = 0; ai < 2; ++ai) {
;             u32x4 bb[4][2];
; #pragma unroll
;             for (int m = 0; m < 4; ++m)
; #pragma unroll
;                 for (int bj = 0; bj < 2; ++bj) bb[m][bj] = *(const u32x4*)(xb + (size_t)(row0 + ai * HALF + m * 16) * D_MODEL + col0 + bj * HALF);
; #pragma unroll
;             for (int m = 0; m < 4; ++m) { float s = 0.f;
; #pragma unroll
;                 for (int bj = 0; bj < 2; ++bj) { const u32x4 w = bb[m][bj];
;                     const f32x4 o0 = (f32x4){bf_lo(w.x), bf_hi(w.x), bf_lo(w.y), bf_hi(w.y)} + acc[ai][bj][m][0] * alpha, o1 = (f32x4){bf_lo(w.z), bf_hi(w.z), bf_lo(w.w), bf_hi(w.w)} + acc[ai][bj][m][1] * alpha;
;                     o[ai][m][bj][0] = o0; o[ai][m][bj][1] = o1;
;                     s += ((o0[0] * o0[0] + o0[1] * o0[1]) + (o0[2] * o0[2] + o0[3] * o0[3])) + ((o1[0] * o1[0] + o1[1] * o1[1]) + (o1[2] * o1[2] + o1[3] * o1[3])); }
;                 s += __shfl_xor(s, 16); s += __shfl_xor(s, 32);
;                 if (fq == 0) ssp[(size_t)(row0 + ai * HALF + m * 16) * 16 + u.pn * 4 + wc] = s; }
.LBB0_1180:
	s_mov_b32 s98, 0xffff0000
	s_mov_b32 s99, 0xffff0000
	s_mov_b32 s100, 0
	s_mov_b32 s101, -1
	v_lshl_add_u32 v176, s42, 8, v197
	v_lshl_or_b32 v174, s43, 8, v199
	v_readlane_b32 s2, v235, 38
	v_ashrrev_i32_e32 v175, 31, v174
	v_readlane_b32 s3, v235, 39
	v_ashrrev_i32_e32 v177, 31, v176
	v_lshlrev_b64 v[128:129], 11, v[176:177]
	v_lshl_add_u64 v[194:195], v[174:175], 1, s[2:3]
	v_lshl_add_u64 v[128:129], v[194:195], 0, v[128:129]
	global_load_dwordx4 v[178:181], v[128:129], off
	global_load_dwordx4 v[182:185], v[128:129], off offset:256
	v_or_b32_e32 v172, 16, v176
	v_or_b32_e32 v170, 32, v176
	v_or_b32_e32 v168, 48, v176
	v_ashrrev_i32_e32 v173, 31, v172
	v_ashrrev_i32_e32 v171, 31, v170
	v_ashrrev_i32_e32 v169, 31, v168
	v_lshlrev_b64 v[128:129], 11, v[172:173]
	v_lshlrev_b64 v[130:131], 11, v[170:171]
	v_lshlrev_b64 v[132:133], 11, v[168:169]
	v_lshl_add_u64 v[128:129], v[194:195], 0, v[128:129]
	v_lshl_add_u64 v[130:131], v[194:195], 0, v[130:131]
	v_lshl_add_u64 v[186:187], v[194:195], 0, v[132:133]
	global_load_dwordx4 v[148:151], v[128:129], off
	global_load_dwordx4 v[144:147], v[128:129], off offset:256
	global_load_dwordx4 v[140:143], v[130:131], off
	global_load_dwordx4 v[136:139], v[130:131], off offset:256
	global_load_dwordx4 v[132:135], v[186:187], off
	s_nop 0
	global_load_dwordx4 v[128:131], v[186:187], off offset:256
	v_and_b32_e32 v187, 64, v203
	v_xor_b32_e32 v186, 16, v203
	v_add_u32_e32 v207, 64, v187
	v_cmp_lt_i32_e32 vcc, v186, v207
	v_xor_b32_e32 v206, 32, v203
	s_lshl_b32 s2, s43, 2
	v_cndmask_b32_e32 v186, v203, v186, vcc
	v_lshlrev_b32_e32 v205, 2, v186
	v_cmp_lt_i32_e32 vcc, v206, v207
	s_ashr_i32 s3, s2, 31
	s_lshl_b64 s[2:3], s[2:3], 2
	s_add_u32 s2, s36, s2
	s_addc_u32 s3, s37, s3
	s_waitcnt vmcnt(0)
	v_lshlrev_b32_e32 v186, 16, v178
	v_and_b32_e32 v187, 0xffff0000, v178
	v_lshlrev_b32_e32 v178, 16, v179
	v_and_b32_e32 v179, 0xffff0000, v179
	v_lshlrev_b32_e32 v188, 16, v180
	v_and_b32_e32 v189, 0xffff0000, v180
	v_lshlrev_b32_e32 v180, 16, v181
	v_and_b32_e32 v181, 0xffff0000, v181
	v_lshlrev_b32_e32 v190, 16, v182
	v_and_b32_e32 v191, 0xffff0000, v182
	v_lshlrev_b32_e32 v182, 16, v183
	v_and_b32_e32 v183, 0xffff0000, v183
	v_lshlrev_b32_e32 v192, 16, v184
	v_and_b32_e32 v193, 0xffff0000, v184
	v_lshlrev_b32_e32 v184, 16, v185
	v_and_b32_e32 v185, 0xffff0000, v185
	v_pk_fma_f32 v[126:127], v[126:127], 0.5, v[178:179] op_sel_hi:[1,0,1]
	v_pk_fma_f32 v[124:125], v[124:125], 0.5, v[186:187] op_sel_hi:[1,0,1]
	v_pk_fma_f32 v[122:123], v[122:123], 0.5, v[180:181] op_sel_hi:[1,0,1]
	v_pk_fma_f32 v[120:121], v[120:121], 0.5, v[188:189] op_sel_hi:[1,0,1]
	v_pk_fma_f32 v[118:119], v[118:119], 0.5, v[182:183] op_sel_hi:[1,0,1]
	v_pk_fma_f32 v[116:117], v[116:117], 0.5, v[190:191] op_sel_hi:[1,0,1]
	v_pk_fma_f32 v[114:115], v[114:115], 0.5, v[184:185] op_sel_hi:[1,0,1]
	v_pk_fma_f32 v[112:113], v[112:113], 0.5, v[192:193] op_sel_hi:[1,0,1]
	v_mul_f32_e32 v178, v125, v125
	v_mul_f32_e32 v179, v127, v127
	v_mul_f32_e32 v180, v121, v121
	v_mul_f32_e32 v181, v123, v123
	v_mul_f32_e32 v182, v117, v117
	v_mul_f32_e32 v183, v119, v119
	v_mul_f32_e32 v184, v113, v113
	v_mul_f32_e32 v185, v115, v115
	v_fmac_f32_e32 v178, v124, v124
	v_fmac_f32_e32 v179, v126, v126
	v_fmac_f32_e32 v180, v120, v120
	v_fmac_f32_e32 v181, v122, v122
	v_fmac_f32_e32 v182, v116, v116
	v_fmac_f32_e32 v183, v118, v118
	v_fmac_f32_e32 v184, v112, v112
	v_fmac_f32_e32 v185, v114, v114
	v_add_f32_e32 v178, v178, v179
	v_add_f32_e32 v179, v180, v181
	v_add_f32_e32 v180, v182, v183
	v_add_f32_e32 v181, v184, v185
	v_add_f32_e32 v178, v178, v179
	v_add_f32_e32 v179, v180, v181
	v_add_f32_e32 v178, v178, v179
	v_mov_b32_e32 v236, v178
	s_nop 1
	v_permlane16_swap_b32_e32 v178, v236
	v_cndmask_b32_e32 v180, v203, v206, vcc
	v_lshlrev_b32_e32 v206, 2, v180
	v_lshlrev_b64 v[186:187], 6, v[176:177]
	s_waitcnt lgkmcnt(0)
	v_add_f32_e32 v178, v178, v236
	v_mov_b32_e32 v236, v178
	s_nop 1
	v_permlane32_swap_b32_e32 v178, v236
	s_and_saveexec_b64 s[20:21], s[0:1]
	s_cbranch_execz .LBB0_1182
	s_waitcnt lgkmcnt(0)
	v_add_f32_e32 v180, v178, v236
	v_lshl_add_u64 v[178:179], s[2:3], 0, v[186:187]
	global_store_dword v[178:179], v180, off
.LBB0_1182:
	s_or_b64 exec, exec, s[20:21]
	v_lshlrev_b32_e32 v178, 16, v148
	s_waitcnt lgkmcnt(0)
	v_and_b32_e32 v179, 0xffff0000, v148
	v_lshlrev_b32_e32 v148, 16, v149
	v_and_b32_e32 v149, 0xffff0000, v149
	v_pk_fma_f32 v[110:111], v[110:111], 0.5, v[148:149] op_sel_hi:[1,0,1]
	v_pk_fma_f32 v[108:109], v[108:109], 0.5, v[178:179] op_sel_hi:[1,0,1]
	v_lshlrev_b32_e32 v148, 16, v150
	v_and_b32_e32 v149, 0xffff0000, v150
	v_lshlrev_b32_e32 v150, 16, v151
	v_and_b32_e32 v151, 0xffff0000, v151
	v_pk_fma_f32 v[104:105], v[104:105], 0.5, v[148:149] op_sel_hi:[1,0,1]
	v_mul_f32_e32 v148, v109, v109
	v_mul_f32_e32 v149, v111, v111
	v_pk_fma_f32 v[106:107], v[106:107], 0.5, v[150:151] op_sel_hi:[1,0,1]
	v_fmac_f32_e32 v148, v108, v108
	v_fmac_f32_e32 v149, v110, v110
	v_add_f32_e32 v148, v148, v149
	v_mul_f32_e32 v149, v105, v105
	v_mul_f32_e32 v150, v107, v107
	v_fmac_f32_e32 v149, v104, v104
	v_fmac_f32_e32 v150, v106, v106
	v_add_f32_e32 v149, v149, v150
	v_add_f32_e32 v150, v148, v149
	v_lshlrev_b32_e32 v148, 16, v144
	v_and_b32_e32 v149, 0xffff0000, v144
	v_lshlrev_b32_e32 v144, 16, v145
	v_and_b32_e32 v145, 0xffff0000, v145
	v_pk_fma_f32 v[102:103], v[102:103], 0.5, v[144:145] op_sel_hi:[1,0,1]
	v_pk_fma_f32 v[100:101], v[100:101], 0.5, v[148:149] op_sel_hi:[1,0,1]
	v_lshlrev_b32_e32 v144, 16, v146
	v_and_b32_e32 v145, 0xffff0000, v146
	v_lshlrev_b32_e32 v146, 16, v147
	v_and_b32_e32 v147, 0xffff0000, v147
	v_pk_fma_f32 v[96:97], v[96:97], 0.5, v[144:145] op_sel_hi:[1,0,1]
	v_mul_f32_e32 v144, v101, v101
	v_mul_f32_e32 v145, v103, v103
	v_pk_fma_f32 v[98:99], v[98:99], 0.5, v[146:147] op_sel_hi:[1,0,1]
	v_fmac_f32_e32 v144, v100, v100
	v_fmac_f32_e32 v145, v102, v102
	v_add_f32_e32 v144, v144, v145
	v_mul_f32_e32 v145, v97, v97
	v_mul_f32_e32 v146, v99, v99
	v_fmac_f32_e32 v145, v96, v96
	v_fmac_f32_e32 v146, v98, v98
	v_add_f32_e32 v145, v145, v146
	v_add_f32_e32 v144, v144, v145
	v_add_f32_e32 v144, v150, v144
	v_mov_b32_e32 v236, v144
	s_nop 1
	v_permlane16_swap_b32_e32 v144, v236
	v_lshlrev_b64 v[188:189], 6, v[172:173]
	s_waitcnt lgkmcnt(0)
	v_add_f32_e32 v144, v144, v236
	v_mov_b32_e32 v236, v144
	s_nop 1
	v_permlane32_swap_b32_e32 v144, v236
	s_and_saveexec_b64 s[20:21], s[0:1]
	s_cbranch_execz .LBB0_1184
	s_waitcnt lgkmcnt(0)
	v_add_f32_e32 v146, v144, v236
	v_lshl_add_u64 v[144:145], s[2:3], 0, v[188:189]
	global_store_dword v[144:145], v146, off
; __device__ __forceinline__ float bf_lo(unsigned w) { return __uint_as_float(w << 16); }
; __device__ __forceinline__ float bf_hi(unsigned w) { return __uint_as_float(w & 0xffff0000u); }
;     __device__ __forceinline__ void operator()(const f32x4 (&acc)[2][2][4][2], const Unit& u, int wr, int wc, int fr, int fq) const {
;     ...
;         for (int ai = 0; ai < 2; ++ai) {
;             u32x4 bb[4][2];
; #pragma unroll
;             for (int m = 0; m < 4; ++m)
; #pragma unroll
;                 for (int bj = 0; bj < 2; ++bj) bb[m][bj] = *(const u32x4*)(xb + (size_t)(row0 + ai * HALF + m * 16) * D_MODEL + col0 + bj * HALF);
; #pragma unroll
;             for (int m = 0; m < 4; ++m) { float s = 0.f;
; #pragma unroll
;                 for (int bj = 0; bj < 2; ++bj) { const u32x4 w = bb[m][bj];
;                     const f32x4 o0 = (f32x4){bf_lo(w.x), bf_hi(w.x), bf_lo(w.y), bf_hi(w.y)} + acc[ai][bj][m][0] * alpha, o1 = (f32x4){bf_lo(w.z), bf_hi(w.z), bf_lo(w.w), bf_hi(w.w)} + acc[ai][bj][m][1] * alpha;
;                     o[ai][m][bj][0] = o0; o[ai][m][bj][1] = o1;
;                     s += ((o0[0] * o0[0] + o0[1] * o0[1]) + (o0[2] * o0[2] + o0[3] * o0[3])) + ((o1[0] * o1[0] + o1[1] * o1[1]) + (o1[2] * o1[2] + o1[3] * o1[3])); }
;                 s += __shfl_xor(s, 16); s += __shfl_xor(s, 32);
;                 if (fq == 0) ssp[(size_t)(row0 + ai * HALF + m * 16) * 16 + u.pn * 4 + wc] = s; }
.LBB0_1184:
	s_or_b64 exec, exec, s[20:21]
	v_lshlrev_b32_e32 v144, 16, v140
	s_waitcnt lgkmcnt(0)
	v_and_b32_e32 v145, 0xffff0000, v140
	v_lshlrev_b32_e32 v140, 16, v141
	v_and_b32_e32 v141, 0xffff0000, v141
	v_pk_fma_f32 v[94:95], v[94:95], 0.5, v[140:141] op_sel_hi:[1,0,1]
	v_pk_fma_f32 v[144:145], v[92:93], 0.5, v[144:145] op_sel_hi:[1,0,1]
	v_lshlrev_b32_e32 v92, 16, v142
	v_and_b32_e32 v93, 0xffff0000, v142
	v_lshlrev_b32_e32 v140, 16, v143
	v_and_b32_e32 v141, 0xffff0000, v143
	v_pk_fma_f32 v[90:91], v[90:91], 0.5, v[140:141] op_sel_hi:[1,0,1]
	v_pk_fma_f32 v[140:141], v[88:89], 0.5, v[92:93] op_sel_hi:[1,0,1]
	v_mul_f32_e32 v88, v145, v145
	v_mul_f32_e32 v89, v95, v95
	v_fmac_f32_e32 v88, v144, v144
	v_fmac_f32_e32 v89, v94, v94
	v_add_f32_e32 v88, v88, v89
	v_mul_f32_e32 v89, v141, v141
	v_mul_f32_e32 v92, v91, v91
	v_fmac_f32_e32 v89, v140, v140
	v_fmac_f32_e32 v92, v90, v90
	v_add_f32_e32 v89, v89, v92
	v_add_f32_e32 v148, v88, v89
	v_lshlrev_b32_e32 v88, 16, v136
	v_and_b32_e32 v89, 0xffff0000, v136
	v_lshlrev_b32_e32 v92, 16, v137
	v_and_b32_e32 v93, 0xffff0000, v137
	v_pk_fma_f32 v[136:137], v[86:87], 0.5, v[92:93] op_sel_hi:[1,0,1]
	v_pk_fma_f32 v[142:143], v[84:85], 0.5, v[88:89] op_sel_hi:[1,0,1]
	v_lshlrev_b32_e32 v84, 16, v138
	v_and_b32_e32 v85, 0xffff0000, v138
	v_lshlrev_b32_e32 v86, 16, v139
	v_and_b32_e32 v87, 0xffff0000, v139
	v_pk_fma_f32 v[146:147], v[80:81], 0.5, v[84:85] op_sel_hi:[1,0,1]
	v_mul_f32_e32 v80, v143, v143
	v_mul_f32_e32 v81, v137, v137
	v_pk_fma_f32 v[138:139], v[82:83], 0.5, v[86:87] op_sel_hi:[1,0,1]
	v_fmac_f32_e32 v80, v142, v142
	v_fmac_f32_e32 v81, v136, v136
	v_add_f32_e32 v80, v80, v81
	v_mul_f32_e32 v81, v147, v147
	v_mul_f32_e32 v82, v139, v139
	v_fmac_f32_e32 v81, v146, v146
	v_fmac_f32_e32 v82, v138, v138
	v_add_f32_e32 v81, v81, v82
	v_add_f32_e32 v80, v80, v81
	v_add_f32_e32 v80, v148, v80
	v_mov_b32_e32 v236, v80
	s_nop 1
	v_permlane16_swap_b32_e32 v80, v236
	v_lshlrev_b64 v[190:191], 6, v[170:171]
	s_waitcnt lgkmcnt(0)
	v_add_f32_e32 v80, v80, v236
	v_mov_b32_e32 v236, v80
	s_nop 1
	v_permlane32_swap_b32_e32 v80, v236
	s_and_saveexec_b64 s[20:21], s[0:1]
	s_cbranch_execz .LBB0_1186
	s_waitcnt lgkmcnt(0)
	v_add_f32_e32 v82, v80, v236
	v_lshl_add_u64 v[80:81], s[2:3], 0, v[190:191]
	global_store_dword v[80:81], v82, off
.LBB0_1186:
	s_or_b64 exec, exec, s[20:21]
	v_lshlrev_b32_e32 v80, 16, v132
	s_waitcnt lgkmcnt(0)
	v_and_b32_e32 v81, 0xffff0000, v132
	v_lshlrev_b32_e32 v82, 16, v133
	v_and_b32_e32 v83, 0xffff0000, v133
	v_pk_fma_f32 v[148:149], v[78:79], 0.5, v[82:83] op_sel_hi:[1,0,1]
	v_pk_fma_f32 v[150:151], v[76:77], 0.5, v[80:81] op_sel_hi:[1,0,1]
	v_lshlrev_b32_e32 v76, 16, v134
	v_and_b32_e32 v77, 0xffff0000, v134
	v_lshlrev_b32_e32 v78, 16, v135
	v_and_b32_e32 v79, 0xffff0000, v135
	v_pk_fma_f32 v[134:135], v[72:73], 0.5, v[76:77] op_sel_hi:[1,0,1]
	v_mul_f32_e32 v72, v151, v151
	v_mul_f32_e32 v73, v149, v149
	v_pk_fma_f32 v[132:133], v[74:75], 0.5, v[78:79] op_sel_hi:[1,0,1]
	v_fmac_f32_e32 v72, v150, v150
	v_fmac_f32_e32 v73, v148, v148
	v_add_f32_e32 v72, v72, v73
	v_mul_f32_e32 v73, v135, v135
	v_mul_f32_e32 v74, v133, v133
	v_fmac_f32_e32 v73, v134, v134
	v_fmac_f32_e32 v74, v132, v132
	v_add_f32_e32 v73, v73, v74
	v_add_f32_e32 v76, v72, v73
	v_lshlrev_b32_e32 v72, 16, v128
	v_and_b32_e32 v73, 0xffff0000, v128
	v_lshlrev_b32_e32 v74, 16, v129
	v_and_b32_e32 v75, 0xffff0000, v129
	v_pk_fma_f32 v[178:179], v[70:71], 0.5, v[74:75] op_sel_hi:[1,0,1]
	v_pk_fma_f32 v[180:181], v[68:69], 0.5, v[72:73] op_sel_hi:[1,0,1]
	v_lshlrev_b32_e32 v68, 16, v130
	v_and_b32_e32 v69, 0xffff0000, v130
	v_lshlrev_b32_e32 v70, 16, v131
	v_and_b32_e32 v71, 0xffff0000, v131
	v_pk_fma_f32 v[182:183], v[64:65], 0.5, v[68:69] op_sel_hi:[1,0,1]
	v_mul_f32_e32 v64, v181, v181
	v_mul_f32_e32 v65, v179, v179
	v_pk_fma_f32 v[130:131], v[66:67], 0.5, v[70:71] op_sel_hi:[1,0,1]
	v_fmac_f32_e32 v64, v180, v180
	v_fmac_f32_e32 v65, v178, v178
	v_add_f32_e32 v64, v64, v65
	v_mul_f32_e32 v65, v183, v183
	v_mul_f32_e32 v66, v131, v131
	v_fmac_f32_e32 v65, v182, v182
	v_fmac_f32_e32 v66, v130, v130
	v_add_f32_e32 v65, v65, v66
	v_add_f32_e32 v64, v64, v65
	v_add_f32_e32 v64, v76, v64
	v_mov_b32_e32 v236, v64
	s_nop 1
	v_permlane16_swap_b32_e32 v64, v236
	v_lshlrev_b64 v[192:193], 6, v[168:169]
	s_waitcnt lgkmcnt(0)
	v_add_f32_e32 v64, v64, v236
	v_mov_b32_e32 v236, v64
	s_nop 1
	v_permlane32_swap_b32_e32 v64, v236
	s_and_saveexec_b64 s[20:21], s[0:1]
	s_cbranch_execz .LBB0_1188
	s_waitcnt lgkmcnt(0)
	v_add_f32_e32 v66, v64, v236
	v_lshl_add_u64 v[64:65], s[2:3], 0, v[192:193]
	global_store_dword v[64:65], v66, off
; __device__ __forceinline__ float bf_lo(unsigned w) { return __uint_as_float(w << 16); }
; __device__ __forceinline__ float bf_hi(unsigned w) { return __uint_as_float(w & 0xffff0000u); }
;     __device__ __forceinline__ void operator()(const f32x4 (&acc)[2][2][4][2], const Unit& u, int wr, int wc, int fr, int fq) const {
;     ...
;         for (int ai = 0; ai < 2; ++ai) {
;             u32x4 bb[4][2];
; #pragma unroll
;             for (int m = 0; m < 4; ++m)
; #pragma unroll
;                 for (int bj = 0; bj < 2; ++bj) bb[m][bj] = *(const u32x4*)(xb + (size_t)(row0 + ai * HALF + m * 16) * D_MODEL + col0 + bj * HALF);
; #pragma unroll
;             for (int m = 0; m < 4; ++m) { float s = 0.f;
; #pragma unroll
;                 for (int bj = 0; bj < 2; ++bj) { const u32x4 w = bb[m][bj];
;                     const f32x4 o0 = (f32x4){bf_lo(w.x), bf_hi(w.x), bf_lo(w.y), bf_hi(w.y)} + acc[ai][bj][m][0] * alpha, o1 = (f32x4){bf_lo(w.z), bf_hi(w.z), bf_lo(w.w), bf_hi(w.w)} + acc[ai][bj][m][1] * alpha;
;                     o[ai][m][bj][0] = o0; o[ai][m][bj][1] = o1;
;                     s += ((o0[0] * o0[0] + o0[1] * o0[1]) + (o0[2] * o0[2] + o0[3] * o0[3])) + ((o1[0] * o1[0] + o1[1] * o1[1]) + (o1[2] * o1[2] + o1[3] * o1[3])); }
;                 s += __shfl_xor(s, 16); s += __shfl_xor(s, 32);
;                 if (fq == 0) ssp[(size_t)(row0 + ai * HALF + m * 16) * 16 + u.pn * 4 + wc] = s; }
.LBB0_1188:
	s_or_b64 exec, exec, s[20:21]
	v_add_u32_e32 v184, 0x80, v176
	v_ashrrev_i32_e32 v185, 31, v184
	s_waitcnt lgkmcnt(0)
	v_lshlrev_b64 v[64:65], 11, v[184:185]
	v_lshl_add_u64 v[64:65], v[194:195], 0, v[64:65]
	global_load_dwordx4 v[208:211], v[64:65], off
	global_load_dwordx4 v[212:215], v[64:65], off offset:256
	v_add_u32_e32 v128, 0x90, v176
	v_add_u32_e32 v92, 0xa0, v176
	v_add_u32_e32 v88, 0xb0, v176
	v_ashrrev_i32_e32 v129, 31, v128
	v_ashrrev_i32_e32 v93, 31, v92
	v_ashrrev_i32_e32 v89, 31, v88
	v_lshlrev_b64 v[64:65], 11, v[128:129]
	v_lshlrev_b64 v[66:67], 11, v[92:93]
	v_lshlrev_b64 v[68:69], 11, v[88:89]
	v_lshl_add_u64 v[64:65], v[194:195], 0, v[64:65]
	v_lshl_add_u64 v[66:67], v[194:195], 0, v[66:67]
	v_lshl_add_u64 v[194:195], v[194:195], 0, v[68:69]
	global_load_dwordx4 v[84:87], v[64:65], off
	global_load_dwordx4 v[80:83], v[64:65], off offset:256
	global_load_dwordx4 v[76:79], v[66:67], off
	global_load_dwordx4 v[72:75], v[66:67], off offset:256
	global_load_dwordx4 v[68:71], v[194:195], off
	s_nop 0
	global_load_dwordx4 v[64:67], v[194:195], off offset:256
	s_waitcnt vmcnt(7)
	v_lshlrev_b32_e32 v194, 16, v208
	v_and_b32_e32 v195, 0xffff0000, v208
	v_lshlrev_b32_e32 v208, 16, v209
	v_and_b32_e32 v209, 0xffff0000, v209
	v_lshlrev_b32_e32 v216, 16, v210
	v_and_b32_e32 v217, 0xffff0000, v210
	v_lshlrev_b32_e32 v210, 16, v211
	v_and_b32_e32 v211, 0xffff0000, v211
	s_waitcnt vmcnt(6)
	v_lshlrev_b32_e32 v218, 16, v212
	v_and_b32_e32 v219, 0xffff0000, v212
	v_lshlrev_b32_e32 v212, 16, v213
	v_and_b32_e32 v213, 0xffff0000, v213
	v_lshlrev_b32_e32 v220, 16, v214
	v_and_b32_e32 v221, 0xffff0000, v214
	v_lshlrev_b32_e32 v214, 16, v215
	v_and_b32_e32 v215, 0xffff0000, v215
	v_pk_fma_f32 v[62:63], v[62:63], 0.5, v[208:209] op_sel_hi:[1,0,1]
	v_pk_fma_f32 v[60:61], v[60:61], 0.5, v[194:195] op_sel_hi:[1,0,1]
	v_pk_fma_f32 v[58:59], v[58:59], 0.5, v[210:211] op_sel_hi:[1,0,1]
	v_pk_fma_f32 v[56:57], v[56:57], 0.5, v[216:217] op_sel_hi:[1,0,1]
	v_pk_fma_f32 v[54:55], v[54:55], 0.5, v[212:213] op_sel_hi:[1,0,1]
	v_pk_fma_f32 v[52:53], v[52:53], 0.5, v[218:219] op_sel_hi:[1,0,1]
	v_pk_fma_f32 v[50:51], v[50:51], 0.5, v[214:215] op_sel_hi:[1,0,1]
	v_pk_fma_f32 v[48:49], v[48:49], 0.5, v[220:221] op_sel_hi:[1,0,1]
	v_mul_f32_e32 v194, v61, v61
	v_mul_f32_e32 v195, v63, v63
	v_mul_f32_e32 v207, v57, v57
	v_mul_f32_e32 v208, v59, v59
	v_mul_f32_e32 v209, v53, v53
	v_mul_f32_e32 v210, v55, v55
	v_mul_f32_e32 v211, v49, v49
	v_mul_f32_e32 v212, v51, v51
	v_fmac_f32_e32 v194, v60, v60
	v_fmac_f32_e32 v195, v62, v62
	v_fmac_f32_e32 v207, v56, v56
	v_fmac_f32_e32 v208, v58, v58
	v_fmac_f32_e32 v209, v52, v52
	v_fmac_f32_e32 v210, v54, v54
	v_fmac_f32_e32 v211, v48, v48
	v_fmac_f32_e32 v212, v50, v50
	v_add_f32_e32 v194, v194, v195
	v_add_f32_e32 v195, v207, v208
	v_add_f32_e32 v207, v209, v210
	v_add_f32_e32 v208, v211, v212
	v_add_f32_e32 v194, v194, v195
	v_add_f32_e32 v195, v207, v208
	v_add_f32_e32 v194, v194, v195
	v_mov_b32_e32 v236, v194
	s_nop 1
	v_permlane16_swap_b32_e32 v194, v236
	s_waitcnt lgkmcnt(0)
	v_add_f32_e32 v207, v194, v236
	v_mov_b32_e32 v236, v207
	s_nop 1
	v_permlane32_swap_b32_e32 v207, v236
	v_lshlrev_b64 v[194:195], 6, v[184:185]
	s_and_saveexec_b64 s[20:21], s[0:1]
	s_cbranch_execz .LBB0_1190
	s_waitcnt lgkmcnt(0)
	v_add_f32_e32 v207, v207, v236
	v_lshl_add_u64 v[208:209], s[2:3], 0, v[194:195]
	global_store_dword v[208:209], v207, off
.LBB0_1190:
	s_or_b64 exec, exec, s[20:21]
	s_waitcnt vmcnt(5) lgkmcnt(0)
	v_lshlrev_b32_e32 v208, 16, v84
	v_and_b32_e32 v209, 0xffff0000, v84
	v_lshlrev_b32_e32 v84, 16, v85
	v_and_b32_e32 v85, 0xffff0000, v85
	v_pk_fma_f32 v[46:47], v[46:47], 0.5, v[84:85] op_sel_hi:[1,0,1]
	v_pk_fma_f32 v[44:45], v[44:45], 0.5, v[208:209] op_sel_hi:[1,0,1]
	v_lshlrev_b32_e32 v84, 16, v86
	v_and_b32_e32 v85, 0xffff0000, v86
	v_lshlrev_b32_e32 v86, 16, v87
	v_and_b32_e32 v87, 0xffff0000, v87
	v_pk_fma_f32 v[40:41], v[40:41], 0.5, v[84:85] op_sel_hi:[1,0,1]
	v_mul_f32_e32 v84, v45, v45
	v_mul_f32_e32 v85, v47, v47
	v_pk_fma_f32 v[42:43], v[42:43], 0.5, v[86:87] op_sel_hi:[1,0,1]
	v_fmac_f32_e32 v84, v44, v44
	v_fmac_f32_e32 v85, v46, v46
	v_add_f32_e32 v84, v84, v85
	v_mul_f32_e32 v85, v41, v41
	v_mul_f32_e32 v86, v43, v43
	v_fmac_f32_e32 v85, v40, v40
	v_fmac_f32_e32 v86, v42, v42
	v_add_f32_e32 v85, v85, v86
	v_add_f32_e32 v86, v84, v85
	s_waitcnt vmcnt(4)
	v_lshlrev_b32_e32 v84, 16, v80
	v_and_b32_e32 v85, 0xffff0000, v80
	v_lshlrev_b32_e32 v80, 16, v81
	v_and_b32_e32 v81, 0xffff0000, v81
	v_pk_fma_f32 v[38:39], v[38:39], 0.5, v[80:81] op_sel_hi:[1,0,1]
	v_pk_fma_f32 v[36:37], v[36:37], 0.5, v[84:85] op_sel_hi:[1,0,1]
	v_lshlrev_b32_e32 v80, 16, v82
	v_and_b32_e32 v81, 0xffff0000, v82
	v_lshlrev_b32_e32 v82, 16, v83
	v_and_b32_e32 v83, 0xffff0000, v83
	v_pk_fma_f32 v[32:33], v[32:33], 0.5, v[80:81] op_sel_hi:[1,0,1]
	v_mul_f32_e32 v80, v37, v37
	v_mul_f32_e32 v81, v39, v39
	v_pk_fma_f32 v[34:35], v[34:35], 0.5, v[82:83] op_sel_hi:[1,0,1]
	v_fmac_f32_e32 v80, v36, v36
	v_fmac_f32_e32 v81, v38, v38
	v_add_f32_e32 v80, v80, v81
	v_mul_f32_e32 v81, v33, v33
	v_mul_f32_e32 v82, v35, v35
	v_fmac_f32_e32 v81, v32, v32
	v_fmac_f32_e32 v82, v34, v34
	v_add_f32_e32 v81, v81, v82
	v_add_f32_e32 v80, v80, v81
	v_add_f32_e32 v80, v86, v80
	v_mov_b32_e32 v236, v80
	s_nop 1
	v_permlane16_swap_b32_e32 v80, v236
	s_waitcnt lgkmcnt(0)
	v_add_f32_e32 v82, v80, v236
	v_mov_b32_e32 v236, v82
	s_nop 1
	v_permlane32_swap_b32_e32 v82, v236
	v_lshlrev_b64 v[80:81], 6, v[128:129]
	s_and_saveexec_b64 s[20:21], s[0:1]
	s_cbranch_execz .LBB0_1192
	s_waitcnt lgkmcnt(0)
	v_add_f32_e32 v84, v82, v236
	v_lshl_add_u64 v[82:83], s[2:3], 0, v[80:81]
	global_store_dword v[82:83], v84, off
; __device__ __forceinline__ float bf_lo(unsigned w) { return __uint_as_float(w << 16); }
; __device__ __forceinline__ float bf_hi(unsigned w) { return __uint_as_float(w & 0xffff0000u); }
;     __device__ __forceinline__ void operator()(const f32x4 (&acc)[2][2][4][2], const Unit& u, int wr, int wc, int fr, int fq) const {
;     ...
;         for (int ai = 0; ai < 2; ++ai) {
;             u32x4 bb[4][2];
; #pragma unroll
;             for (int m = 0; m < 4; ++m)
; #pragma unroll
;                 for (int bj = 0; bj < 2; ++bj) bb[m][bj] = *(const u32x4*)(xb + (size_t)(row0 + ai * HALF + m * 16) * D_MODEL + col0 + bj * HALF);
; #pragma unroll
;             for (int m = 0; m < 4; ++m) { float s = 0.f;
; #pragma unroll
;                 for (int bj = 0; bj < 2; ++bj) { const u32x4 w = bb[m][bj];
;                     const f32x4 o0 = (f32x4){bf_lo(w.x), bf_hi(w.x), bf_lo(w.y), bf_hi(w.y)} + acc[ai][bj][m][0] * alpha, o1 = (f32x4){bf_lo(w.z), bf_hi(w.z), bf_lo(w.w), bf_hi(w.w)} + acc[ai][bj][m][1] * alpha;
;                     o[ai][m][bj][0] = o0; o[ai][m][bj][1] = o1;
;                     s += ((o0[0] * o0[0] + o0[1] * o0[1]) + (o0[2] * o0[2] + o0[3] * o0[3])) + ((o1[0] * o1[0] + o1[1] * o1[1]) + (o1[2] * o1[2] + o1[3] * o1[3])); }
;                 s += __shfl_xor(s, 16); s += __shfl_xor(s, 32);
;                 if (fq == 0) ssp[(size_t)(row0 + ai * HALF + m * 16) * 16 + u.pn * 4 + wc] = s; }
.LBB0_1192:
	s_or_b64 exec, exec, s[20:21]
	s_waitcnt vmcnt(3)
	v_lshlrev_b32_e32 v82, 16, v76
	s_waitcnt lgkmcnt(0)
	v_and_b32_e32 v83, 0xffff0000, v76
	v_lshlrev_b32_e32 v76, 16, v77
	v_and_b32_e32 v77, 0xffff0000, v77
	v_pk_fma_f32 v[30:31], v[30:31], 0.5, v[76:77] op_sel_hi:[1,0,1]
	v_pk_fma_f32 v[28:29], v[28:29], 0.5, v[82:83] op_sel_hi:[1,0,1]
	v_lshlrev_b32_e32 v76, 16, v78
	v_and_b32_e32 v77, 0xffff0000, v78
	v_lshlrev_b32_e32 v78, 16, v79
	v_and_b32_e32 v79, 0xffff0000, v79
	v_pk_fma_f32 v[24:25], v[24:25], 0.5, v[76:77] op_sel_hi:[1,0,1]
	v_mul_f32_e32 v76, v29, v29
	v_mul_f32_e32 v77, v31, v31
	v_pk_fma_f32 v[26:27], v[26:27], 0.5, v[78:79] op_sel_hi:[1,0,1]
	v_fmac_f32_e32 v76, v28, v28
	v_fmac_f32_e32 v77, v30, v30
	v_add_f32_e32 v76, v76, v77
	v_mul_f32_e32 v77, v25, v25
	v_mul_f32_e32 v78, v27, v27
	v_fmac_f32_e32 v77, v24, v24
	v_fmac_f32_e32 v78, v26, v26
	v_add_f32_e32 v77, v77, v78
	v_add_f32_e32 v78, v76, v77
	s_waitcnt vmcnt(2)
	v_lshlrev_b32_e32 v76, 16, v72
	v_and_b32_e32 v77, 0xffff0000, v72
	v_lshlrev_b32_e32 v72, 16, v73
	v_and_b32_e32 v73, 0xffff0000, v73
	v_pk_fma_f32 v[22:23], v[22:23], 0.5, v[72:73] op_sel_hi:[1,0,1]
	v_pk_fma_f32 v[20:21], v[20:21], 0.5, v[76:77] op_sel_hi:[1,0,1]
	v_lshlrev_b32_e32 v72, 16, v74
	v_and_b32_e32 v73, 0xffff0000, v74
	v_lshlrev_b32_e32 v74, 16, v75
	v_and_b32_e32 v75, 0xffff0000, v75
	v_pk_fma_f32 v[16:17], v[16:17], 0.5, v[72:73] op_sel_hi:[1,0,1]
	v_mul_f32_e32 v72, v21, v21
	v_mul_f32_e32 v73, v23, v23
	v_pk_fma_f32 v[18:19], v[18:19], 0.5, v[74:75] op_sel_hi:[1,0,1]
	v_fmac_f32_e32 v72, v20, v20
	v_fmac_f32_e32 v73, v22, v22
	v_add_f32_e32 v72, v72, v73
	v_mul_f32_e32 v73, v17, v17
	v_mul_f32_e32 v74, v19, v19
	v_fmac_f32_e32 v73, v16, v16
	v_fmac_f32_e32 v74, v18, v18
	v_add_f32_e32 v73, v73, v74
	v_add_f32_e32 v72, v72, v73
	v_add_f32_e32 v72, v78, v72
	v_mov_b32_e32 v236, v72
	s_nop 1
	v_permlane16_swap_b32_e32 v72, v236
	v_lshlrev_b64 v[82:83], 6, v[92:93]
	s_waitcnt lgkmcnt(0)
	v_add_f32_e32 v72, v72, v236
	v_mov_b32_e32 v236, v72
	s_nop 1
	v_permlane32_swap_b32_e32 v72, v236
	s_and_saveexec_b64 s[20:21], s[0:1]
	s_cbranch_execz .LBB0_1194
	s_waitcnt lgkmcnt(0)
	v_add_f32_e32 v74, v72, v236
	v_lshl_add_u64 v[72:73], s[2:3], 0, v[82:83]
	global_store_dword v[72:73], v74, off
.LBB0_1194:
	s_or_b64 exec, exec, s[20:21]
	s_waitcnt vmcnt(1)
	v_lshlrev_b32_e32 v74, 16, v68
	v_and_b32_e32 v75, 0xffff0000, v68
	v_lshlrev_b32_e32 v68, 16, v69
	v_and_b32_e32 v69, 0xffff0000, v69
	s_waitcnt lgkmcnt(0)
	v_pk_fma_f32 v[72:73], v[14:15], 0.5, v[68:69] op_sel_hi:[1,0,1]
	v_pk_fma_f32 v[74:75], v[12:13], 0.5, v[74:75] op_sel_hi:[1,0,1]
	v_lshlrev_b32_e32 v12, 16, v70
	v_and_b32_e32 v13, 0xffff0000, v70
	v_lshlrev_b32_e32 v14, 16, v71
	v_and_b32_e32 v15, 0xffff0000, v71
	v_pk_fma_f32 v[70:71], v[8:9], 0.5, v[12:13] op_sel_hi:[1,0,1]
	v_mul_f32_e32 v8, v75, v75
	v_mul_f32_e32 v9, v73, v73
	v_pk_fma_f32 v[68:69], v[10:11], 0.5, v[14:15] op_sel_hi:[1,0,1]
	v_fmac_f32_e32 v8, v74, v74
	v_fmac_f32_e32 v9, v72, v72
	v_add_f32_e32 v8, v8, v9
	v_mul_f32_e32 v9, v71, v71
	v_mul_f32_e32 v10, v69, v69
	v_fmac_f32_e32 v9, v70, v70
	v_fmac_f32_e32 v10, v68, v68
	v_add_f32_e32 v9, v9, v10
	v_add_f32_e32 v12, v8, v9
	s_waitcnt vmcnt(0)
	v_lshlrev_b32_e32 v8, 16, v64
	v_and_b32_e32 v9, 0xffff0000, v64
	v_lshlrev_b32_e32 v10, 16, v65
	v_and_b32_e32 v11, 0xffff0000, v65
	v_pk_fma_f32 v[64:65], v[6:7], 0.5, v[10:11] op_sel_hi:[1,0,1]
	v_pk_fma_f32 v[76:77], v[4:5], 0.5, v[8:9] op_sel_hi:[1,0,1]
	v_lshlrev_b32_e32 v4, 16, v66
	v_and_b32_e32 v5, 0xffff0000, v66
	v_lshlrev_b32_e32 v6, 16, v67
	v_and_b32_e32 v7, 0xffff0000, v67
	v_pk_fma_f32 v[78:79], v[0:1], 0.5, v[4:5] op_sel_hi:[1,0,1]
	v_mul_f32_e32 v0, v77, v77
	v_mul_f32_e32 v1, v65, v65
	v_pk_fma_f32 v[66:67], v[2:3], 0.5, v[6:7] op_sel_hi:[1,0,1]
	v_fmac_f32_e32 v0, v76, v76
	v_fmac_f32_e32 v1, v64, v64
	v_add_f32_e32 v0, v0, v1
	v_mul_f32_e32 v1, v79, v79
	v_mul_f32_e32 v2, v67, v67
	v_fmac_f32_e32 v1, v78, v78
	v_fmac_f32_e32 v2, v66, v66
	v_add_f32_e32 v1, v1, v2
	v_add_f32_e32 v0, v0, v1
	v_add_f32_e32 v0, v12, v0
	v_mov_b32_e32 v236, v0
	s_nop 1
	v_permlane16_swap_b32_e32 v0, v236
	v_lshlrev_b64 v[84:85], 6, v[88:89]
	s_waitcnt lgkmcnt(0)
	v_add_f32_e32 v0, v0, v236
	v_mov_b32_e32 v236, v0
	s_nop 1
	v_permlane32_swap_b32_e32 v0, v236
	s_and_saveexec_b64 s[20:21], s[0:1]
	s_cbranch_execz .LBB0_1196
	s_waitcnt lgkmcnt(0)
	v_add_f32_e32 v2, v0, v236
	v_lshl_add_u64 v[0:1], s[2:3], 0, v[84:85]
	global_store_dword v[0:1], v2, off

;     __device__ __forceinline__ void operator()(const f32x4 (&acc)[2][2][4][2], const Unit& u, int wr, int wc, int fr, int fq) const {
;     ...
;         __builtin_amdgcn_s_barrier(); asm volatile("" ::: "memory");
;         float rs[2][4];
;         { f32x4 p[2][4];
; #pragma unroll
;           for (int ai = 0; ai < 2; ++ai)
; #pragma unroll
;             for (int m = 0; m < 4; ++m) p[ai][m] = *(const volatile f32x4*)(ssp + (size_t)(row0 + ai * HALF + m * 16) * 16 + 4 * fq);
; #pragma unroll
;           for (int ai = 0; ai < 2; ++ai)
; #pragma unroll
;             for (int m = 0; m < 4; ++m) { float s = (p[ai][m][0] + p[ai][m][1]) + (p[ai][m][2] + p[ai][m][3]); s += __shfl_xor(s, 16); s += __shfl_xor(s, 32); rs[ai][m] = __builtin_amdgcn_rsqf(s * (1.0f / D_MODEL) + RMS_EPS); } }
; #pragma unroll
;         for (int ai = 0; ai < 2; ++ai)
; #pragma unroll
;             for (int m = 0; m < 4; ++m) { const size_t off = (size_t)(row0 + ai * HALF + m * 16) * D_MODEL + col0; const float r = rs[ai][m];
; #pragma unroll
;                 for (int bj = 0; bj < 2; ++bj) { *(f32x4*)(out + off + bj * HALF) = o[ai][m][bj][0] * r * gv[bj][0]; *(f32x4*)(out + off + bj * HALF + 4) = o[ai][m][bj][1] * r * gv[bj][1]; } }
.LBB0_1210:
	s_barrier
	v_lshl_add_u64 v[86:87], v[160:161], 0, v[186:187]
	flat_load_dwordx4 v[208:211], v[86:87] sc0 sc1
	v_lshl_add_u64 v[86:87], v[160:161], 0, v[188:189]
	flat_load_dwordx4 v[186:189], v[86:87] sc0 sc1
	v_lshl_add_u64 v[86:87], v[160:161], 0, v[190:191]
	flat_load_dwordx4 v[212:215], v[86:87] sc0 sc1
	v_lshl_add_u64 v[86:87], v[160:161], 0, v[192:193]
	flat_load_dwordx4 v[190:193], v[86:87] sc0 sc1
	v_lshl_add_u64 v[86:87], v[160:161], 0, v[194:195]
	v_lshl_add_u64 v[80:81], v[160:161], 0, v[80:81]
	flat_load_dwordx4 v[216:219], v[86:87] sc0 sc1
	flat_load_dwordx4 v[220:223], v[80:81] sc0 sc1
	v_lshl_add_u64 v[80:81], v[160:161], 0, v[82:83]
	v_lshl_add_u64 v[84:85], v[160:161], 0, v[84:85]
	flat_load_dwordx4 v[80:83], v[80:81] sc0 sc1
	s_and_b64 vcc, exec, s[4:5]
	flat_load_dwordx4 v[84:87], v[84:85] sc0 sc1
	s_waitcnt vmcnt(0)
	s_mov_b64 s[2:3], -1
	s_waitcnt lgkmcnt(0)
	v_mov_b32_e32 v194, v209
	v_mov_b32_e32 v195, v210
	v_mov_b32_e32 v209, v211
	v_mov_b32_e32 v210, v187
	v_mov_b32_e32 v211, v188
	v_mov_b32_e32 v187, v189
	v_mov_b32_e32 v188, v213
	v_mov_b32_e32 v189, v214
	v_mov_b32_e32 v213, v215
	v_mov_b32_e32 v214, v191
	v_mov_b32_e32 v215, v192
	v_mov_b32_e32 v191, v193
	v_mov_b32_e32 v192, v217
	v_mov_b32_e32 v193, v218
	v_mov_b32_e32 v217, v219
	v_mov_b32_e32 v218, v221
	v_mov_b32_e32 v219, v222
	v_mov_b32_e32 v221, v223
	v_mov_b32_e32 v222, v81
	v_mov_b32_e32 v223, v82
	v_mov_b32_e32 v81, v83
	v_mov_b32_e32 v82, v85
	v_mov_b32_e32 v83, v86
	v_mov_b32_e32 v85, v87
	v_pk_add_f32 v[86:87], v[194:195], v[208:209]
	v_pk_add_f32 v[186:187], v[210:211], v[186:187]
	v_pk_add_f32 v[188:189], v[188:189], v[212:213]
	v_pk_add_f32 v[192:193], v[192:193], v[216:217]
	v_pk_add_f32 v[80:81], v[222:223], v[80:81]
	v_pk_add_f32 v[82:83], v[82:83], v[84:85]
	v_add_f32_e32 v84, v86, v87
	v_pk_add_f32 v[190:191], v[214:215], v[190:191]
	v_add_f32_e32 v85, v186, v187
	v_add_f32_e32 v86, v188, v189
	v_add_f32_e32 v186, v192, v193
	v_add_f32_e32 v80, v80, v81
	v_add_f32_e32 v81, v82, v83
	v_mov_b32_e32 v236, v84
	s_nop 1
	v_permlane16_swap_b32_e32 v84, v236
	v_add_f32_e32 v87, v190, v191
	v_mov_b32_e32 v237, v86
	s_nop 1
	v_permlane16_swap_b32_e32 v86, v237
	v_mov_b32_e32 v238, v186
	s_nop 1
	v_permlane16_swap_b32_e32 v186, v238
	v_pk_add_f32 v[194:195], v[218:219], v[220:221]
	v_mov_b32_e32 v239, v85
	s_nop 1
	v_permlane16_swap_b32_e32 v85, v239
	v_add_f32_e32 v187, v194, v195
	v_mov_b32_e32 v240, v80
	s_nop 1
	v_permlane16_swap_b32_e32 v80, v240
	s_waitcnt lgkmcnt(4)
	v_add_f32_e32 v82, v84, v236
	v_mov_b32_e32 v236, v87
	s_nop 1
	v_permlane16_swap_b32_e32 v87, v236
	v_mov_b32_e32 v241, v187
	s_nop 1
	v_permlane16_swap_b32_e32 v187, v241
	v_mov_b32_e32 v242, v81
	s_nop 1
	v_permlane16_swap_b32_e32 v81, v242
	s_waitcnt lgkmcnt(6)
	v_add_f32_e32 v84, v86, v237
	s_waitcnt lgkmcnt(5)
	v_add_f32_e32 v86, v186, v238
	v_mov_b32_e32 v237, v82
	s_nop 1
	v_permlane32_swap_b32_e32 v82, v237
	s_waitcnt lgkmcnt(5)
	v_add_f32_e32 v83, v85, v239
	s_waitcnt lgkmcnt(4)
	v_add_f32_e32 v80, v80, v240
	s_waitcnt lgkmcnt(3)
	v_add_f32_e32 v85, v87, v236
	s_waitcnt lgkmcnt(2)
	v_add_f32_e32 v87, v187, v241
	s_waitcnt lgkmcnt(1)
	v_add_f32_e32 v81, v81, v242
	v_mov_b32_e32 v236, v83
	s_nop 1
	v_permlane32_swap_b32_e32 v83, v236
	v_mov_b32_e32 v238, v84
	s_nop 1
	v_permlane32_swap_b32_e32 v84, v238
	v_mov_b32_e32 v239, v80
	s_nop 1
	v_permlane32_swap_b32_e32 v80, v239
	s_waitcnt lgkmcnt(3)
	v_add_f32_e32 v82, v82, v237
	v_fmamk_f32 v82, v82, 0x3a800000, v204
	v_mov_b32_e32 v237, v86
	s_nop 1
	v_permlane32_swap_b32_e32 v86, v237
	v_rsq_f32_e32 v186, v82
	v_mov_b32_e32 v244, v81
	v_mov_b32_e32 v245, v81
	s_nop 1
	v_permlane32_swap_b32_e32 v244, v245
	v_cndmask_b32_e64 v82, v245, v244, s[100:101]
	s_waitcnt lgkmcnt(4)
	v_add_f32_e32 v83, v83, v236
	s_waitcnt lgkmcnt(3)
	v_add_f32_e32 v84, v84, v238
	s_waitcnt lgkmcnt(2)
	v_add_f32_e32 v80, v80, v239
	v_fmamk_f32 v83, v83, 0x3a800000, v204
	v_fmamk_f32 v84, v84, 0x3a800000, v204
	v_fmamk_f32 v80, v80, 0x3a800000, v204
	v_mov_b32_e32 v244, v85
	v_mov_b32_e32 v245, v85
	s_nop 1
	v_permlane32_swap_b32_e32 v244, v245
	v_cndmask_b32_e64 v189, v245, v244, s[100:101]
	s_waitcnt lgkmcnt(2)
	v_add_f32_e32 v86, v86, v237
	v_rsq_f32_e32 v188, v83
	v_rsq_f32_e32 v190, v84
	v_rsq_f32_e32 v84, v80
	s_waitcnt lgkmcnt(1)
	v_add_f32_e32 v80, v81, v82
	v_pk_mul_f32 v[82:83], v[124:125], v[186:187] op_sel_hi:[1,0]
	v_pk_mul_f32 v[124:125], v[126:127], v[186:187] op_sel_hi:[1,0]
	v_mov_b32_e32 v244, v87
	v_mov_b32_e32 v245, v87
	s_nop 1
	v_permlane32_swap_b32_e32 v244, v245
	v_cndmask_b32_e64 v191, v245, v244, s[100:101]
	v_pk_mul_f32 v[126:127], v[14:15], v[124:125]
	v_pk_mul_f32 v[124:125], v[12:13], v[82:83]
	v_lshlrev_b64 v[82:83], 12, v[176:177]
	v_lshl_add_u64 v[176:177], s[70:71], 0, v[82:83]
	v_lshlrev_b64 v[82:83], 2, v[174:175]
	v_pk_mul_f32 v[112:113], v[112:113], v[186:187] op_sel_hi:[1,0]
	v_pk_mul_f32 v[114:115], v[114:115], v[186:187] op_sel_hi:[1,0]
	v_lshl_add_u64 v[174:175], v[176:177], 0, v[82:83]
	v_pk_mul_f32 v[114:115], v[2:3], v[114:115]
	v_pk_mul_f32 v[112:113], v[0:1], v[112:113]
	global_store_dwordx4 v[174:175], v[112:115], off offset:528
	s_waitcnt lgkmcnt(1)
	v_pk_mul_f32 v[96:97], v[96:97], v[188:189] op_sel_hi:[1,0]
	v_pk_mul_f32 v[98:99], v[98:99], v[188:189] op_sel_hi:[1,0]
	v_lshlrev_b64 v[112:113], 12, v[172:173]
	v_lshl_add_u64 v[112:113], s[70:71], 0, v[112:113]
	v_lshl_add_u64 v[112:113], v[112:113], 0, v[82:83]
	v_pk_mul_f32 v[98:99], v[2:3], v[98:99]
	v_pk_mul_f32 v[96:97], v[0:1], v[96:97]
	global_store_dwordx4 v[112:113], v[96:99], off offset:528
	s_waitcnt lgkmcnt(0)
;     __device__ __forceinline__ void operator()(const f32x4 (&acc)[2][2][4][2], const Unit& u, int wr, int wc, int fr, int fq) const {
;     ...
; #pragma unroll
;           for (int ai = 0; ai < 2; ++ai)
; #pragma unroll
;             for (int m = 0; m < 4; ++m) { float s = (p[ai][m][0] + p[ai][m][1]) + (p[ai][m][2] + p[ai][m][3]); s += __shfl_xor(s, 16); s += __shfl_xor(s, 32); rs[ai][m] = __builtin_amdgcn_rsqf(s * (1.0f / D_MODEL) + RMS_EPS); } }
; #pragma unroll
;         for (int ai = 0; ai < 2; ++ai)
; #pragma unroll
;             for (int m = 0; m < 4; ++m) { const size_t off = (size_t)(row0 + ai * HALF + m * 16) * D_MODEL + col0; const float r = rs[ai][m];
; #pragma unroll
;                 for (int bj = 0; bj < 2; ++bj) { *(f32x4*)(out + off + bj * HALF) = o[ai][m][bj][0] * r * gv[bj][0]; *(f32x4*)(out + off + bj * HALF + 4) = o[ai][m][bj][1] * r * gv[bj][1]; } }
	v_pk_mul_f32 v[94:95], v[94:95], v[190:191] op_sel_hi:[1,0]
	v_add_f32_e32 v85, v85, v189
	v_pk_mul_f32 v[98:99], v[144:145], v[190:191] op_sel_hi:[1,0]
	v_pk_mul_f32 v[96:97], v[14:15], v[94:95]
	v_pk_mul_f32 v[94:95], v[12:13], v[98:99]
	v_lshlrev_b64 v[98:99], 12, v[170:171]
	v_lshl_add_u64 v[98:99], s[70:71], 0, v[98:99]
	v_lshl_add_u64 v[98:99], v[98:99], 0, v[82:83]
	global_store_dwordx4 v[98:99], v[94:97], off
	v_pk_mul_f32 v[90:91], v[90:91], v[190:191] op_sel_hi:[1,0]
	v_fmamk_f32 v85, v85, 0x3a800000, v204
	v_pk_mul_f32 v[94:95], v[140:141], v[190:191] op_sel_hi:[1,0]
	v_pk_mul_f32 v[96:97], v[10:11], v[90:91]
	v_pk_mul_f32 v[94:95], v[8:9], v[94:95]
	v_rsq_f32_e32 v192, v85
	global_store_dwordx4 v[98:99], v[94:97], off offset:16
	v_pk_mul_f32 v[90:91], v[142:143], v[190:191] op_sel_hi:[1,0]
	v_fmamk_f32 v86, v86, 0x3a800000, v204
	v_pk_mul_f32 v[94:95], v[136:137], v[190:191] op_sel_hi:[1,0]
	v_rsq_f32_e32 v194, v86
	v_pk_mul_f32 v[96:97], v[6:7], v[94:95]
	v_pk_mul_f32 v[94:95], v[4:5], v[90:91]
	global_store_dwordx4 v[98:99], v[94:97], off offset:512
	v_pk_mul_f32 v[90:91], v[146:147], v[190:191] op_sel_hi:[1,0]
	v_add_f32_e32 v87, v87, v191
	v_pk_mul_f32 v[94:95], v[138:139], v[190:191] op_sel_hi:[1,0]
	v_fmamk_f32 v87, v87, 0x3a800000, v204
	v_pk_mul_f32 v[96:97], v[2:3], v[94:95]
	v_pk_mul_f32 v[94:95], v[0:1], v[90:91]
	global_store_dwordx4 v[98:99], v[94:97], off offset:528
	v_pk_mul_f32 v[90:91], v[150:151], v[192:193] op_sel_hi:[1,0]
	v_rsq_f32_e32 v86, v87
	v_pk_mul_f32 v[94:95], v[148:149], v[192:193] op_sel_hi:[1,0]
	v_pk_mul_f32 v[48:49], v[48:49], v[194:195] op_sel_hi:[1,0]
	v_pk_mul_f32 v[96:97], v[14:15], v[94:95]
	v_pk_mul_f32 v[94:95], v[12:13], v[90:91]
	v_lshlrev_b64 v[90:91], 12, v[168:169]
	v_lshl_add_u64 v[90:91], s[70:71], 0, v[90:91]
	v_lshl_add_u64 v[90:91], v[90:91], 0, v[82:83]
	global_store_dwordx4 v[90:91], v[94:97], off
	v_pk_mul_f32 v[50:51], v[50:51], v[194:195] op_sel_hi:[1,0]
	v_pk_mul_f32 v[48:49], v[0:1], v[48:49]
	v_pk_mul_f32 v[94:95], v[134:135], v[192:193] op_sel_hi:[1,0]
	v_pk_mul_f32 v[96:97], v[132:133], v[192:193] op_sel_hi:[1,0]
	v_pk_mul_f32 v[94:95], v[8:9], v[94:95]
	v_pk_mul_f32 v[96:97], v[10:11], v[96:97]
	global_store_dwordx4 v[90:91], v[94:97], off offset:16
	v_pk_mul_f32 v[50:51], v[2:3], v[50:51]
	v_fmamk_f32 v80, v80, 0x3a800000, v204
	v_pk_mul_f32 v[94:95], v[180:181], v[192:193] op_sel_hi:[1,0]
	v_pk_mul_f32 v[96:97], v[178:179], v[192:193] op_sel_hi:[1,0]
	v_pk_mul_f32 v[94:95], v[4:5], v[94:95]
	v_pk_mul_f32 v[96:97], v[6:7], v[96:97]
	global_store_dwordx4 v[90:91], v[94:97], off offset:512
	v_pk_mul_f32 v[32:33], v[32:33], v[86:87] op_sel_hi:[1,0]
	v_pk_mul_f32 v[34:35], v[34:35], v[86:87] op_sel_hi:[1,0]
	v_pk_mul_f32 v[94:95], v[182:183], v[192:193] op_sel_hi:[1,0]
	v_pk_mul_f32 v[96:97], v[130:131], v[192:193] op_sel_hi:[1,0]
	v_pk_mul_f32 v[94:95], v[0:1], v[94:95]
	v_pk_mul_f32 v[96:97], v[2:3], v[96:97]
	global_store_dwordx4 v[90:91], v[94:97], off offset:528
	v_lshlrev_b64 v[90:91], 12, v[184:185]
	v_lshl_add_u64 v[90:91], s[70:71], 0, v[90:91]
	v_lshl_add_u64 v[90:91], v[90:91], 0, v[82:83]
	global_store_dwordx4 v[90:91], v[48:51], off offset:528
	v_rsq_f32_e32 v80, v80
	v_pk_mul_f32 v[34:35], v[2:3], v[34:35]
	v_lshlrev_b64 v[48:49], 12, v[128:129]
	v_lshl_add_u64 v[48:49], s[70:71], 0, v[48:49]
	v_lshl_add_u64 v[48:49], v[48:49], 0, v[82:83]
	v_pk_mul_f32 v[32:33], v[0:1], v[32:33]
	global_store_dwordx4 v[48:49], v[32:35], off offset:528
	v_pk_mul_f32 v[16:17], v[16:17], v[84:85] op_sel_hi:[1,0]
	v_pk_mul_f32 v[18:19], v[18:19], v[84:85] op_sel_hi:[1,0]
	v_lshlrev_b64 v[32:33], 12, v[92:93]
	v_lshl_add_u64 v[32:33], s[70:71], 0, v[32:33]
	v_lshl_add_u64 v[32:33], v[32:33], 0, v[82:83]
	v_pk_mul_f32 v[18:19], v[2:3], v[18:19]
	v_pk_mul_f32 v[16:17], v[0:1], v[16:17]
	v_pk_mul_f32 v[108:109], v[108:109], v[188:189] op_sel_hi:[1,0]
	v_pk_mul_f32 v[60:61], v[60:61], v[194:195] op_sel_hi:[1,0]
	v_pk_mul_f32 v[44:45], v[44:45], v[86:87] op_sel_hi:[1,0]
	v_pk_mul_f32 v[28:29], v[28:29], v[84:85] op_sel_hi:[1,0]
	global_store_dwordx4 v[32:33], v[16:19], off offset:528
	v_pk_mul_f32 v[108:109], v[12:13], v[108:109]
	v_pk_mul_f32 v[60:61], v[12:13], v[60:61]
	v_pk_mul_f32 v[16:17], v[74:75], v[80:81] op_sel_hi:[1,0]
	v_pk_mul_f32 v[44:45], v[12:13], v[44:45]
	v_pk_mul_f32 v[28:29], v[12:13], v[28:29]
	v_pk_mul_f32 v[12:13], v[12:13], v[16:17]
	v_lshlrev_b64 v[16:17], 12, v[88:89]
; #define PG8_BAR __builtin_amdgcn_s_barrier()
;     __device__ __forceinline__ void operator()(const f32x4 (&acc)[2][2][4][2], const Unit& u, int wr, int wc, int fr, int fq) const {
;     ...
;         for (int ai = 0; ai < 2; ++ai)
; #pragma unroll
;             for (int m = 0; m < 4; ++m) { const size_t off = (size_t)(row0 + ai * HALF + m * 16) * D_MODEL + col0; const float r = rs[ai][m];
; #pragma unroll
;                 for (int bj = 0; bj < 2; ++bj) { *(f32x4*)(out + off + bj * HALF) = o[ai][m][bj][0] * r * gv[bj][0]; *(f32x4*)(out + off + bj * HALF + 4) = o[ai][m][bj][1] * r * gv[bj][1]; } }
; template <class Epi>
; __device__ __forceinline__ void gemm_phase(LAS unsigned char* lds, const Gemm g, const StaticOrder& S, const Epi& E) {
;     ...
;         if (!has_next) break;
; #pragma unroll
;         for (int a = 0; a < 2; ++a)
; #pragma unroll
;             for (int b = 0; b < 2; ++b)
; #pragma unroll
;                 for (int m = 0; m < 4; ++m)
; #pragma unroll
;                     for (int n = 0; n < 2; ++n) acc[a][b][m][n] = (f32x4){0.f, 0.f, 0.f, 0.f};
;         cur = nxt; cA = nA; cB = nB; ++ui;
;         if (wr == 1) PG8_BAR;
	v_pk_mul_f32 v[110:111], v[110:111], v[188:189] op_sel_hi:[1,0]
	v_pk_mul_f32 v[62:63], v[62:63], v[194:195] op_sel_hi:[1,0]
	v_pk_mul_f32 v[46:47], v[46:47], v[86:87] op_sel_hi:[1,0]
	v_pk_mul_f32 v[30:31], v[30:31], v[84:85] op_sel_hi:[1,0]
	v_pk_mul_f32 v[18:19], v[72:73], v[80:81] op_sel_hi:[1,0]
	v_lshl_add_u64 v[16:17], s[70:71], 0, v[16:17]
	v_pk_mul_f32 v[110:111], v[14:15], v[110:111]
	v_pk_mul_f32 v[62:63], v[14:15], v[62:63]
	v_pk_mul_f32 v[46:47], v[14:15], v[46:47]
	v_pk_mul_f32 v[30:31], v[14:15], v[30:31]
	v_pk_mul_f32 v[14:15], v[14:15], v[18:19]
	v_lshl_add_u64 v[16:17], v[16:17], 0, v[82:83]
	global_store_dwordx4 v[174:175], v[124:127], off
	v_pk_mul_f32 v[120:121], v[120:121], v[186:187] op_sel_hi:[1,0]
	v_pk_mul_f32 v[122:123], v[122:123], v[186:187] op_sel_hi:[1,0]
	global_store_dwordx4 v[112:113], v[108:111], off
	v_pk_mul_f32 v[104:105], v[104:105], v[188:189] op_sel_hi:[1,0]
	v_pk_mul_f32 v[106:107], v[106:107], v[188:189] op_sel_hi:[1,0]
	global_store_dwordx4 v[90:91], v[60:63], off
	v_pk_mul_f32 v[56:57], v[56:57], v[194:195] op_sel_hi:[1,0]
	v_pk_mul_f32 v[58:59], v[58:59], v[194:195] op_sel_hi:[1,0]
	global_store_dwordx4 v[48:49], v[44:47], off
	v_pk_mul_f32 v[40:41], v[40:41], v[86:87] op_sel_hi:[1,0]
	v_pk_mul_f32 v[42:43], v[42:43], v[86:87] op_sel_hi:[1,0]
	global_store_dwordx4 v[32:33], v[28:31], off
	v_pk_mul_f32 v[24:25], v[24:25], v[84:85] op_sel_hi:[1,0]
	v_pk_mul_f32 v[26:27], v[26:27], v[84:85] op_sel_hi:[1,0]
	global_store_dwordx4 v[16:17], v[12:15], off
	v_pk_mul_f32 v[122:123], v[10:11], v[122:123]
	v_pk_mul_f32 v[120:121], v[8:9], v[120:121]
	v_pk_mul_f32 v[12:13], v[70:71], v[80:81] op_sel_hi:[1,0]
	v_pk_mul_f32 v[14:15], v[68:69], v[80:81] op_sel_hi:[1,0]
	v_pk_mul_f32 v[106:107], v[10:11], v[106:107]
	v_pk_mul_f32 v[104:105], v[8:9], v[104:105]
	v_pk_mul_f32 v[58:59], v[10:11], v[58:59]
	v_pk_mul_f32 v[56:57], v[8:9], v[56:57]
	v_pk_mul_f32 v[42:43], v[10:11], v[42:43]
	v_pk_mul_f32 v[40:41], v[8:9], v[40:41]
	v_pk_mul_f32 v[26:27], v[10:11], v[26:27]
	v_pk_mul_f32 v[24:25], v[8:9], v[24:25]
	v_pk_mul_f32 v[10:11], v[10:11], v[14:15]
	v_pk_mul_f32 v[8:9], v[8:9], v[12:13]
	global_store_dwordx4 v[174:175], v[120:123], off offset:16
	v_pk_mul_f32 v[116:117], v[116:117], v[186:187] op_sel_hi:[1,0]
	v_pk_mul_f32 v[118:119], v[118:119], v[186:187] op_sel_hi:[1,0]
	global_store_dwordx4 v[112:113], v[104:107], off offset:16
	v_pk_mul_f32 v[100:101], v[100:101], v[188:189] op_sel_hi:[1,0]
	v_pk_mul_f32 v[102:103], v[102:103], v[188:189] op_sel_hi:[1,0]
	global_store_dwordx4 v[90:91], v[56:59], off offset:16
	v_pk_mul_f32 v[52:53], v[52:53], v[194:195] op_sel_hi:[1,0]
	v_pk_mul_f32 v[54:55], v[54:55], v[194:195] op_sel_hi:[1,0]
	global_store_dwordx4 v[48:49], v[40:43], off offset:16
	v_pk_mul_f32 v[36:37], v[36:37], v[86:87] op_sel_hi:[1,0]
	v_pk_mul_f32 v[38:39], v[38:39], v[86:87] op_sel_hi:[1,0]
	global_store_dwordx4 v[32:33], v[24:27], off offset:16
	v_pk_mul_f32 v[20:21], v[20:21], v[84:85] op_sel_hi:[1,0]
	v_pk_mul_f32 v[22:23], v[22:23], v[84:85] op_sel_hi:[1,0]
	global_store_dwordx4 v[16:17], v[8:11], off offset:16
	v_pk_mul_f32 v[118:119], v[6:7], v[118:119]
	v_pk_mul_f32 v[116:117], v[4:5], v[116:117]
	v_pk_mul_f32 v[8:9], v[76:77], v[80:81] op_sel_hi:[1,0]
	v_pk_mul_f32 v[10:11], v[64:65], v[80:81] op_sel_hi:[1,0]
	v_pk_mul_f32 v[102:103], v[6:7], v[102:103]
	v_pk_mul_f32 v[100:101], v[4:5], v[100:101]
	v_pk_mul_f32 v[54:55], v[6:7], v[54:55]
	v_pk_mul_f32 v[52:53], v[4:5], v[52:53]
	v_pk_mul_f32 v[38:39], v[6:7], v[38:39]
	v_pk_mul_f32 v[36:37], v[4:5], v[36:37]
	v_pk_mul_f32 v[22:23], v[6:7], v[22:23]
	v_pk_mul_f32 v[20:21], v[4:5], v[20:21]
	v_pk_mul_f32 v[6:7], v[6:7], v[10:11]
	v_pk_mul_f32 v[4:5], v[4:5], v[8:9]
	global_store_dwordx4 v[174:175], v[116:119], off offset:512
	global_store_dwordx4 v[112:113], v[100:103], off offset:512
	global_store_dwordx4 v[90:91], v[52:55], off offset:512
	global_store_dwordx4 v[48:49], v[36:39], off offset:512
	global_store_dwordx4 v[32:33], v[20:23], off offset:512
	global_store_dwordx4 v[16:17], v[4:7], off offset:512
	s_nop 1
	v_pk_mul_f32 v[4:5], v[78:79], v[80:81] op_sel_hi:[1,0]
	v_pk_mul_f32 v[6:7], v[66:67], v[80:81] op_sel_hi:[1,0]
	v_pk_mul_f32 v[0:1], v[0:1], v[4:5]
	v_pk_mul_f32 v[2:3], v[2:3], v[6:7]
	global_store_dwordx4 v[16:17], v[0:3], off offset:528
	s_cbranch_vccnz .LBB0_1165
	s_andn2_b64 vcc, exec, s[12:13]
	s_cbranch_vccnz .LBB0_1164
	s_barrier
	s_branch .LBB0_1164
